# combination: attention row max as v_max3 chains, layer-0 context gating units on wave 1, m0 write hoisted above the address add (no s_nop) in GEMM load segments, layer-1 adaLN items moved from the pro
# speedup vs baseline: 1.0058x; 1.0033x over previous
; __device__ __forceinline__ void prologue(const kptr_t kp, LAS float* scr, int gw, int NGW, int lane) {
;     ...
;     for (int it = gw; it < IT_TOTAL; it += NGW) {
;         int r = it;
;         if (r < IT_ADA) {
.Lzero_skip:
	s_mov_b32 s98, 0
	s_movk_i32 s99, 0x800
	s_movk_i32 s100, 0x240
	s_mov_b32 s101, 0

; __device__ __forceinline__ void prologue(const kptr_t kp, LAS float* scr, int gw, int NGW, int lane) {
;     ...
;     for (int it = gw; it < IT_TOTAL; it += NGW) {
;         int r = it;
;         if (r < IT_ADA) {
.Lcv_ret:
	s_cmp_lg_u32 s101, 0
	s_cbranch_scc1 .Lcv_r1
	s_movk_i32 s98, 0x480
	s_movk_i32 s100, 0xf80
	s_mov_b32 s101, 1
	s_branch .Lcv_entry
.Lcv_r1:
	s_cmp_lg_u32 s101, 1
	s_cbranch_scc1 .Lcv_r2
	s_movk_i32 s98, 0x7180
	s_movk_i32 s100, 0x79d0
	s_mov_b32 s101, 2
	s_branch .Lcv_entry

; #define PG8_STAGE(bufoff, gbase, voff) do { _Pragma("unroll") for (int _i = 0; _i < 2; ++_i) \
;         __builtin_amdgcn_global_load_lds((const unsigned*)((const char*)(gbase) + (voff)[_i]), (PG8_LAS unsigned*)(lds + (bufoff) + ldsw + _i * 8192), 16, 0, 0); } while (0)
; #define PG8_LDA(dst, b, h) do { _Pragma("unroll") for (int m = 0; m < 4; ++m) _Pragma("unroll") for (int k = 0; k < 2; ++k) dst[m][k] = *(const PG8_LAS bf16x8*)(lds + PG8_SA(b, h) + aoff + m * 2048 + k * 1024); } while (0)
; #define PG8_LDB(dst, b, h) do { _Pragma("unroll") for (int n = 0; n < 2; ++n) _Pragma("unroll") for (int k = 0; k < 2; ++k) dst[n][k] = *(const PG8_LAS bf16x8*)(lds + PG8_SB(b, h) + boff + n * 2048 + k * 1024); } while (0)
; #define PG8_WAIT_V(n) asm volatile("s_waitcnt vmcnt(" #n ")" ::: "memory")
; #define PG8_WAIT_L(n) asm volatile("s_waitcnt lgkmcnt(" #n ")" ::: "memory")
; #define PG8_BAR __builtin_amdgcn_s_barrier()
; #define PG8_SCHED __builtin_amdgcn_sched_barrier(0)
; #define PG8_MMA2(ai) PG8_MMA(ai, 0, At, B0)
;     ...
;         for (int t = 0; t < nt; t += 2) {
;             const bool last = (t == nt - 2);
;             const char* a1 = cA + (size_t)(t + 1) * kstep;
;             const char* a2 = last ? nA : cA + (size_t)(t + 2) * kstep; const char* b2 = last ? nB : cB + (size_t)(t + 2) * kstep;
;             const char* a3 = a2 + kstep; const char* b3 = b2 + kstep;
;             if (last && has_next) S.a_ready(nxt);
;             if constexpr (SP2) {
;             PG8_LDB(B0, 0, 0); PG8_LDB(B1, 0, 1); PG8_SCHED; PG8_LDA(At, 0, 0); PG8_STAGE(PG8_SA(1, 1), a1 + hstep, voffA);
;             PG8_WAIT_V(8); PG8_WAIT_L(0); PG8_BAR; PG8_MMA2(0); PG8_BAR; PG8_SCHED;
;             PG8_LDA(At, 0, 1); PG8_STAGE(PG8_SB(0, 0), b2, voffB); PG8_STAGE(PG8_SB(0, 1), b2 + hstep, voffB); PG8_STAGE(PG8_SA(0, 0), a2, voffA);
;             PG8_WAIT_V(8); PG8_WAIT_L(0); PG8_BAR; PG8_MMA2(1); PG8_BAR; PG8_SCHED;
;             PG8_LDB(B0, 1, 0); PG8_LDB(B1, 1, 1); PG8_SCHED; PG8_LDA(At, 1, 0); PG8_STAGE(PG8_SA(0, 1), a2 + hstep, voffA);
;             PG8_WAIT_V(8); PG8_WAIT_L(0); PG8_BAR; PG8_MMA2(0); PG8_BAR; PG8_SCHED;
;             PG8_LDA(At, 1, 1); PG8_STAGE(PG8_SB(1, 0), b3, voffB); PG8_STAGE(PG8_SB(1, 1), b3 + hstep, voffB); PG8_STAGE(PG8_SA(1, 0), a3, voffA);
;             PG8_WAIT_V(8); PG8_WAIT_L(0); PG8_BAR; PG8_MMA2(1); PG8_BAR; PG8_SCHED;
.Ldf_skipA_0:
	ds_read_b128 v[152:155], v149
	ds_read_b128 v[156:159], v149 offset:1024
	ds_read_b128 v[160:163], v149 offset:2048
	ds_read_b128 v[164:167], v149 offset:3072
	ds_read_b128 v[168:171], v150
	ds_read_b128 v[172:175], v150 offset:1024
	ds_read_b128 v[176:179], v150 offset:2048
	ds_read_b128 v[180:183], v150 offset:3072
	s_add_u32 s16, s36, 0xfffc0080
	s_addc_u32 s17, s37, -1
	s_cmp_eq_u32 s62, 12
	s_cselect_b32 s41, s19, s17
	s_cselect_b32 s40, s58, s16
	s_cselect_b32 s39, s15, s61
	s_cselect_b32 s38, s59, s60
	v_lshl_add_u64 v[144:145], s[36:37], 0, v[138:139]
	s_add_i32 m0, s27, 0xc000
	ds_read_b128 v[184:187], v151
	ds_read_b128 v[188:191], v151 offset:1024
	ds_read_b128 v[192:195], v151 offset:2048
	ds_read_b128 v[196:199], v151 offset:3072
	ds_read_b128 v[200:203], v151 offset:4096
	ds_read_b128 v[208:211], v151 offset:5120
	ds_read_b128 v[214:217], v151 offset:6144
	ds_read_b128 v[218:221], v151 offset:7168
	global_load_lds_dwordx4 v[144:145], off
	s_add_i32 m0, s27, 0xe000
	v_lshl_add_u64 v[144:145], s[36:37], 0, v[136:137]
	global_load_lds_dwordx4 v[144:145], off
	s_waitcnt vmcnt(8)
	s_waitcnt lgkmcnt(0)
	s_barrier
	s_setprio 1
	s_waitcnt lgkmcnt(0)
	v_mfma_f32_16x16x32_bf16 v[124:127], v[152:155], v[184:187], v[124:127]
	v_mfma_f32_16x16x32_bf16 v[120:123], v[160:163], v[184:187], v[120:123]
	v_mfma_f32_16x16x32_bf16 v[108:111], v[152:155], v[192:195], v[108:111]
	v_mfma_f32_16x16x32_bf16 v[104:107], v[160:163], v[192:195], v[104:107]
	v_mfma_f32_16x16x32_bf16 v[92:95], v[152:155], v[200:203], v[92:95]
	v_mfma_f32_16x16x32_bf16 v[88:91], v[160:163], v[200:203], v[88:91]
	v_mfma_f32_16x16x32_bf16 v[76:79], v[152:155], v[214:217], v[76:79]
	v_mfma_f32_16x16x32_bf16 v[72:75], v[160:163], v[214:217], v[72:75]
	v_mfma_f32_16x16x32_bf16 v[124:127], v[156:159], v[188:191], v[124:127]
	v_mfma_f32_16x16x32_bf16 v[120:123], v[164:167], v[188:191], v[120:123]
	v_mfma_f32_16x16x32_bf16 v[108:111], v[156:159], v[196:199], v[108:111]
	v_mfma_f32_16x16x32_bf16 v[104:107], v[164:167], v[196:199], v[104:107]
	v_mfma_f32_16x16x32_bf16 v[92:95], v[156:159], v[208:211], v[92:95]
	v_mfma_f32_16x16x32_bf16 v[88:91], v[164:167], v[208:211], v[88:91]
	v_mfma_f32_16x16x32_bf16 v[76:79], v[156:159], v[218:221], v[76:79]
	v_mfma_f32_16x16x32_bf16 v[72:75], v[164:167], v[218:221], v[72:75]
	s_setprio 0
	s_setprio 1
	v_mfma_f32_16x16x32_bf16 v[116:119], v[168:171], v[184:187], v[116:119]
	v_mfma_f32_16x16x32_bf16 v[112:115], v[176:179], v[184:187], v[112:115]
	v_mfma_f32_16x16x32_bf16 v[100:103], v[168:171], v[192:195], v[100:103]
	v_mfma_f32_16x16x32_bf16 v[96:99], v[176:179], v[192:195], v[96:99]
	v_mfma_f32_16x16x32_bf16 v[84:87], v[168:171], v[200:203], v[84:87]
	v_mfma_f32_16x16x32_bf16 v[80:83], v[176:179], v[200:203], v[80:83]
	v_mfma_f32_16x16x32_bf16 v[68:71], v[168:171], v[214:217], v[68:71]
	v_mfma_f32_16x16x32_bf16 v[64:67], v[176:179], v[214:217], v[64:67]
	v_mfma_f32_16x16x32_bf16 v[116:119], v[172:175], v[188:191], v[116:119]
	v_mfma_f32_16x16x32_bf16 v[112:115], v[180:183], v[188:191], v[112:115]
	v_mfma_f32_16x16x32_bf16 v[100:103], v[172:175], v[196:199], v[100:103]
	v_mfma_f32_16x16x32_bf16 v[96:99], v[180:183], v[196:199], v[96:99]
	v_mfma_f32_16x16x32_bf16 v[84:87], v[172:175], v[208:211], v[84:87]
	v_mfma_f32_16x16x32_bf16 v[80:83], v[180:183], v[208:211], v[80:83]
	v_mfma_f32_16x16x32_bf16 v[68:71], v[172:175], v[218:221], v[68:71]
	v_mfma_f32_16x16x32_bf16 v[64:67], v[180:183], v[218:221], v[64:67]
	s_setprio 0
	s_barrier
	s_add_i32 s16, s54, s45
	v_lshl_add_u64 v[144:145], s[38:39], 0, v[130:131]
	s_mov_b32 m0, s16
	ds_read_b128 v[184:187], v151 offset:16384
	ds_read_b128 v[188:191], v151 offset:17408
	ds_read_b128 v[192:195], v151 offset:18432
	ds_read_b128 v[196:199], v151 offset:19456
	ds_read_b128 v[200:203], v151 offset:20480
	ds_read_b128 v[208:211], v151 offset:21504
	ds_read_b128 v[214:217], v151 offset:22528
	ds_read_b128 v[218:221], v151 offset:23552
	global_load_lds_dwordx4 v[144:145], off
	s_add_i32 m0, s16, 0x2000
	s_add_u32 s34, s38, 0x40000
	v_lshl_add_u64 v[204:205], s[38:39], 0, v[134:135]
	s_addc_u32 s35, s39, 0
	s_add_i32 s16, s55, s45
	global_load_lds_dwordx4 v[204:205], off
	v_lshl_add_u64 v[222:223], s[34:35], 0, v[130:131]
	s_mov_b32 m0, s16
	v_lshl_add_u64 v[224:225], s[40:41], 0, v[132:133]
	global_load_lds_dwordx4 v[222:223], off
	s_add_i32 m0, s16, 0x2000
	v_lshl_add_u64 v[222:223], s[34:35], 0, v[134:135]
	global_load_lds_dwordx4 v[222:223], off
	s_mov_b32 m0, s27
	v_lshl_add_u64 v[222:223], s[40:41], 0, v[128:129]
	global_load_lds_dwordx4 v[222:223], off
	s_nop 0
	s_waitcnt vmcnt(7)
	s_waitcnt lgkmcnt(0)
	s_barrier
; #define PG8_STAGE(bufoff, gbase, voff) do { _Pragma("unroll") for (int _i = 0; _i < 2; ++_i) \
;         __builtin_amdgcn_global_load_lds((const unsigned*)((const char*)(gbase) + (voff)[_i]), (PG8_LAS unsigned*)(lds + (bufoff) + ldsw + _i * 8192), 16, 0, 0); } while (0)
; #define PG8_LDA(dst, b, h) do { _Pragma("unroll") for (int m = 0; m < 4; ++m) _Pragma("unroll") for (int k = 0; k < 2; ++k) dst[m][k] = *(const PG8_LAS bf16x8*)(lds + PG8_SA(b, h) + aoff + m * 2048 + k * 1024); } while (0)
; #define PG8_LDB(dst, b, h) do { _Pragma("unroll") for (int n = 0; n < 2; ++n) _Pragma("unroll") for (int k = 0; k < 2; ++k) dst[n][k] = *(const PG8_LAS bf16x8*)(lds + PG8_SB(b, h) + boff + n * 2048 + k * 1024); } while (0)
; #define PG8_WAIT_V(n) asm volatile("s_waitcnt vmcnt(" #n ")" ::: "memory")
; #define PG8_WAIT_L(n) asm volatile("s_waitcnt lgkmcnt(" #n ")" ::: "memory")
; #define PG8_BAR __builtin_amdgcn_s_barrier()
; #define PG8_SCHED __builtin_amdgcn_sched_barrier(0)
; #define PG8_MMA2(ai) PG8_MMA(ai, 0, At, B0)
;     ...
;         for (int t = 0; t < nt; t += 2) {
;             const bool last = (t == nt - 2);
;             const char* a1 = cA + (size_t)(t + 1) * kstep;
;             const char* a2 = last ? nA : cA + (size_t)(t + 2) * kstep; const char* b2 = last ? nB : cB + (size_t)(t + 2) * kstep;
;             const char* a3 = a2 + kstep; const char* b3 = b2 + kstep;
;             if (last && has_next) S.a_ready(nxt);
;             if constexpr (SP2) {
;             PG8_LDB(B0, 0, 0); PG8_LDB(B1, 0, 1); PG8_SCHED; PG8_LDA(At, 0, 0); PG8_STAGE(PG8_SA(1, 1), a1 + hstep, voffA);
;             PG8_WAIT_V(8); PG8_WAIT_L(0); PG8_BAR; PG8_MMA2(0); PG8_BAR; PG8_SCHED;
;             PG8_LDA(At, 0, 1); PG8_STAGE(PG8_SB(0, 0), b2, voffB); PG8_STAGE(PG8_SB(0, 1), b2 + hstep, voffB); PG8_STAGE(PG8_SA(0, 0), a2, voffA);
;             PG8_WAIT_V(8); PG8_WAIT_L(0); PG8_BAR; PG8_MMA2(1); PG8_BAR; PG8_SCHED;
;             PG8_LDB(B0, 1, 0); PG8_LDB(B1, 1, 1); PG8_SCHED; PG8_LDA(At, 1, 0); PG8_STAGE(PG8_SA(0, 1), a2 + hstep, voffA);
;             PG8_WAIT_V(8); PG8_WAIT_L(0); PG8_BAR; PG8_MMA2(0); PG8_BAR; PG8_SCHED;
;             PG8_LDA(At, 1, 1); PG8_STAGE(PG8_SB(1, 0), b3, voffB); PG8_STAGE(PG8_SB(1, 1), b3 + hstep, voffB); PG8_STAGE(PG8_SA(1, 0), a3, voffA);
;             PG8_WAIT_V(8); PG8_WAIT_L(0); PG8_BAR; PG8_MMA2(1); PG8_BAR; PG8_SCHED;
	s_setprio 1
	s_waitcnt lgkmcnt(0)
	v_mfma_f32_16x16x32_bf16 v[60:63], v[152:155], v[184:187], v[60:63]
	v_mfma_f32_16x16x32_bf16 v[56:59], v[160:163], v[184:187], v[56:59]
	v_mfma_f32_16x16x32_bf16 v[44:47], v[152:155], v[192:195], v[44:47]
	v_mfma_f32_16x16x32_bf16 v[40:43], v[160:163], v[192:195], v[40:43]
	v_mfma_f32_16x16x32_bf16 v[28:31], v[152:155], v[200:203], v[28:31]
	v_mfma_f32_16x16x32_bf16 v[24:27], v[160:163], v[200:203], v[24:27]
	v_mfma_f32_16x16x32_bf16 v[12:15], v[152:155], v[214:217], v[12:15]
	v_mfma_f32_16x16x32_bf16 v[8:11], v[160:163], v[214:217], v[8:11]
	v_mfma_f32_16x16x32_bf16 v[60:63], v[156:159], v[188:191], v[60:63]
	v_mfma_f32_16x16x32_bf16 v[56:59], v[164:167], v[188:191], v[56:59]
	v_mfma_f32_16x16x32_bf16 v[44:47], v[156:159], v[196:199], v[44:47]
	v_mfma_f32_16x16x32_bf16 v[40:43], v[164:167], v[196:199], v[40:43]
	v_mfma_f32_16x16x32_bf16 v[28:31], v[156:159], v[208:211], v[28:31]
	v_mfma_f32_16x16x32_bf16 v[24:27], v[164:167], v[208:211], v[24:27]
	v_mfma_f32_16x16x32_bf16 v[12:15], v[156:159], v[218:221], v[12:15]
	v_mfma_f32_16x16x32_bf16 v[8:11], v[164:167], v[218:221], v[8:11]
	s_setprio 0
	s_setprio 1
	v_mfma_f32_16x16x32_bf16 v[52:55], v[168:171], v[184:187], v[52:55]
	v_mfma_f32_16x16x32_bf16 v[48:51], v[176:179], v[184:187], v[48:51]
	v_mfma_f32_16x16x32_bf16 v[36:39], v[168:171], v[192:195], v[36:39]
	v_mfma_f32_16x16x32_bf16 v[32:35], v[176:179], v[192:195], v[32:35]
	v_mfma_f32_16x16x32_bf16 v[20:23], v[168:171], v[200:203], v[20:23]
	v_mfma_f32_16x16x32_bf16 v[16:19], v[176:179], v[200:203], v[16:19]
	v_mfma_f32_16x16x32_bf16 v[4:7], v[168:171], v[214:217], v[4:7]
	v_mfma_f32_16x16x32_bf16 v[0:3], v[176:179], v[214:217], v[0:3]
	v_mfma_f32_16x16x32_bf16 v[52:55], v[172:175], v[188:191], v[52:55]
	v_mfma_f32_16x16x32_bf16 v[48:51], v[180:183], v[188:191], v[48:51]
	v_mfma_f32_16x16x32_bf16 v[36:39], v[172:175], v[196:199], v[36:39]
	v_mfma_f32_16x16x32_bf16 v[32:35], v[180:183], v[196:199], v[32:35]
	v_mfma_f32_16x16x32_bf16 v[20:23], v[172:175], v[208:211], v[20:23]
	v_mfma_f32_16x16x32_bf16 v[16:19], v[180:183], v[208:211], v[16:19]
	v_mfma_f32_16x16x32_bf16 v[4:7], v[172:175], v[218:221], v[4:7]
	v_mfma_f32_16x16x32_bf16 v[0:3], v[180:183], v[218:221], v[0:3]
	s_setprio 0
	s_barrier
	s_add_i32 s16, 0, 0x18000
	s_add_i32 s17, 0, 0x1c000
	v_add_u32_e32 v164, s16, v147
	v_add_u32_e32 v180, s17, v147
	ds_read_b128 v[152:155], v164
	ds_read_b128 v[156:159], v164 offset:1024
	ds_read_b128 v[160:163], v164 offset:2048
	ds_read_b128 v[164:167], v164 offset:3072
	ds_read_b128 v[168:171], v180
	ds_read_b128 v[172:175], v180 offset:1024
	ds_read_b128 v[176:179], v180 offset:2048
	ds_read_b128 v[180:183], v180 offset:3072
	s_add_u32 s34, s40, 0x40000
	s_addc_u32 s35, s41, 0
	s_mov_b32 m0, s46
	s_nop 0
	global_load_lds_dwordx4 v[224:225], off
	s_mov_b32 m0, s47
	v_lshl_add_u64 v[226:227], s[34:35], 0, v[128:129]
	ds_read_b128 v[184:187], v151 offset:32768
	ds_read_b128 v[188:191], v151 offset:33792
	ds_read_b128 v[192:195], v151 offset:34816
	ds_read_b128 v[196:199], v151 offset:35840
	ds_read_b128 v[200:203], v151 offset:36864
	ds_read_b128 v[208:211], v151 offset:37888
	ds_read_b128 v[214:217], v151 offset:38912
	ds_read_b128 v[218:221], v151 offset:39936
	global_load_lds_dwordx4 v[226:227], off
	s_mov_b32 m0, s48
	v_lshl_add_u64 v[226:227], s[34:35], 0, v[132:133]
	global_load_lds_dwordx4 v[226:227], off
	s_waitcnt vmcnt(8)
	s_waitcnt lgkmcnt(0)
	s_barrier
	s_setprio 1
	s_waitcnt lgkmcnt(0)
	v_mfma_f32_16x16x32_bf16 v[124:127], v[152:155], v[184:187], v[124:127]
	v_mfma_f32_16x16x32_bf16 v[120:123], v[160:163], v[184:187], v[120:123]
	v_mfma_f32_16x16x32_bf16 v[108:111], v[152:155], v[192:195], v[108:111]
	v_mfma_f32_16x16x32_bf16 v[104:107], v[160:163], v[192:195], v[104:107]
	v_mfma_f32_16x16x32_bf16 v[92:95], v[152:155], v[200:203], v[92:95]
	v_mfma_f32_16x16x32_bf16 v[88:91], v[160:163], v[200:203], v[88:91]
	v_mfma_f32_16x16x32_bf16 v[76:79], v[152:155], v[214:217], v[76:79]
	v_mfma_f32_16x16x32_bf16 v[72:75], v[160:163], v[214:217], v[72:75]
	v_mfma_f32_16x16x32_bf16 v[124:127], v[156:159], v[188:191], v[124:127]
	v_mfma_f32_16x16x32_bf16 v[120:123], v[164:167], v[188:191], v[120:123]
	v_mfma_f32_16x16x32_bf16 v[108:111], v[156:159], v[196:199], v[108:111]
	v_mfma_f32_16x16x32_bf16 v[104:107], v[164:167], v[196:199], v[104:107]
	v_mfma_f32_16x16x32_bf16 v[92:95], v[156:159], v[208:211], v[92:95]
	v_mfma_f32_16x16x32_bf16 v[88:91], v[164:167], v[208:211], v[88:91]
	v_mfma_f32_16x16x32_bf16 v[76:79], v[156:159], v[218:221], v[76:79]
	v_mfma_f32_16x16x32_bf16 v[72:75], v[164:167], v[218:221], v[72:75]
	s_setprio 0
	s_setprio 1
	v_mfma_f32_16x16x32_bf16 v[116:119], v[168:171], v[184:187], v[116:119]
	v_mfma_f32_16x16x32_bf16 v[112:115], v[176:179], v[184:187], v[112:115]
	v_mfma_f32_16x16x32_bf16 v[100:103], v[168:171], v[192:195], v[100:103]
	v_mfma_f32_16x16x32_bf16 v[96:99], v[176:179], v[192:195], v[96:99]
	v_mfma_f32_16x16x32_bf16 v[84:87], v[168:171], v[200:203], v[84:87]
	v_mfma_f32_16x16x32_bf16 v[80:83], v[176:179], v[200:203], v[80:83]
	v_mfma_f32_16x16x32_bf16 v[68:71], v[168:171], v[214:217], v[68:71]
	v_mfma_f32_16x16x32_bf16 v[64:67], v[176:179], v[214:217], v[64:67]
	v_mfma_f32_16x16x32_bf16 v[116:119], v[172:175], v[188:191], v[116:119]
	v_mfma_f32_16x16x32_bf16 v[112:115], v[180:183], v[188:191], v[112:115]
	v_mfma_f32_16x16x32_bf16 v[100:103], v[172:175], v[196:199], v[100:103]
	v_mfma_f32_16x16x32_bf16 v[96:99], v[180:183], v[196:199], v[96:99]
	v_mfma_f32_16x16x32_bf16 v[84:87], v[172:175], v[208:211], v[84:87]
	v_mfma_f32_16x16x32_bf16 v[80:83], v[180:183], v[208:211], v[80:83]
	v_mfma_f32_16x16x32_bf16 v[68:71], v[172:175], v[218:221], v[68:71]
	v_mfma_f32_16x16x32_bf16 v[64:67], v[180:183], v[218:221], v[64:67]
	s_setprio 0
	s_barrier
	s_add_i32 s16, s16, s45
	v_lshl_add_u64 v[144:145], v[144:145], 0, s[10:11]
	s_mov_b32 m0, s16
	ds_read_b128 v[184:187], v151 offset:49152
	ds_read_b128 v[188:191], v151 offset:50176
	ds_read_b128 v[192:195], v151 offset:51200
	ds_read_b128 v[196:199], v151 offset:52224
	ds_read_b128 v[200:203], v151 offset:53248
	ds_read_b128 v[208:211], v151 offset:54272
	ds_read_b128 v[214:217], v151 offset:55296
	ds_read_b128 v[218:221], v151 offset:56320
	global_load_lds_dwordx4 v[144:145], off
	s_add_i32 m0, s16, 0x2000
	s_add_u32 s34, s38, 0x40080
	v_lshl_add_u64 v[144:145], v[204:205], 0, s[10:11]
	s_addc_u32 s35, s39, 0
	s_add_i32 s16, s17, s45
	global_load_lds_dwordx4 v[144:145], off
	s_mov_b32 m0, s16
	v_lshl_add_u64 v[144:145], s[34:35], 0, v[130:131]
	global_load_lds_dwordx4 v[144:145], off
	s_add_i32 m0, s16, 0x2000
	v_lshl_add_u64 v[144:145], s[34:35], 0, v[134:135]
	global_load_lds_dwordx4 v[144:145], off
	s_mov_b32 m0, s50
	v_lshl_add_u64 v[144:145], v[222:223], 0, s[10:11]
	global_load_lds_dwordx4 v[144:145], off
	v_lshl_add_u64 v[144:145], v[224:225], 0, s[10:11]
	s_nop 0
	s_cmp_lg_u32 s62, 12
	s_cbranch_scc1 .Ldf_skipD_0
	s_mov_b32 m0, s51
	s_nop 0
	global_load_lds_dwordx4 v[144:145], off

; #define PG8_STAGE(bufoff, gbase, voff) do { _Pragma("unroll") for (int _i = 0; _i < 2; ++_i) \
;         __builtin_amdgcn_global_load_lds((const unsigned*)((const char*)(gbase) + (voff)[_i]), (PG8_LAS unsigned*)(lds + (bufoff) + ldsw + _i * 8192), 16, 0, 0); } while (0)
; #define PG8_LDA(dst, b, h) do { _Pragma("unroll") for (int m = 0; m < 4; ++m) _Pragma("unroll") for (int k = 0; k < 2; ++k) dst[m][k] = *(const PG8_LAS bf16x8*)(lds + PG8_SA(b, h) + aoff + m * 2048 + k * 1024); } while (0)
; #define PG8_LDB(dst, b, h) do { _Pragma("unroll") for (int n = 0; n < 2; ++n) _Pragma("unroll") for (int k = 0; k < 2; ++k) dst[n][k] = *(const PG8_LAS bf16x8*)(lds + PG8_SB(b, h) + boff + n * 2048 + k * 1024); } while (0)
; #define PG8_WAIT_V(n) asm volatile("s_waitcnt vmcnt(" #n ")" ::: "memory")
; #define PG8_WAIT_L(n) asm volatile("s_waitcnt lgkmcnt(" #n ")" ::: "memory")
; #define PG8_BAR __builtin_amdgcn_s_barrier()
; #define PG8_SCHED __builtin_amdgcn_sched_barrier(0)
; #define PG8_MMA2(ai) PG8_MMA(ai, 0, At, B0)
;     ...
;         for (int t = 0; t < nt; t += 2) {
;             const bool last = (t == nt - 2);
;             const char* a1 = cA + (size_t)(t + 1) * kstep;
;             const char* a2 = last ? nA : cA + (size_t)(t + 2) * kstep; const char* b2 = last ? nB : cB + (size_t)(t + 2) * kstep;
;             const char* a3 = a2 + kstep; const char* b3 = b2 + kstep;
;             if (last && has_next) S.a_ready(nxt);
;             if constexpr (SP2) {
;             PG8_LDB(B0, 0, 0); PG8_LDB(B1, 0, 1); PG8_SCHED; PG8_LDA(At, 0, 0); PG8_STAGE(PG8_SA(1, 1), a1 + hstep, voffA);
;             PG8_WAIT_V(8); PG8_WAIT_L(0); PG8_BAR; PG8_MMA2(0); PG8_BAR; PG8_SCHED;
;             PG8_LDA(At, 0, 1); PG8_STAGE(PG8_SB(0, 0), b2, voffB); PG8_STAGE(PG8_SB(0, 1), b2 + hstep, voffB); PG8_STAGE(PG8_SA(0, 0), a2, voffA);
;             PG8_WAIT_V(8); PG8_WAIT_L(0); PG8_BAR; PG8_MMA2(1); PG8_BAR; PG8_SCHED;
;             PG8_LDB(B0, 1, 0); PG8_LDB(B1, 1, 1); PG8_SCHED; PG8_LDA(At, 1, 0); PG8_STAGE(PG8_SA(0, 1), a2 + hstep, voffA);
;             PG8_WAIT_V(8); PG8_WAIT_L(0); PG8_BAR; PG8_MMA2(0); PG8_BAR; PG8_SCHED;
;             PG8_LDA(At, 1, 1); PG8_STAGE(PG8_SB(1, 0), b3, voffB); PG8_STAGE(PG8_SB(1, 1), b3 + hstep, voffB); PG8_STAGE(PG8_SA(1, 0), a3, voffA);
;             PG8_WAIT_V(8); PG8_WAIT_L(0); PG8_BAR; PG8_MMA2(1); PG8_BAR; PG8_SCHED;
.Ldf_skipA_1:
	ds_read_b128 v[140:143], v149
	ds_read_b128 v[152:155], v149 offset:1024
	ds_read_b128 v[156:159], v149 offset:2048
	ds_read_b128 v[160:163], v149 offset:3072
	ds_read_b128 v[164:167], v150
	ds_read_b128 v[168:171], v150 offset:1024
	ds_read_b128 v[172:175], v150 offset:2048
	ds_read_b128 v[176:179], v150 offset:3072
	s_add_u32 s36, s26, 0x100
	s_addc_u32 s37, s27, 0
	s_cmp_eq_u32 s69, 40
	s_cselect_b32 s41, s7, s37
	s_cselect_b32 s40, s6, s36
	s_cselect_b32 s39, s23, s68
	s_cselect_b32 s38, s22, s67
	v_lshl_add_u64 v[144:145], s[26:27], 0, v[134:135]
	s_add_i32 m0, s46, 0xc000
	ds_read_b128 v[180:183], v151
	ds_read_b128 v[184:187], v151 offset:1024
	ds_read_b128 v[188:191], v151 offset:2048
	ds_read_b128 v[192:195], v151 offset:3072
	ds_read_b128 v[196:199], v151 offset:4096
	ds_read_b128 v[200:203], v151 offset:5120
	ds_read_b128 v[208:211], v151 offset:6144
	ds_read_b128 v[214:217], v151 offset:7168
	global_load_lds_dwordx4 v[144:145], off
	s_add_i32 m0, s46, 0xe000
	v_lshl_add_u64 v[144:145], s[26:27], 0, v[132:133]
	global_load_lds_dwordx4 v[144:145], off
	s_waitcnt vmcnt(8)
	s_waitcnt lgkmcnt(0)
	s_barrier
	s_setprio 1
	s_waitcnt lgkmcnt(0)
	v_mfma_f32_16x16x32_bf16 v[124:127], v[140:143], v[180:183], v[124:127]
	v_mfma_f32_16x16x32_bf16 v[120:123], v[156:159], v[180:183], v[120:123]
	v_mfma_f32_16x16x32_bf16 v[112:115], v[140:143], v[188:191], v[112:115]
	v_mfma_f32_16x16x32_bf16 v[104:107], v[156:159], v[188:191], v[104:107]
	v_mfma_f32_16x16x32_bf16 v[96:99], v[140:143], v[196:199], v[96:99]
	v_mfma_f32_16x16x32_bf16 v[88:91], v[156:159], v[196:199], v[88:91]
	v_mfma_f32_16x16x32_bf16 v[80:83], v[140:143], v[208:211], v[80:83]
	v_mfma_f32_16x16x32_bf16 v[72:75], v[156:159], v[208:211], v[72:75]
	v_mfma_f32_16x16x32_bf16 v[124:127], v[152:155], v[184:187], v[124:127]
	v_mfma_f32_16x16x32_bf16 v[120:123], v[160:163], v[184:187], v[120:123]
	v_mfma_f32_16x16x32_bf16 v[112:115], v[152:155], v[192:195], v[112:115]
	v_mfma_f32_16x16x32_bf16 v[104:107], v[160:163], v[192:195], v[104:107]
	v_mfma_f32_16x16x32_bf16 v[96:99], v[152:155], v[200:203], v[96:99]
	v_mfma_f32_16x16x32_bf16 v[88:91], v[160:163], v[200:203], v[88:91]
	v_mfma_f32_16x16x32_bf16 v[80:83], v[152:155], v[214:217], v[80:83]
	v_mfma_f32_16x16x32_bf16 v[72:75], v[160:163], v[214:217], v[72:75]
	s_setprio 0
	s_setprio 1
	v_mfma_f32_16x16x32_bf16 v[116:119], v[164:167], v[180:183], v[116:119]
	v_mfma_f32_16x16x32_bf16 v[108:111], v[172:175], v[180:183], v[108:111]
	v_mfma_f32_16x16x32_bf16 v[100:103], v[164:167], v[188:191], v[100:103]
	v_mfma_f32_16x16x32_bf16 v[92:95], v[172:175], v[188:191], v[92:95]
	v_mfma_f32_16x16x32_bf16 v[84:87], v[164:167], v[196:199], v[84:87]
	v_mfma_f32_16x16x32_bf16 v[76:79], v[172:175], v[196:199], v[76:79]
	v_mfma_f32_16x16x32_bf16 v[68:71], v[164:167], v[208:211], v[68:71]
	v_mfma_f32_16x16x32_bf16 v[64:67], v[172:175], v[208:211], v[64:67]
	v_mfma_f32_16x16x32_bf16 v[116:119], v[168:171], v[184:187], v[116:119]
	v_mfma_f32_16x16x32_bf16 v[108:111], v[176:179], v[184:187], v[108:111]
	v_mfma_f32_16x16x32_bf16 v[100:103], v[168:171], v[192:195], v[100:103]
	v_mfma_f32_16x16x32_bf16 v[92:95], v[176:179], v[192:195], v[92:95]
	v_mfma_f32_16x16x32_bf16 v[84:87], v[168:171], v[200:203], v[84:87]
	v_mfma_f32_16x16x32_bf16 v[76:79], v[176:179], v[200:203], v[76:79]
	v_mfma_f32_16x16x32_bf16 v[68:71], v[168:171], v[214:217], v[68:71]
	v_mfma_f32_16x16x32_bf16 v[64:67], v[176:179], v[214:217], v[64:67]
	s_setprio 0
	s_barrier
	s_add_i32 s16, s60, s45
	v_lshl_add_u64 v[144:145], s[38:39], 0, v[128:129]
	s_mov_b32 m0, s16
	ds_read_b128 v[180:183], v151 offset:16384
	ds_read_b128 v[184:187], v151 offset:17408
	ds_read_b128 v[188:191], v151 offset:18432
	ds_read_b128 v[192:195], v151 offset:19456
	ds_read_b128 v[196:199], v151 offset:20480
	ds_read_b128 v[200:203], v151 offset:21504
	ds_read_b128 v[208:211], v151 offset:22528
	ds_read_b128 v[214:217], v151 offset:23552
	global_load_lds_dwordx4 v[144:145], off
	s_add_i32 m0, s16, 0x2000
	s_add_u32 s26, s38, 0xb0000
	v_lshl_add_u64 v[204:205], s[38:39], 0, v[130:131]
	s_addc_u32 s27, s39, 0
	s_add_i32 s16, s61, s45
	global_load_lds_dwordx4 v[204:205], off
	v_lshl_add_u64 v[218:219], s[26:27], 0, v[128:129]
	s_mov_b32 m0, s16
	v_lshl_add_u64 v[220:221], s[40:41], 0, v[130:131]
	global_load_lds_dwordx4 v[218:219], off
	s_add_i32 m0, s16, 0x2000
	v_lshl_add_u64 v[218:219], s[26:27], 0, v[130:131]
	global_load_lds_dwordx4 v[218:219], off
	s_mov_b32 m0, s46
	v_lshl_add_u64 v[218:219], s[40:41], 0, v[128:129]
	global_load_lds_dwordx4 v[218:219], off
	s_nop 0
	s_waitcnt vmcnt(7)
	s_waitcnt lgkmcnt(0)
	s_barrier
; #define PG8_STAGE(bufoff, gbase, voff) do { _Pragma("unroll") for (int _i = 0; _i < 2; ++_i) \
;         __builtin_amdgcn_global_load_lds((const unsigned*)((const char*)(gbase) + (voff)[_i]), (PG8_LAS unsigned*)(lds + (bufoff) + ldsw + _i * 8192), 16, 0, 0); } while (0)
; #define PG8_LDA(dst, b, h) do { _Pragma("unroll") for (int m = 0; m < 4; ++m) _Pragma("unroll") for (int k = 0; k < 2; ++k) dst[m][k] = *(const PG8_LAS bf16x8*)(lds + PG8_SA(b, h) + aoff + m * 2048 + k * 1024); } while (0)
; #define PG8_LDB(dst, b, h) do { _Pragma("unroll") for (int n = 0; n < 2; ++n) _Pragma("unroll") for (int k = 0; k < 2; ++k) dst[n][k] = *(const PG8_LAS bf16x8*)(lds + PG8_SB(b, h) + boff + n * 2048 + k * 1024); } while (0)
; #define PG8_WAIT_V(n) asm volatile("s_waitcnt vmcnt(" #n ")" ::: "memory")
; #define PG8_WAIT_L(n) asm volatile("s_waitcnt lgkmcnt(" #n ")" ::: "memory")
; #define PG8_BAR __builtin_amdgcn_s_barrier()
; #define PG8_SCHED __builtin_amdgcn_sched_barrier(0)
; #define PG8_MMA2(ai) PG8_MMA(ai, 0, At, B0)
;     ...
;         for (int t = 0; t < nt; t += 2) {
;             const bool last = (t == nt - 2);
;             const char* a1 = cA + (size_t)(t + 1) * kstep;
;             const char* a2 = last ? nA : cA + (size_t)(t + 2) * kstep; const char* b2 = last ? nB : cB + (size_t)(t + 2) * kstep;
;             const char* a3 = a2 + kstep; const char* b3 = b2 + kstep;
;             if (last && has_next) S.a_ready(nxt);
;             if constexpr (SP2) {
;             PG8_LDB(B0, 0, 0); PG8_LDB(B1, 0, 1); PG8_SCHED; PG8_LDA(At, 0, 0); PG8_STAGE(PG8_SA(1, 1), a1 + hstep, voffA);
;             PG8_WAIT_V(8); PG8_WAIT_L(0); PG8_BAR; PG8_MMA2(0); PG8_BAR; PG8_SCHED;
;             PG8_LDA(At, 0, 1); PG8_STAGE(PG8_SB(0, 0), b2, voffB); PG8_STAGE(PG8_SB(0, 1), b2 + hstep, voffB); PG8_STAGE(PG8_SA(0, 0), a2, voffA);
;             PG8_WAIT_V(8); PG8_WAIT_L(0); PG8_BAR; PG8_MMA2(1); PG8_BAR; PG8_SCHED;
;             PG8_LDB(B0, 1, 0); PG8_LDB(B1, 1, 1); PG8_SCHED; PG8_LDA(At, 1, 0); PG8_STAGE(PG8_SA(0, 1), a2 + hstep, voffA);
;             PG8_WAIT_V(8); PG8_WAIT_L(0); PG8_BAR; PG8_MMA2(0); PG8_BAR; PG8_SCHED;
;             PG8_LDA(At, 1, 1); PG8_STAGE(PG8_SB(1, 0), b3, voffB); PG8_STAGE(PG8_SB(1, 1), b3 + hstep, voffB); PG8_STAGE(PG8_SA(1, 0), a3, voffA);
;             PG8_WAIT_V(8); PG8_WAIT_L(0); PG8_BAR; PG8_MMA2(1); PG8_BAR; PG8_SCHED;
	s_setprio 1
	s_waitcnt lgkmcnt(0)
	v_mfma_f32_16x16x32_bf16 v[60:63], v[140:143], v[180:183], v[60:63]
	v_mfma_f32_16x16x32_bf16 v[56:59], v[156:159], v[180:183], v[56:59]
	v_mfma_f32_16x16x32_bf16 v[48:51], v[140:143], v[188:191], v[48:51]
	v_mfma_f32_16x16x32_bf16 v[40:43], v[156:159], v[188:191], v[40:43]
	v_mfma_f32_16x16x32_bf16 v[32:35], v[140:143], v[196:199], v[32:35]
	v_mfma_f32_16x16x32_bf16 v[24:27], v[156:159], v[196:199], v[24:27]
	v_mfma_f32_16x16x32_bf16 v[16:19], v[140:143], v[208:211], v[16:19]
	v_mfma_f32_16x16x32_bf16 v[8:11], v[156:159], v[208:211], v[8:11]
	v_mfma_f32_16x16x32_bf16 v[60:63], v[152:155], v[184:187], v[60:63]
	v_mfma_f32_16x16x32_bf16 v[56:59], v[160:163], v[184:187], v[56:59]
	v_mfma_f32_16x16x32_bf16 v[48:51], v[152:155], v[192:195], v[48:51]
	v_mfma_f32_16x16x32_bf16 v[40:43], v[160:163], v[192:195], v[40:43]
	v_mfma_f32_16x16x32_bf16 v[32:35], v[152:155], v[200:203], v[32:35]
	v_mfma_f32_16x16x32_bf16 v[24:27], v[160:163], v[200:203], v[24:27]
	v_mfma_f32_16x16x32_bf16 v[16:19], v[152:155], v[214:217], v[16:19]
	v_mfma_f32_16x16x32_bf16 v[8:11], v[160:163], v[214:217], v[8:11]
	s_setprio 0
	s_setprio 1
	v_mfma_f32_16x16x32_bf16 v[52:55], v[164:167], v[180:183], v[52:55]
	v_mfma_f32_16x16x32_bf16 v[44:47], v[172:175], v[180:183], v[44:47]
	v_mfma_f32_16x16x32_bf16 v[36:39], v[164:167], v[188:191], v[36:39]
	v_mfma_f32_16x16x32_bf16 v[28:31], v[172:175], v[188:191], v[28:31]
	v_mfma_f32_16x16x32_bf16 v[20:23], v[164:167], v[196:199], v[20:23]
	v_mfma_f32_16x16x32_bf16 v[12:15], v[172:175], v[196:199], v[12:15]
	v_mfma_f32_16x16x32_bf16 v[4:7], v[164:167], v[208:211], v[4:7]
	v_mfma_f32_16x16x32_bf16 v[0:3], v[172:175], v[208:211], v[0:3]
	v_mfma_f32_16x16x32_bf16 v[52:55], v[168:171], v[184:187], v[52:55]
	v_mfma_f32_16x16x32_bf16 v[44:47], v[176:179], v[184:187], v[44:47]
	v_mfma_f32_16x16x32_bf16 v[36:39], v[168:171], v[192:195], v[36:39]
	v_mfma_f32_16x16x32_bf16 v[28:31], v[176:179], v[192:195], v[28:31]
	v_mfma_f32_16x16x32_bf16 v[20:23], v[168:171], v[200:203], v[20:23]
	v_mfma_f32_16x16x32_bf16 v[12:15], v[176:179], v[200:203], v[12:15]
	v_mfma_f32_16x16x32_bf16 v[4:7], v[168:171], v[214:217], v[4:7]
	v_mfma_f32_16x16x32_bf16 v[0:3], v[176:179], v[214:217], v[0:3]
	s_setprio 0
	s_barrier
	s_add_i32 s16, 0, 0x18000
	s_add_i32 s17, 0, 0x1c000
	v_add_u32_e32 v160, s16, v147
	v_add_u32_e32 v176, s17, v147
	ds_read_b128 v[140:143], v160
	ds_read_b128 v[152:155], v160 offset:1024
	ds_read_b128 v[156:159], v160 offset:2048
	ds_read_b128 v[160:163], v160 offset:3072
	ds_read_b128 v[164:167], v176
	ds_read_b128 v[168:171], v176 offset:1024
	ds_read_b128 v[172:175], v176 offset:2048
	ds_read_b128 v[176:179], v176 offset:3072
	s_add_u32 s26, s40, 0xb0000
	s_addc_u32 s27, s41, 0
	s_mov_b32 m0, s47
	s_nop 0
	global_load_lds_dwordx4 v[220:221], off
	s_mov_b32 m0, s48
	v_lshl_add_u64 v[222:223], s[26:27], 0, v[128:129]
	ds_read_b128 v[180:183], v151 offset:32768
	ds_read_b128 v[184:187], v151 offset:33792
	ds_read_b128 v[188:191], v151 offset:34816
	ds_read_b128 v[192:195], v151 offset:35840
	ds_read_b128 v[196:199], v151 offset:36864
	ds_read_b128 v[200:203], v151 offset:37888
	ds_read_b128 v[208:211], v151 offset:38912
	ds_read_b128 v[214:217], v151 offset:39936
	global_load_lds_dwordx4 v[222:223], off
	s_mov_b32 m0, s49
	v_lshl_add_u64 v[222:223], s[26:27], 0, v[130:131]
	global_load_lds_dwordx4 v[222:223], off
	s_waitcnt vmcnt(8)
	s_waitcnt lgkmcnt(0)
	s_barrier
	s_setprio 1
	s_waitcnt lgkmcnt(0)
	v_mfma_f32_16x16x32_bf16 v[124:127], v[140:143], v[180:183], v[124:127]
	v_mfma_f32_16x16x32_bf16 v[120:123], v[156:159], v[180:183], v[120:123]
	v_mfma_f32_16x16x32_bf16 v[112:115], v[140:143], v[188:191], v[112:115]
	v_mfma_f32_16x16x32_bf16 v[104:107], v[156:159], v[188:191], v[104:107]
	v_mfma_f32_16x16x32_bf16 v[96:99], v[140:143], v[196:199], v[96:99]
	v_mfma_f32_16x16x32_bf16 v[88:91], v[156:159], v[196:199], v[88:91]
	v_mfma_f32_16x16x32_bf16 v[80:83], v[140:143], v[208:211], v[80:83]
	v_mfma_f32_16x16x32_bf16 v[72:75], v[156:159], v[208:211], v[72:75]
	v_mfma_f32_16x16x32_bf16 v[124:127], v[152:155], v[184:187], v[124:127]
	v_mfma_f32_16x16x32_bf16 v[120:123], v[160:163], v[184:187], v[120:123]
	v_mfma_f32_16x16x32_bf16 v[112:115], v[152:155], v[192:195], v[112:115]
	v_mfma_f32_16x16x32_bf16 v[104:107], v[160:163], v[192:195], v[104:107]
	v_mfma_f32_16x16x32_bf16 v[96:99], v[152:155], v[200:203], v[96:99]
	v_mfma_f32_16x16x32_bf16 v[88:91], v[160:163], v[200:203], v[88:91]
	v_mfma_f32_16x16x32_bf16 v[80:83], v[152:155], v[214:217], v[80:83]
	v_mfma_f32_16x16x32_bf16 v[72:75], v[160:163], v[214:217], v[72:75]
	s_setprio 0
	s_setprio 1
	v_mfma_f32_16x16x32_bf16 v[116:119], v[164:167], v[180:183], v[116:119]
	v_mfma_f32_16x16x32_bf16 v[108:111], v[172:175], v[180:183], v[108:111]
	v_mfma_f32_16x16x32_bf16 v[100:103], v[164:167], v[188:191], v[100:103]
	v_mfma_f32_16x16x32_bf16 v[92:95], v[172:175], v[188:191], v[92:95]
	v_mfma_f32_16x16x32_bf16 v[84:87], v[164:167], v[196:199], v[84:87]
	v_mfma_f32_16x16x32_bf16 v[76:79], v[172:175], v[196:199], v[76:79]
	v_mfma_f32_16x16x32_bf16 v[68:71], v[164:167], v[208:211], v[68:71]
	v_mfma_f32_16x16x32_bf16 v[64:67], v[172:175], v[208:211], v[64:67]
	v_mfma_f32_16x16x32_bf16 v[116:119], v[168:171], v[184:187], v[116:119]
	v_mfma_f32_16x16x32_bf16 v[108:111], v[176:179], v[184:187], v[108:111]
	v_mfma_f32_16x16x32_bf16 v[100:103], v[168:171], v[192:195], v[100:103]
	v_mfma_f32_16x16x32_bf16 v[92:95], v[176:179], v[192:195], v[92:95]
	v_mfma_f32_16x16x32_bf16 v[84:87], v[168:171], v[200:203], v[84:87]
	v_mfma_f32_16x16x32_bf16 v[76:79], v[176:179], v[200:203], v[76:79]
	v_mfma_f32_16x16x32_bf16 v[68:71], v[168:171], v[214:217], v[68:71]
	v_mfma_f32_16x16x32_bf16 v[64:67], v[176:179], v[214:217], v[64:67]
	s_setprio 0
	s_barrier
	s_add_i32 s16, s16, s45
	v_lshl_add_u64 v[144:145], v[144:145], 0, s[14:15]
	s_mov_b32 m0, s16
	ds_read_b128 v[180:183], v151 offset:49152
	ds_read_b128 v[184:187], v151 offset:50176
	ds_read_b128 v[188:191], v151 offset:51200
	ds_read_b128 v[192:195], v151 offset:52224
	ds_read_b128 v[196:199], v151 offset:53248
	ds_read_b128 v[200:203], v151 offset:54272
	ds_read_b128 v[208:211], v151 offset:55296
	ds_read_b128 v[214:217], v151 offset:56320
	global_load_lds_dwordx4 v[144:145], off
	s_add_i32 m0, s16, 0x2000
	s_add_u32 s26, s38, 0xb0080
	v_lshl_add_u64 v[144:145], v[204:205], 0, s[14:15]
	s_addc_u32 s27, s39, 0
	s_add_i32 s16, s17, s45
	global_load_lds_dwordx4 v[144:145], off
	s_mov_b32 m0, s16
	v_lshl_add_u64 v[144:145], s[26:27], 0, v[128:129]
	global_load_lds_dwordx4 v[144:145], off
	s_add_i32 m0, s16, 0x2000
	v_lshl_add_u64 v[144:145], s[26:27], 0, v[130:131]
	global_load_lds_dwordx4 v[144:145], off
	s_mov_b32 m0, s55
	v_lshl_add_u64 v[144:145], v[218:219], 0, s[14:15]
	global_load_lds_dwordx4 v[144:145], off
	v_lshl_add_u64 v[144:145], v[220:221], 0, s[14:15]
	s_nop 0
	s_cmp_lg_u32 s69, 40
	s_cbranch_scc1 .Ldf_skipD_1
	s_mov_b32 m0, s56
	s_nop 0
	global_load_lds_dwordx4 v[144:145], off

; #define PG8_STAGE(bufoff, gbase, voff) do { _Pragma("unroll") for (int _i = 0; _i < 2; ++_i) \
;         __builtin_amdgcn_global_load_lds((const unsigned*)((const char*)(gbase) + (voff)[_i]), (PG8_LAS unsigned*)(lds + (bufoff) + ldsw + _i * 8192), 16, 0, 0); } while (0)
; #define PG8_LDA(dst, b, h) do { _Pragma("unroll") for (int m = 0; m < 4; ++m) _Pragma("unroll") for (int k = 0; k < 2; ++k) dst[m][k] = *(const PG8_LAS bf16x8*)(lds + PG8_SA(b, h) + aoff + m * 2048 + k * 1024); } while (0)
; #define PG8_LDB(dst, b, h) do { _Pragma("unroll") for (int n = 0; n < 2; ++n) _Pragma("unroll") for (int k = 0; k < 2; ++k) dst[n][k] = *(const PG8_LAS bf16x8*)(lds + PG8_SB(b, h) + boff + n * 2048 + k * 1024); } while (0)
; #define PG8_WAIT_V(n) asm volatile("s_waitcnt vmcnt(" #n ")" ::: "memory")
; #define PG8_WAIT_L(n) asm volatile("s_waitcnt lgkmcnt(" #n ")" ::: "memory")
; #define PG8_BAR __builtin_amdgcn_s_barrier()
; #define PG8_SCHED __builtin_amdgcn_sched_barrier(0)
; #define PG8_MMA2(ai) PG8_MMA(ai, 0, At, B0)
;     ...
;         for (int t = 0; t < nt; t += 2) {
;             const bool last = (t == nt - 2);
;             const char* a1 = cA + (size_t)(t + 1) * kstep;
;             const char* a2 = last ? nA : cA + (size_t)(t + 2) * kstep; const char* b2 = last ? nB : cB + (size_t)(t + 2) * kstep;
;             const char* a3 = a2 + kstep; const char* b3 = b2 + kstep;
;             if (last && has_next) S.a_ready(nxt);
;             if constexpr (SP2) {
;             PG8_LDB(B0, 0, 0); PG8_LDB(B1, 0, 1); PG8_SCHED; PG8_LDA(At, 0, 0); PG8_STAGE(PG8_SA(1, 1), a1 + hstep, voffA);
;             PG8_WAIT_V(8); PG8_WAIT_L(0); PG8_BAR; PG8_MMA2(0); PG8_BAR; PG8_SCHED;
;             PG8_LDA(At, 0, 1); PG8_STAGE(PG8_SB(0, 0), b2, voffB); PG8_STAGE(PG8_SB(0, 1), b2 + hstep, voffB); PG8_STAGE(PG8_SA(0, 0), a2, voffA);
;             PG8_WAIT_V(8); PG8_WAIT_L(0); PG8_BAR; PG8_MMA2(1); PG8_BAR; PG8_SCHED;
;             PG8_LDB(B0, 1, 0); PG8_LDB(B1, 1, 1); PG8_SCHED; PG8_LDA(At, 1, 0); PG8_STAGE(PG8_SA(0, 1), a2 + hstep, voffA);
;             PG8_WAIT_V(8); PG8_WAIT_L(0); PG8_BAR; PG8_MMA2(0); PG8_BAR; PG8_SCHED;
;             PG8_LDA(At, 1, 1); PG8_STAGE(PG8_SB(1, 0), b3, voffB); PG8_STAGE(PG8_SB(1, 1), b3 + hstep, voffB); PG8_STAGE(PG8_SA(1, 0), a3, voffA);
;             PG8_WAIT_V(8); PG8_WAIT_L(0); PG8_BAR; PG8_MMA2(1); PG8_BAR; PG8_SCHED;
.Ldf_skipA_2:
	s_waitcnt lgkmcnt(0)
	ds_read_b128 v[128:131], v182
	ds_read_b128 v[132:135], v182 offset:1024
	ds_read_b128 v[136:139], v182 offset:2048
	ds_read_b128 v[140:143], v182 offset:3072
	ds_read_b128 v[168:171], v183
	ds_read_b128 v[188:191], v183 offset:1024
	ds_read_b128 v[192:195], v183 offset:2048
	ds_read_b128 v[196:199], v183 offset:3072
	s_add_u32 s16, s12, 0xfffc0080
	s_addc_u32 s17, s13, -1
	s_cmp_eq_u32 s67, 12
	s_cselect_b32 s71, s6, s17
	s_cselect_b32 s70, s7, s16
	s_cselect_b32 s69, s15, s61
	s_cselect_b32 s68, s22, s59
	v_lshl_add_u64 v[172:173], s[12:13], 0, v[162:163]
	s_add_i32 m0, s75, 0xc000
	ds_read_b128 v[200:203], v184
	ds_read_b128 v[208:211], v184 offset:1024
	ds_read_b128 v[214:217], v184 offset:2048
	ds_read_b128 v[218:221], v184 offset:3072
	ds_read_b128 v[222:225], v184 offset:4096
	ds_read_b128 v[226:229], v184 offset:5120
	ds_read_b128 v[230:233], v184 offset:6144
	ds_read_b128 v[234:237], v184 offset:7168
	global_load_lds_dwordx4 v[172:173], off
	s_add_i32 m0, s75, 0xe000
	v_lshl_add_u64 v[172:173], s[12:13], 0, v[160:161]
	global_load_lds_dwordx4 v[172:173], off
	s_waitcnt vmcnt(8)
	s_waitcnt lgkmcnt(0)
	s_barrier
	s_setprio 1
	s_waitcnt lgkmcnt(0)
	v_mfma_f32_16x16x32_bf16 v[124:127], v[128:131], v[200:203], v[124:127]
	v_mfma_f32_16x16x32_bf16 v[120:123], v[136:139], v[200:203], v[120:123]
	v_mfma_f32_16x16x32_bf16 v[108:111], v[128:131], v[214:217], v[108:111]
	v_mfma_f32_16x16x32_bf16 v[104:107], v[136:139], v[214:217], v[104:107]
	v_mfma_f32_16x16x32_bf16 v[92:95], v[128:131], v[222:225], v[92:95]
	v_mfma_f32_16x16x32_bf16 v[88:91], v[136:139], v[222:225], v[88:91]
	v_mfma_f32_16x16x32_bf16 v[76:79], v[128:131], v[230:233], v[76:79]
	v_mfma_f32_16x16x32_bf16 v[72:75], v[136:139], v[230:233], v[72:75]
	v_mfma_f32_16x16x32_bf16 v[124:127], v[132:135], v[208:211], v[124:127]
	v_mfma_f32_16x16x32_bf16 v[120:123], v[140:143], v[208:211], v[120:123]
	v_mfma_f32_16x16x32_bf16 v[108:111], v[132:135], v[218:221], v[108:111]
	v_mfma_f32_16x16x32_bf16 v[104:107], v[140:143], v[218:221], v[104:107]
	v_mfma_f32_16x16x32_bf16 v[92:95], v[132:135], v[226:229], v[92:95]
	v_mfma_f32_16x16x32_bf16 v[88:91], v[140:143], v[226:229], v[88:91]
	v_mfma_f32_16x16x32_bf16 v[76:79], v[132:135], v[234:237], v[76:79]
	v_mfma_f32_16x16x32_bf16 v[72:75], v[140:143], v[234:237], v[72:75]
	s_setprio 0
	s_setprio 1
	v_mfma_f32_16x16x32_bf16 v[116:119], v[168:171], v[200:203], v[116:119]
	v_mfma_f32_16x16x32_bf16 v[112:115], v[192:195], v[200:203], v[112:115]
	v_mfma_f32_16x16x32_bf16 v[100:103], v[168:171], v[214:217], v[100:103]
	v_mfma_f32_16x16x32_bf16 v[96:99], v[192:195], v[214:217], v[96:99]
	v_mfma_f32_16x16x32_bf16 v[84:87], v[168:171], v[222:225], v[84:87]
	v_mfma_f32_16x16x32_bf16 v[80:83], v[192:195], v[222:225], v[80:83]
	v_mfma_f32_16x16x32_bf16 v[68:71], v[168:171], v[230:233], v[68:71]
	v_mfma_f32_16x16x32_bf16 v[64:67], v[192:195], v[230:233], v[64:67]
	v_mfma_f32_16x16x32_bf16 v[116:119], v[188:191], v[208:211], v[116:119]
	v_mfma_f32_16x16x32_bf16 v[112:115], v[196:199], v[208:211], v[112:115]
	v_mfma_f32_16x16x32_bf16 v[100:103], v[188:191], v[218:221], v[100:103]
	v_mfma_f32_16x16x32_bf16 v[96:99], v[196:199], v[218:221], v[96:99]
	v_mfma_f32_16x16x32_bf16 v[84:87], v[188:191], v[226:229], v[84:87]
	v_mfma_f32_16x16x32_bf16 v[80:83], v[196:199], v[226:229], v[80:83]
	v_mfma_f32_16x16x32_bf16 v[68:71], v[188:191], v[234:237], v[68:71]
	v_mfma_f32_16x16x32_bf16 v[64:67], v[196:199], v[234:237], v[64:67]
	s_setprio 0
	s_barrier
	s_add_i32 s16, s88, s74
	v_lshl_add_u64 v[172:173], s[68:69], 0, v[146:147]
	s_mov_b32 m0, s16
	ds_read_b128 v[200:203], v184 offset:16384
	ds_read_b128 v[208:211], v184 offset:17408
	ds_read_b128 v[214:217], v184 offset:18432
	ds_read_b128 v[218:221], v184 offset:19456
	ds_read_b128 v[222:225], v184 offset:20480
	ds_read_b128 v[226:229], v184 offset:21504
	ds_read_b128 v[230:233], v184 offset:22528
	ds_read_b128 v[234:237], v184 offset:23552
	global_load_lds_dwordx4 v[172:173], off
	s_add_i32 m0, s16, 0x2000
	s_add_u32 s34, s68, 0x40000
	v_lshl_add_u64 v[204:205], s[68:69], 0, v[150:151]
	s_addc_u32 s35, s69, 0
	s_add_i32 s16, s89, s74
	global_load_lds_dwordx4 v[204:205], off
	v_lshl_add_u64 v[238:239], s[34:35], 0, v[146:147]
	s_mov_b32 m0, s16
	v_lshl_add_u64 v[240:241], s[70:71], 0, v[148:149]
	global_load_lds_dwordx4 v[238:239], off
	s_add_i32 m0, s16, 0x2000
	v_lshl_add_u64 v[238:239], s[34:35], 0, v[150:151]
	global_load_lds_dwordx4 v[238:239], off
	s_mov_b32 m0, s75
	v_lshl_add_u64 v[238:239], s[70:71], 0, v[144:145]
	global_load_lds_dwordx4 v[238:239], off
	s_nop 0
	s_waitcnt vmcnt(7)
	s_waitcnt lgkmcnt(0)
	s_barrier
; #define PG8_STAGE(bufoff, gbase, voff) do { _Pragma("unroll") for (int _i = 0; _i < 2; ++_i) \
;         __builtin_amdgcn_global_load_lds((const unsigned*)((const char*)(gbase) + (voff)[_i]), (PG8_LAS unsigned*)(lds + (bufoff) + ldsw + _i * 8192), 16, 0, 0); } while (0)
; #define PG8_LDA(dst, b, h) do { _Pragma("unroll") for (int m = 0; m < 4; ++m) _Pragma("unroll") for (int k = 0; k < 2; ++k) dst[m][k] = *(const PG8_LAS bf16x8*)(lds + PG8_SA(b, h) + aoff + m * 2048 + k * 1024); } while (0)
; #define PG8_LDB(dst, b, h) do { _Pragma("unroll") for (int n = 0; n < 2; ++n) _Pragma("unroll") for (int k = 0; k < 2; ++k) dst[n][k] = *(const PG8_LAS bf16x8*)(lds + PG8_SB(b, h) + boff + n * 2048 + k * 1024); } while (0)
; #define PG8_WAIT_V(n) asm volatile("s_waitcnt vmcnt(" #n ")" ::: "memory")
; #define PG8_WAIT_L(n) asm volatile("s_waitcnt lgkmcnt(" #n ")" ::: "memory")
; #define PG8_BAR __builtin_amdgcn_s_barrier()
; #define PG8_SCHED __builtin_amdgcn_sched_barrier(0)
; #define PG8_MMA2(ai) PG8_MMA(ai, 0, At, B0)
;     ...
;         for (int t = 0; t < nt; t += 2) {
;             const bool last = (t == nt - 2);
;             const char* a1 = cA + (size_t)(t + 1) * kstep;
;             const char* a2 = last ? nA : cA + (size_t)(t + 2) * kstep; const char* b2 = last ? nB : cB + (size_t)(t + 2) * kstep;
;             const char* a3 = a2 + kstep; const char* b3 = b2 + kstep;
;             if (last && has_next) S.a_ready(nxt);
;             if constexpr (SP2) {
;             PG8_LDB(B0, 0, 0); PG8_LDB(B1, 0, 1); PG8_SCHED; PG8_LDA(At, 0, 0); PG8_STAGE(PG8_SA(1, 1), a1 + hstep, voffA);
;             PG8_WAIT_V(8); PG8_WAIT_L(0); PG8_BAR; PG8_MMA2(0); PG8_BAR; PG8_SCHED;
;             PG8_LDA(At, 0, 1); PG8_STAGE(PG8_SB(0, 0), b2, voffB); PG8_STAGE(PG8_SB(0, 1), b2 + hstep, voffB); PG8_STAGE(PG8_SA(0, 0), a2, voffA);
;             PG8_WAIT_V(8); PG8_WAIT_L(0); PG8_BAR; PG8_MMA2(1); PG8_BAR; PG8_SCHED;
;             PG8_LDB(B0, 1, 0); PG8_LDB(B1, 1, 1); PG8_SCHED; PG8_LDA(At, 1, 0); PG8_STAGE(PG8_SA(0, 1), a2 + hstep, voffA);
;             PG8_WAIT_V(8); PG8_WAIT_L(0); PG8_BAR; PG8_MMA2(0); PG8_BAR; PG8_SCHED;
;             PG8_LDA(At, 1, 1); PG8_STAGE(PG8_SB(1, 0), b3, voffB); PG8_STAGE(PG8_SB(1, 1), b3 + hstep, voffB); PG8_STAGE(PG8_SA(1, 0), a3, voffA);
;             PG8_WAIT_V(8); PG8_WAIT_L(0); PG8_BAR; PG8_MMA2(1); PG8_BAR; PG8_SCHED;
	s_setprio 1
	s_waitcnt lgkmcnt(0)
	v_mfma_f32_16x16x32_bf16 v[60:63], v[128:131], v[200:203], v[60:63]
	v_mfma_f32_16x16x32_bf16 v[56:59], v[136:139], v[200:203], v[56:59]
	v_mfma_f32_16x16x32_bf16 v[44:47], v[128:131], v[214:217], v[44:47]
	v_mfma_f32_16x16x32_bf16 v[40:43], v[136:139], v[214:217], v[40:43]
	v_mfma_f32_16x16x32_bf16 v[28:31], v[128:131], v[222:225], v[28:31]
	v_mfma_f32_16x16x32_bf16 v[24:27], v[136:139], v[222:225], v[24:27]
	v_mfma_f32_16x16x32_bf16 v[12:15], v[128:131], v[230:233], v[12:15]
	v_mfma_f32_16x16x32_bf16 v[8:11], v[136:139], v[230:233], v[8:11]
	v_mfma_f32_16x16x32_bf16 v[60:63], v[132:135], v[208:211], v[60:63]
	v_mfma_f32_16x16x32_bf16 v[56:59], v[140:143], v[208:211], v[56:59]
	v_mfma_f32_16x16x32_bf16 v[44:47], v[132:135], v[218:221], v[44:47]
	v_mfma_f32_16x16x32_bf16 v[40:43], v[140:143], v[218:221], v[40:43]
	v_mfma_f32_16x16x32_bf16 v[28:31], v[132:135], v[226:229], v[28:31]
	v_mfma_f32_16x16x32_bf16 v[24:27], v[140:143], v[226:229], v[24:27]
	v_mfma_f32_16x16x32_bf16 v[12:15], v[132:135], v[234:237], v[12:15]
	v_mfma_f32_16x16x32_bf16 v[8:11], v[140:143], v[234:237], v[8:11]
	s_setprio 0
	s_setprio 1
	v_mfma_f32_16x16x32_bf16 v[52:55], v[168:171], v[200:203], v[52:55]
	v_mfma_f32_16x16x32_bf16 v[48:51], v[192:195], v[200:203], v[48:51]
	v_mfma_f32_16x16x32_bf16 v[36:39], v[168:171], v[214:217], v[36:39]
	v_mfma_f32_16x16x32_bf16 v[32:35], v[192:195], v[214:217], v[32:35]
	v_mfma_f32_16x16x32_bf16 v[20:23], v[168:171], v[222:225], v[20:23]
	v_mfma_f32_16x16x32_bf16 v[16:19], v[192:195], v[222:225], v[16:19]
	v_mfma_f32_16x16x32_bf16 v[4:7], v[168:171], v[230:233], v[4:7]
	v_mfma_f32_16x16x32_bf16 v[0:3], v[192:195], v[230:233], v[0:3]
	v_mfma_f32_16x16x32_bf16 v[52:55], v[188:191], v[208:211], v[52:55]
	v_mfma_f32_16x16x32_bf16 v[48:51], v[196:199], v[208:211], v[48:51]
	v_mfma_f32_16x16x32_bf16 v[36:39], v[188:191], v[218:221], v[36:39]
	v_mfma_f32_16x16x32_bf16 v[32:35], v[196:199], v[218:221], v[32:35]
	v_mfma_f32_16x16x32_bf16 v[20:23], v[188:191], v[226:229], v[20:23]
	v_mfma_f32_16x16x32_bf16 v[16:19], v[196:199], v[226:229], v[16:19]
	v_mfma_f32_16x16x32_bf16 v[4:7], v[188:191], v[234:237], v[4:7]
	v_mfma_f32_16x16x32_bf16 v[0:3], v[196:199], v[234:237], v[0:3]
	s_setprio 0
	s_barrier
	s_add_i32 s16, 0, 0x18000
	s_add_i32 s17, 0, 0x1c000
	v_add_u32_e32 v140, s16, v174
	v_add_u32_e32 v196, s17, v174
	ds_read_b128 v[128:131], v140
	ds_read_b128 v[132:135], v140 offset:1024
	ds_read_b128 v[136:139], v140 offset:2048
	ds_read_b128 v[140:143], v140 offset:3072
	ds_read_b128 v[168:171], v196
	ds_read_b128 v[188:191], v196 offset:1024
	ds_read_b128 v[192:195], v196 offset:2048
	ds_read_b128 v[196:199], v196 offset:3072
	s_add_u32 s34, s70, 0x40000
	s_addc_u32 s35, s71, 0
	s_mov_b32 m0, s76
	s_nop 0
	global_load_lds_dwordx4 v[240:241], off
	s_mov_b32 m0, s77
	v_lshl_add_u64 v[242:243], s[34:35], 0, v[144:145]
	ds_read_b128 v[200:203], v184 offset:32768
	ds_read_b128 v[208:211], v184 offset:33792
	ds_read_b128 v[214:217], v184 offset:34816
	ds_read_b128 v[218:221], v184 offset:35840
	ds_read_b128 v[222:225], v184 offset:36864
	ds_read_b128 v[226:229], v184 offset:37888
	ds_read_b128 v[230:233], v184 offset:38912
	ds_read_b128 v[234:237], v184 offset:39936
	global_load_lds_dwordx4 v[242:243], off
	s_mov_b32 m0, s78
	v_lshl_add_u64 v[242:243], s[34:35], 0, v[148:149]
	global_load_lds_dwordx4 v[242:243], off
	s_waitcnt vmcnt(8)
	s_waitcnt lgkmcnt(0)
	s_barrier
	s_setprio 1
	s_waitcnt lgkmcnt(0)
	v_mfma_f32_16x16x32_bf16 v[124:127], v[128:131], v[200:203], v[124:127]
	v_mfma_f32_16x16x32_bf16 v[120:123], v[136:139], v[200:203], v[120:123]
	v_mfma_f32_16x16x32_bf16 v[108:111], v[128:131], v[214:217], v[108:111]
	v_mfma_f32_16x16x32_bf16 v[104:107], v[136:139], v[214:217], v[104:107]
	v_mfma_f32_16x16x32_bf16 v[92:95], v[128:131], v[222:225], v[92:95]
	v_mfma_f32_16x16x32_bf16 v[88:91], v[136:139], v[222:225], v[88:91]
	v_mfma_f32_16x16x32_bf16 v[76:79], v[128:131], v[230:233], v[76:79]
	v_mfma_f32_16x16x32_bf16 v[72:75], v[136:139], v[230:233], v[72:75]
	v_mfma_f32_16x16x32_bf16 v[124:127], v[132:135], v[208:211], v[124:127]
	v_mfma_f32_16x16x32_bf16 v[120:123], v[140:143], v[208:211], v[120:123]
	v_mfma_f32_16x16x32_bf16 v[108:111], v[132:135], v[218:221], v[108:111]
	v_mfma_f32_16x16x32_bf16 v[104:107], v[140:143], v[218:221], v[104:107]
	v_mfma_f32_16x16x32_bf16 v[92:95], v[132:135], v[226:229], v[92:95]
	v_mfma_f32_16x16x32_bf16 v[88:91], v[140:143], v[226:229], v[88:91]
	v_mfma_f32_16x16x32_bf16 v[76:79], v[132:135], v[234:237], v[76:79]
	v_mfma_f32_16x16x32_bf16 v[72:75], v[140:143], v[234:237], v[72:75]
	s_setprio 0
	s_setprio 1
	v_mfma_f32_16x16x32_bf16 v[116:119], v[168:171], v[200:203], v[116:119]
	v_mfma_f32_16x16x32_bf16 v[112:115], v[192:195], v[200:203], v[112:115]
	v_mfma_f32_16x16x32_bf16 v[100:103], v[168:171], v[214:217], v[100:103]
	v_mfma_f32_16x16x32_bf16 v[96:99], v[192:195], v[214:217], v[96:99]
	v_mfma_f32_16x16x32_bf16 v[84:87], v[168:171], v[222:225], v[84:87]
	v_mfma_f32_16x16x32_bf16 v[80:83], v[192:195], v[222:225], v[80:83]
	v_mfma_f32_16x16x32_bf16 v[68:71], v[168:171], v[230:233], v[68:71]
	v_mfma_f32_16x16x32_bf16 v[64:67], v[192:195], v[230:233], v[64:67]
	v_mfma_f32_16x16x32_bf16 v[116:119], v[188:191], v[208:211], v[116:119]
	v_mfma_f32_16x16x32_bf16 v[112:115], v[196:199], v[208:211], v[112:115]
	v_mfma_f32_16x16x32_bf16 v[100:103], v[188:191], v[218:221], v[100:103]
	v_mfma_f32_16x16x32_bf16 v[96:99], v[196:199], v[218:221], v[96:99]
	v_mfma_f32_16x16x32_bf16 v[84:87], v[188:191], v[226:229], v[84:87]
	v_mfma_f32_16x16x32_bf16 v[80:83], v[196:199], v[226:229], v[80:83]
	v_mfma_f32_16x16x32_bf16 v[68:71], v[188:191], v[234:237], v[68:71]
	v_mfma_f32_16x16x32_bf16 v[64:67], v[196:199], v[234:237], v[64:67]
	s_setprio 0
	s_barrier
	s_add_i32 s16, s16, s74
	v_lshl_add_u64 v[172:173], v[172:173], 0, s[42:43]
	s_mov_b32 m0, s16
	ds_read_b128 v[200:203], v184 offset:49152
	ds_read_b128 v[208:211], v184 offset:50176
	ds_read_b128 v[214:217], v184 offset:51200
	ds_read_b128 v[218:221], v184 offset:52224
	ds_read_b128 v[222:225], v184 offset:53248
	ds_read_b128 v[226:229], v184 offset:54272
	ds_read_b128 v[230:233], v184 offset:55296
	ds_read_b128 v[234:237], v184 offset:56320
	global_load_lds_dwordx4 v[172:173], off
	s_add_i32 m0, s16, 0x2000
	s_add_u32 s34, s68, 0x40080
	v_lshl_add_u64 v[172:173], v[204:205], 0, s[42:43]
	s_addc_u32 s35, s69, 0
	s_add_i32 s16, s17, s74
	global_load_lds_dwordx4 v[172:173], off
	s_mov_b32 m0, s16
	v_lshl_add_u64 v[172:173], s[34:35], 0, v[146:147]
	global_load_lds_dwordx4 v[172:173], off
	s_add_i32 m0, s16, 0x2000
	v_lshl_add_u64 v[172:173], s[34:35], 0, v[150:151]
	global_load_lds_dwordx4 v[172:173], off
	s_mov_b32 m0, s83
	v_lshl_add_u64 v[172:173], v[238:239], 0, s[42:43]
	global_load_lds_dwordx4 v[172:173], off
	v_lshl_add_u64 v[172:173], v[240:241], 0, s[42:43]
	s_nop 0
	s_cmp_lg_u32 s67, 12
	s_cbranch_scc1 .Ldf_skipD_2
	s_mov_b32 m0, s84
	s_nop 0
	global_load_lds_dwordx4 v[172:173], off

; __device__ __forceinline__ int wq_next(unsigned* cnt, int lane) { unsigned v = 0u; if (lane == 0) v = atomicAdd(cnt, 1u); return (int)__builtin_amdgcn_readfirstlane(v); }
; #define KIN(i) KPTR(const float, i)
; template <int L> __device__ __forceinline__ void layer_fwd(cg::grid_group& grid, LAS unsigned char* lds) {
;     ...
;         unsigned* cnt_sg = (unsigned*)(ws + CTL_CNT) + 64 * (2 * L + 1);
;         const bf16_t* VSTp = (const bf16_t*)(ws + WS_VST); const bf16_t* QUp = (const bf16_t*)(ws + WS_QU); bf16_t* OBp = (bf16_t*)(ws + WS_H); const float* stp = (const float*)(ws + STL); const bf16_t* wsb = (const bf16_t*)(ws + WL + W_S);
;         for (int u = gw; u < 2048; u += NGW) sg_unit<4>(u >> 3, (u >> 1) & 3, (u & 1) * 64, VSTp, QUp, OBp, stp, KIN(12) + L * 512, KIN(13) + L * 512, wsb, KIN(15) + L * 512, lane);
;         if (L == 0)
;             for (;;) { const int u = wq_next(cnt_sg, lane); if (u >= 64) break; sg_unit<2>(256 + (u >> 4), (u >> 2) & 3, (u & 3) * 32, VSTp, QUp, OBp, stp, KIN(12) + L * 512, KIN(13) + L * 512, wsb, KIN(15) + L * 512, lane); }
.LBB0_964:
	v_readfirstlane_b32 s100, v206
	s_nop 0
	s_cmp_eq_u32 s100, 64
	s_cselect_b32 s100, s2, 64
	s_min_u32 s100, s100, 64
	v_mbcnt_hi_u32_b32 v202, -1, v212
	s_add_u32 s40, s40, 0xc2100
	v_and_b32_e32 v205, 64, v202
	s_addc_u32 s41, s41, 0
	s_mov_b32 s43, 0
	v_cmp_eq_u32_e64 s[4:5], 0, v161
	v_mov_b32_e32 v113, 0
	s_mov_b32 s51, 0x8000
	s_mov_b64 s[44:45], 0x8000
	s_mov_b64 s[46:47], 0x10000
	s_mov_b32 s55, 0x10000
	s_mov_b64 s[48:49], 0x18000
	s_mov_b32 s56, 0x18000
	s_mov_b32 s50, 0x3b000000
	s_mov_b32 s57, 0xf800000
	v_mov_b32_e32 v125, 0x260
	s_movk_i32 s58, 0x1000
	s_movk_i32 s59, 0x2000
	v_mov_b32_e32 v114, 0x3b000000
	v_xor_b32_e32 v204, 16, v202
	v_add_u32_e32 v203, 64, v205
	s_branch .LBB0_967

; __device__ __forceinline__ void prologue(const kptr_t kp, LAS float* scr, int gw, int NGW, int lane) {
;     ...
;     for (int it = gw; it < IT_TOTAL; it += NGW) {
;         int r = it;
;         if (r < IT_ADA) {
;             const int l = r / 576, rem = r % 576, cgp = rem / 16, ks = rem % 16, j0 = cgp * 256 + 4 * lane;
.Lslot_3_ret:
	s_cmp_eq_u32 s100, 0x4b80
	s_cbranch_scc0 .Lslot_3_done
	s_mov_b32 s98, 0x1c0
	s_mov_b32 s100, 0x480
	s_branch .Lcv_hop2

; #define PG8_STAGE(bufoff, gbase, voff) do { _Pragma("unroll") for (int _i = 0; _i < 2; ++_i) \
;         __builtin_amdgcn_global_load_lds((const unsigned*)((const char*)(gbase) + (voff)[_i]), (PG8_LAS unsigned*)(lds + (bufoff) + ldsw + _i * 8192), 16, 0, 0); } while (0)
; #define PG8_LDA(dst, b, h) do { _Pragma("unroll") for (int m = 0; m < 4; ++m) _Pragma("unroll") for (int k = 0; k < 2; ++k) dst[m][k] = *(const PG8_LAS bf16x8*)(lds + PG8_SA(b, h) + aoff + m * 2048 + k * 1024); } while (0)
; #define PG8_LDB(dst, b, h) do { _Pragma("unroll") for (int n = 0; n < 2; ++n) _Pragma("unroll") for (int k = 0; k < 2; ++k) dst[n][k] = *(const PG8_LAS bf16x8*)(lds + PG8_SB(b, h) + boff + n * 2048 + k * 1024); } while (0)
; #define PG8_WAIT_V(n) asm volatile("s_waitcnt vmcnt(" #n ")" ::: "memory")
; #define PG8_WAIT_L(n) asm volatile("s_waitcnt lgkmcnt(" #n ")" ::: "memory")
; #define PG8_BAR __builtin_amdgcn_s_barrier()
; #define PG8_SCHED __builtin_amdgcn_sched_barrier(0)
; #define PG8_MMA2(ai) PG8_MMA(ai, 0, At, B0)
;     ...
;         for (int t = 0; t < nt; t += 2) {
;             const bool last = (t == nt - 2);
;             const char* a1 = cA + (size_t)(t + 1) * kstep;
;             const char* a2 = last ? nA : cA + (size_t)(t + 2) * kstep; const char* b2 = last ? nB : cB + (size_t)(t + 2) * kstep;
;             const char* a3 = a2 + kstep; const char* b3 = b2 + kstep;
;             if (last && has_next) S.a_ready(nxt);
;             if constexpr (SP2) {
;             PG8_LDB(B0, 0, 0); PG8_LDB(B1, 0, 1); PG8_SCHED; PG8_LDA(At, 0, 0); PG8_STAGE(PG8_SA(1, 1), a1 + hstep, voffA);
;             PG8_WAIT_V(8); PG8_WAIT_L(0); PG8_BAR; PG8_MMA2(0); PG8_BAR; PG8_SCHED;
;             PG8_LDA(At, 0, 1); PG8_STAGE(PG8_SB(0, 0), b2, voffB); PG8_STAGE(PG8_SB(0, 1), b2 + hstep, voffB); PG8_STAGE(PG8_SA(0, 0), a2, voffA);
;             PG8_WAIT_V(8); PG8_WAIT_L(0); PG8_BAR; PG8_MMA2(1); PG8_BAR; PG8_SCHED;
;             PG8_LDB(B0, 1, 0); PG8_LDB(B1, 1, 1); PG8_SCHED; PG8_LDA(At, 1, 0); PG8_STAGE(PG8_SA(0, 1), a2 + hstep, voffA);
;             PG8_WAIT_V(8); PG8_WAIT_L(0); PG8_BAR; PG8_MMA2(0); PG8_BAR; PG8_SCHED;
;             PG8_LDA(At, 1, 1); PG8_STAGE(PG8_SB(1, 0), b3, voffB); PG8_STAGE(PG8_SB(1, 1), b3 + hstep, voffB); PG8_STAGE(PG8_SA(1, 0), a3, voffA);
;             PG8_WAIT_V(8); PG8_WAIT_L(0); PG8_BAR; PG8_MMA2(1); PG8_BAR; PG8_SCHED;
.Ldf_skipA_3:
	ds_read_b128 v[128:131], v161
	ds_read_b128 v[132:135], v161 offset:1024
	ds_read_b128 v[136:139], v161 offset:2048
	ds_read_b128 v[140:143], v161 offset:3072
	ds_read_b128 v[164:167], v162
	ds_read_b128 v[168:171], v162 offset:1024
	ds_read_b128 v[172:175], v162 offset:2048
	ds_read_b128 v[176:179], v162 offset:3072
	s_add_u32 s44, s42, 0x100
	s_addc_u32 s45, s43, 0
	s_cmp_eq_u32 s71, 12
	s_cselect_b32 s49, s7, s45
	s_cselect_b32 s48, s8, s44
	s_cselect_b32 s47, s9, s70
	s_cselect_b32 s46, s23, s27
	v_lshl_add_u64 v[156:157], s[42:43], 0, v[150:151]
	s_add_i32 m0, s41, 0xc000
	ds_read_b128 v[180:183], v163
	ds_read_b128 v[184:187], v163 offset:1024
	ds_read_b128 v[188:191], v163 offset:2048
	ds_read_b128 v[192:195], v163 offset:3072
	ds_read_b128 v[196:199], v163 offset:4096
	ds_read_b128 v[212:215], v163 offset:5120
	ds_read_b128 v[216:219], v163 offset:6144
	ds_read_b128 v[220:223], v163 offset:7168
	global_load_lds_dwordx4 v[156:157], off
	s_add_i32 m0, s41, 0xe000
	v_lshl_add_u64 v[156:157], s[42:43], 0, v[148:149]
	global_load_lds_dwordx4 v[156:157], off
	s_waitcnt vmcnt(8)
	s_waitcnt lgkmcnt(0)
	s_barrier
	s_setprio 1
	s_waitcnt lgkmcnt(0)
	v_mfma_f32_16x16x32_bf16 v[124:127], v[128:131], v[180:183], v[124:127]
	v_mfma_f32_16x16x32_bf16 v[120:123], v[136:139], v[180:183], v[120:123]
	v_mfma_f32_16x16x32_bf16 v[108:111], v[128:131], v[188:191], v[108:111]
	v_mfma_f32_16x16x32_bf16 v[104:107], v[136:139], v[188:191], v[104:107]
	v_mfma_f32_16x16x32_bf16 v[92:95], v[128:131], v[196:199], v[92:95]
	v_mfma_f32_16x16x32_bf16 v[88:91], v[136:139], v[196:199], v[88:91]
	v_mfma_f32_16x16x32_bf16 v[76:79], v[128:131], v[216:219], v[76:79]
	v_mfma_f32_16x16x32_bf16 v[72:75], v[136:139], v[216:219], v[72:75]
	v_mfma_f32_16x16x32_bf16 v[124:127], v[132:135], v[184:187], v[124:127]
	v_mfma_f32_16x16x32_bf16 v[120:123], v[140:143], v[184:187], v[120:123]
	v_mfma_f32_16x16x32_bf16 v[108:111], v[132:135], v[192:195], v[108:111]
	v_mfma_f32_16x16x32_bf16 v[104:107], v[140:143], v[192:195], v[104:107]
	v_mfma_f32_16x16x32_bf16 v[92:95], v[132:135], v[212:215], v[92:95]
	v_mfma_f32_16x16x32_bf16 v[88:91], v[140:143], v[212:215], v[88:91]
	v_mfma_f32_16x16x32_bf16 v[76:79], v[132:135], v[220:223], v[76:79]
	v_mfma_f32_16x16x32_bf16 v[72:75], v[140:143], v[220:223], v[72:75]
	s_setprio 0
	s_setprio 1
	v_mfma_f32_16x16x32_bf16 v[116:119], v[164:167], v[180:183], v[116:119]
	v_mfma_f32_16x16x32_bf16 v[112:115], v[172:175], v[180:183], v[112:115]
	v_mfma_f32_16x16x32_bf16 v[100:103], v[164:167], v[188:191], v[100:103]
	v_mfma_f32_16x16x32_bf16 v[96:99], v[172:175], v[188:191], v[96:99]
	v_mfma_f32_16x16x32_bf16 v[84:87], v[164:167], v[196:199], v[84:87]
	v_mfma_f32_16x16x32_bf16 v[80:83], v[172:175], v[196:199], v[80:83]
	v_mfma_f32_16x16x32_bf16 v[68:71], v[164:167], v[216:219], v[68:71]
	v_mfma_f32_16x16x32_bf16 v[64:67], v[172:175], v[216:219], v[64:67]
	v_mfma_f32_16x16x32_bf16 v[116:119], v[168:171], v[184:187], v[116:119]
	v_mfma_f32_16x16x32_bf16 v[112:115], v[176:179], v[184:187], v[112:115]
	v_mfma_f32_16x16x32_bf16 v[100:103], v[168:171], v[192:195], v[100:103]
	v_mfma_f32_16x16x32_bf16 v[96:99], v[176:179], v[192:195], v[96:99]
	v_mfma_f32_16x16x32_bf16 v[84:87], v[168:171], v[212:215], v[84:87]
	v_mfma_f32_16x16x32_bf16 v[80:83], v[176:179], v[212:215], v[80:83]
	v_mfma_f32_16x16x32_bf16 v[68:71], v[168:171], v[220:223], v[68:71]
	v_mfma_f32_16x16x32_bf16 v[64:67], v[176:179], v[220:223], v[64:67]
	s_setprio 0
	s_barrier
	s_add_i32 s16, s3, s54
	v_lshl_add_u64 v[156:157], s[46:47], 0, v[144:145]
	s_mov_b32 m0, s16
	ds_read_b128 v[180:183], v163 offset:16384
	ds_read_b128 v[184:187], v163 offset:17408
	ds_read_b128 v[188:191], v163 offset:18432
	ds_read_b128 v[192:195], v163 offset:19456
	ds_read_b128 v[196:199], v163 offset:20480
	ds_read_b128 v[212:215], v163 offset:21504
	ds_read_b128 v[216:219], v163 offset:22528
	ds_read_b128 v[220:223], v163 offset:23552
	global_load_lds_dwordx4 v[156:157], off
	s_add_i32 m0, s16, 0x2000
	s_add_u32 s16, s46, 0x40000
	v_lshl_add_u64 v[224:225], s[46:47], 0, v[146:147]
	s_addc_u32 s17, s47, 0
	s_add_i32 s34, s68, s54
	global_load_lds_dwordx4 v[224:225], off
	v_lshl_add_u64 v[226:227], s[16:17], 0, v[144:145]
	s_mov_b32 m0, s34
	v_lshl_add_u64 v[228:229], s[48:49], 0, v[146:147]
	global_load_lds_dwordx4 v[226:227], off
	s_add_i32 m0, s34, 0x2000
	v_lshl_add_u64 v[226:227], s[16:17], 0, v[146:147]
	global_load_lds_dwordx4 v[226:227], off
	s_mov_b32 m0, s41
	v_lshl_add_u64 v[226:227], s[48:49], 0, v[144:145]
	global_load_lds_dwordx4 v[226:227], off
	s_nop 0
	s_waitcnt vmcnt(7)
	s_waitcnt lgkmcnt(0)
	s_barrier
; #define PG8_STAGE(bufoff, gbase, voff) do { _Pragma("unroll") for (int _i = 0; _i < 2; ++_i) \
;         __builtin_amdgcn_global_load_lds((const unsigned*)((const char*)(gbase) + (voff)[_i]), (PG8_LAS unsigned*)(lds + (bufoff) + ldsw + _i * 8192), 16, 0, 0); } while (0)
; #define PG8_LDA(dst, b, h) do { _Pragma("unroll") for (int m = 0; m < 4; ++m) _Pragma("unroll") for (int k = 0; k < 2; ++k) dst[m][k] = *(const PG8_LAS bf16x8*)(lds + PG8_SA(b, h) + aoff + m * 2048 + k * 1024); } while (0)
; #define PG8_LDB(dst, b, h) do { _Pragma("unroll") for (int n = 0; n < 2; ++n) _Pragma("unroll") for (int k = 0; k < 2; ++k) dst[n][k] = *(const PG8_LAS bf16x8*)(lds + PG8_SB(b, h) + boff + n * 2048 + k * 1024); } while (0)
; #define PG8_WAIT_V(n) asm volatile("s_waitcnt vmcnt(" #n ")" ::: "memory")
; #define PG8_WAIT_L(n) asm volatile("s_waitcnt lgkmcnt(" #n ")" ::: "memory")
; #define PG8_BAR __builtin_amdgcn_s_barrier()
; #define PG8_SCHED __builtin_amdgcn_sched_barrier(0)
; #define PG8_MMA2(ai) PG8_MMA(ai, 0, At, B0)
;     ...
;         for (int t = 0; t < nt; t += 2) {
;             const bool last = (t == nt - 2);
;             const char* a1 = cA + (size_t)(t + 1) * kstep;
;             const char* a2 = last ? nA : cA + (size_t)(t + 2) * kstep; const char* b2 = last ? nB : cB + (size_t)(t + 2) * kstep;
;             const char* a3 = a2 + kstep; const char* b3 = b2 + kstep;
;             if (last && has_next) S.a_ready(nxt);
;             if constexpr (SP2) {
;             PG8_LDB(B0, 0, 0); PG8_LDB(B1, 0, 1); PG8_SCHED; PG8_LDA(At, 0, 0); PG8_STAGE(PG8_SA(1, 1), a1 + hstep, voffA);
;             PG8_WAIT_V(8); PG8_WAIT_L(0); PG8_BAR; PG8_MMA2(0); PG8_BAR; PG8_SCHED;
;             PG8_LDA(At, 0, 1); PG8_STAGE(PG8_SB(0, 0), b2, voffB); PG8_STAGE(PG8_SB(0, 1), b2 + hstep, voffB); PG8_STAGE(PG8_SA(0, 0), a2, voffA);
;             PG8_WAIT_V(8); PG8_WAIT_L(0); PG8_BAR; PG8_MMA2(1); PG8_BAR; PG8_SCHED;
;             PG8_LDB(B0, 1, 0); PG8_LDB(B1, 1, 1); PG8_SCHED; PG8_LDA(At, 1, 0); PG8_STAGE(PG8_SA(0, 1), a2 + hstep, voffA);
;             PG8_WAIT_V(8); PG8_WAIT_L(0); PG8_BAR; PG8_MMA2(0); PG8_BAR; PG8_SCHED;
;             PG8_LDA(At, 1, 1); PG8_STAGE(PG8_SB(1, 0), b3, voffB); PG8_STAGE(PG8_SB(1, 1), b3 + hstep, voffB); PG8_STAGE(PG8_SA(1, 0), a3, voffA);
;             PG8_WAIT_V(8); PG8_WAIT_L(0); PG8_BAR; PG8_MMA2(1); PG8_BAR; PG8_SCHED;
	s_setprio 1
	s_waitcnt lgkmcnt(0)
	v_mfma_f32_16x16x32_bf16 v[60:63], v[128:131], v[180:183], v[60:63]
	v_mfma_f32_16x16x32_bf16 v[56:59], v[136:139], v[180:183], v[56:59]
	v_mfma_f32_16x16x32_bf16 v[44:47], v[128:131], v[188:191], v[44:47]
	v_mfma_f32_16x16x32_bf16 v[40:43], v[136:139], v[188:191], v[40:43]
	v_mfma_f32_16x16x32_bf16 v[28:31], v[128:131], v[196:199], v[28:31]
	v_mfma_f32_16x16x32_bf16 v[24:27], v[136:139], v[196:199], v[24:27]
	v_mfma_f32_16x16x32_bf16 v[12:15], v[128:131], v[216:219], v[12:15]
	v_mfma_f32_16x16x32_bf16 v[8:11], v[136:139], v[216:219], v[8:11]
	v_mfma_f32_16x16x32_bf16 v[60:63], v[132:135], v[184:187], v[60:63]
	v_mfma_f32_16x16x32_bf16 v[56:59], v[140:143], v[184:187], v[56:59]
	v_mfma_f32_16x16x32_bf16 v[44:47], v[132:135], v[192:195], v[44:47]
	v_mfma_f32_16x16x32_bf16 v[40:43], v[140:143], v[192:195], v[40:43]
	v_mfma_f32_16x16x32_bf16 v[28:31], v[132:135], v[212:215], v[28:31]
	v_mfma_f32_16x16x32_bf16 v[24:27], v[140:143], v[212:215], v[24:27]
	v_mfma_f32_16x16x32_bf16 v[12:15], v[132:135], v[220:223], v[12:15]
	v_mfma_f32_16x16x32_bf16 v[8:11], v[140:143], v[220:223], v[8:11]
	s_setprio 0
	s_setprio 1
	v_mfma_f32_16x16x32_bf16 v[52:55], v[164:167], v[180:183], v[52:55]
	v_mfma_f32_16x16x32_bf16 v[48:51], v[172:175], v[180:183], v[48:51]
	v_mfma_f32_16x16x32_bf16 v[36:39], v[164:167], v[188:191], v[36:39]
	v_mfma_f32_16x16x32_bf16 v[32:35], v[172:175], v[188:191], v[32:35]
	v_mfma_f32_16x16x32_bf16 v[20:23], v[164:167], v[196:199], v[20:23]
	v_mfma_f32_16x16x32_bf16 v[16:19], v[172:175], v[196:199], v[16:19]
	v_mfma_f32_16x16x32_bf16 v[4:7], v[164:167], v[216:219], v[4:7]
	v_mfma_f32_16x16x32_bf16 v[0:3], v[172:175], v[216:219], v[0:3]
	v_mfma_f32_16x16x32_bf16 v[52:55], v[168:171], v[184:187], v[52:55]
	v_mfma_f32_16x16x32_bf16 v[48:51], v[176:179], v[184:187], v[48:51]
	v_mfma_f32_16x16x32_bf16 v[36:39], v[168:171], v[192:195], v[36:39]
	v_mfma_f32_16x16x32_bf16 v[32:35], v[176:179], v[192:195], v[32:35]
	v_mfma_f32_16x16x32_bf16 v[20:23], v[168:171], v[212:215], v[20:23]
	v_mfma_f32_16x16x32_bf16 v[16:19], v[176:179], v[212:215], v[16:19]
	v_mfma_f32_16x16x32_bf16 v[4:7], v[168:171], v[220:223], v[4:7]
	v_mfma_f32_16x16x32_bf16 v[0:3], v[176:179], v[220:223], v[0:3]
	s_setprio 0
	s_barrier
	s_add_i32 s34, 0, 0x18000
	s_add_i32 s35, 0, 0x1c000
	v_add_u32_e32 v140, s34, v159
	v_add_u32_e32 v176, s35, v159
	ds_read_b128 v[128:131], v140
	ds_read_b128 v[132:135], v140 offset:1024
	ds_read_b128 v[136:139], v140 offset:2048
	ds_read_b128 v[140:143], v140 offset:3072
	ds_read_b128 v[164:167], v176
	ds_read_b128 v[168:171], v176 offset:1024
	ds_read_b128 v[172:175], v176 offset:2048
	ds_read_b128 v[176:179], v176 offset:3072
	s_add_u32 s16, s48, 0x40000
	s_addc_u32 s17, s49, 0
	s_mov_b32 m0, s55
	s_nop 0
	global_load_lds_dwordx4 v[228:229], off
	s_mov_b32 m0, s56
	v_lshl_add_u64 v[230:231], s[16:17], 0, v[144:145]
	ds_read_b128 v[180:183], v163 offset:32768
	ds_read_b128 v[184:187], v163 offset:33792
	ds_read_b128 v[188:191], v163 offset:34816
	ds_read_b128 v[192:195], v163 offset:35840
	ds_read_b128 v[196:199], v163 offset:36864
	ds_read_b128 v[212:215], v163 offset:37888
	ds_read_b128 v[216:219], v163 offset:38912
	ds_read_b128 v[220:223], v163 offset:39936
	global_load_lds_dwordx4 v[230:231], off
	s_mov_b32 m0, s57
	v_lshl_add_u64 v[230:231], s[16:17], 0, v[146:147]
	global_load_lds_dwordx4 v[230:231], off
	s_waitcnt vmcnt(8)
	s_waitcnt lgkmcnt(0)
	s_barrier
	s_setprio 1
	s_waitcnt lgkmcnt(0)
	v_mfma_f32_16x16x32_bf16 v[124:127], v[128:131], v[180:183], v[124:127]
	v_mfma_f32_16x16x32_bf16 v[120:123], v[136:139], v[180:183], v[120:123]
	v_mfma_f32_16x16x32_bf16 v[108:111], v[128:131], v[188:191], v[108:111]
	v_mfma_f32_16x16x32_bf16 v[104:107], v[136:139], v[188:191], v[104:107]
	v_mfma_f32_16x16x32_bf16 v[92:95], v[128:131], v[196:199], v[92:95]
	v_mfma_f32_16x16x32_bf16 v[88:91], v[136:139], v[196:199], v[88:91]
	v_mfma_f32_16x16x32_bf16 v[76:79], v[128:131], v[216:219], v[76:79]
	v_mfma_f32_16x16x32_bf16 v[72:75], v[136:139], v[216:219], v[72:75]
	v_mfma_f32_16x16x32_bf16 v[124:127], v[132:135], v[184:187], v[124:127]
	v_mfma_f32_16x16x32_bf16 v[120:123], v[140:143], v[184:187], v[120:123]
	v_mfma_f32_16x16x32_bf16 v[108:111], v[132:135], v[192:195], v[108:111]
	v_mfma_f32_16x16x32_bf16 v[104:107], v[140:143], v[192:195], v[104:107]
	v_mfma_f32_16x16x32_bf16 v[92:95], v[132:135], v[212:215], v[92:95]
	v_mfma_f32_16x16x32_bf16 v[88:91], v[140:143], v[212:215], v[88:91]
	v_mfma_f32_16x16x32_bf16 v[76:79], v[132:135], v[220:223], v[76:79]
	v_mfma_f32_16x16x32_bf16 v[72:75], v[140:143], v[220:223], v[72:75]
	s_setprio 0
	s_setprio 1
	v_mfma_f32_16x16x32_bf16 v[116:119], v[164:167], v[180:183], v[116:119]
	v_mfma_f32_16x16x32_bf16 v[112:115], v[172:175], v[180:183], v[112:115]
	v_mfma_f32_16x16x32_bf16 v[100:103], v[164:167], v[188:191], v[100:103]
	v_mfma_f32_16x16x32_bf16 v[96:99], v[172:175], v[188:191], v[96:99]
	v_mfma_f32_16x16x32_bf16 v[84:87], v[164:167], v[196:199], v[84:87]
	v_mfma_f32_16x16x32_bf16 v[80:83], v[172:175], v[196:199], v[80:83]
	v_mfma_f32_16x16x32_bf16 v[68:71], v[164:167], v[216:219], v[68:71]
	v_mfma_f32_16x16x32_bf16 v[64:67], v[172:175], v[216:219], v[64:67]
	v_mfma_f32_16x16x32_bf16 v[116:119], v[168:171], v[184:187], v[116:119]
	v_mfma_f32_16x16x32_bf16 v[112:115], v[176:179], v[184:187], v[112:115]
	v_mfma_f32_16x16x32_bf16 v[100:103], v[168:171], v[192:195], v[100:103]
	v_mfma_f32_16x16x32_bf16 v[96:99], v[176:179], v[192:195], v[96:99]
	v_mfma_f32_16x16x32_bf16 v[84:87], v[168:171], v[212:215], v[84:87]
	v_mfma_f32_16x16x32_bf16 v[80:83], v[176:179], v[212:215], v[80:83]
	v_mfma_f32_16x16x32_bf16 v[68:71], v[168:171], v[220:223], v[68:71]
	v_mfma_f32_16x16x32_bf16 v[64:67], v[176:179], v[220:223], v[64:67]
	s_setprio 0
	s_barrier
	s_add_i32 s16, s34, s54
	v_lshl_add_u64 v[156:157], v[156:157], 0, s[18:19]
	s_mov_b32 m0, s16
	ds_read_b128 v[180:183], v163 offset:49152
	ds_read_b128 v[184:187], v163 offset:50176
	ds_read_b128 v[188:191], v163 offset:51200
	ds_read_b128 v[192:195], v163 offset:52224
	ds_read_b128 v[196:199], v163 offset:53248
	ds_read_b128 v[212:215], v163 offset:54272
	ds_read_b128 v[216:219], v163 offset:55296
	ds_read_b128 v[220:223], v163 offset:56320
	global_load_lds_dwordx4 v[156:157], off
	s_add_i32 m0, s16, 0x2000
	s_add_u32 s16, s46, 0x40080
	v_lshl_add_u64 v[156:157], v[224:225], 0, s[18:19]
	s_addc_u32 s17, s47, 0
	s_add_i32 s34, s35, s54
	global_load_lds_dwordx4 v[156:157], off
	s_mov_b32 m0, s34
	v_lshl_add_u64 v[156:157], s[16:17], 0, v[144:145]
	global_load_lds_dwordx4 v[156:157], off
	s_add_i32 m0, s34, 0x2000
	v_lshl_add_u64 v[156:157], s[16:17], 0, v[146:147]
	global_load_lds_dwordx4 v[156:157], off
	s_mov_b32 m0, s63
	v_lshl_add_u64 v[156:157], v[226:227], 0, s[18:19]
	global_load_lds_dwordx4 v[156:157], off
	v_lshl_add_u64 v[156:157], v[228:229], 0, s[18:19]
	s_nop 0
	s_cmp_lg_u32 s71, 12
	s_cbranch_scc1 .Ldf_skipD_3
	s_mov_b32 m0, s64
	s_nop 0
	global_load_lds_dwordx4 v[156:157], off

; #define PG8_STAGE(bufoff, gbase, voff) do { _Pragma("unroll") for (int _i = 0; _i < 2; ++_i) \
;         __builtin_amdgcn_global_load_lds((const unsigned*)((const char*)(gbase) + (voff)[_i]), (PG8_LAS unsigned*)(lds + (bufoff) + ldsw + _i * 8192), 16, 0, 0); } while (0)
; #define PG8_LDA(dst, b, h) do { _Pragma("unroll") for (int m = 0; m < 4; ++m) _Pragma("unroll") for (int k = 0; k < 2; ++k) dst[m][k] = *(const PG8_LAS bf16x8*)(lds + PG8_SA(b, h) + aoff + m * 2048 + k * 1024); } while (0)
; #define PG8_LDB(dst, b, h) do { _Pragma("unroll") for (int n = 0; n < 2; ++n) _Pragma("unroll") for (int k = 0; k < 2; ++k) dst[n][k] = *(const PG8_LAS bf16x8*)(lds + PG8_SB(b, h) + boff + n * 2048 + k * 1024); } while (0)
; #define PG8_WAIT_V(n) asm volatile("s_waitcnt vmcnt(" #n ")" ::: "memory")
; #define PG8_WAIT_L(n) asm volatile("s_waitcnt lgkmcnt(" #n ")" ::: "memory")
; #define PG8_BAR __builtin_amdgcn_s_barrier()
; #define PG8_SCHED __builtin_amdgcn_sched_barrier(0)
; #define PG8_MMA2(ai) PG8_MMA(ai, 0, At, B0)
;     ...
;         for (int t = 0; t < nt; t += 2) {
;             const bool last = (t == nt - 2);
;             const char* a1 = cA + (size_t)(t + 1) * kstep;
;             const char* a2 = last ? nA : cA + (size_t)(t + 2) * kstep; const char* b2 = last ? nB : cB + (size_t)(t + 2) * kstep;
;             const char* a3 = a2 + kstep; const char* b3 = b2 + kstep;
;             if (last && has_next) S.a_ready(nxt);
;             if constexpr (SP2) {
;             PG8_LDB(B0, 0, 0); PG8_LDB(B1, 0, 1); PG8_SCHED; PG8_LDA(At, 0, 0); PG8_STAGE(PG8_SA(1, 1), a1 + hstep, voffA);
;             PG8_WAIT_V(8); PG8_WAIT_L(0); PG8_BAR; PG8_MMA2(0); PG8_BAR; PG8_SCHED;
;             PG8_LDA(At, 0, 1); PG8_STAGE(PG8_SB(0, 0), b2, voffB); PG8_STAGE(PG8_SB(0, 1), b2 + hstep, voffB); PG8_STAGE(PG8_SA(0, 0), a2, voffA);
;             PG8_WAIT_V(8); PG8_WAIT_L(0); PG8_BAR; PG8_MMA2(1); PG8_BAR; PG8_SCHED;
;             PG8_LDB(B0, 1, 0); PG8_LDB(B1, 1, 1); PG8_SCHED; PG8_LDA(At, 1, 0); PG8_STAGE(PG8_SA(0, 1), a2 + hstep, voffA);
;             PG8_WAIT_V(8); PG8_WAIT_L(0); PG8_BAR; PG8_MMA2(0); PG8_BAR; PG8_SCHED;
;             PG8_LDA(At, 1, 1); PG8_STAGE(PG8_SB(1, 0), b3, voffB); PG8_STAGE(PG8_SB(1, 1), b3 + hstep, voffB); PG8_STAGE(PG8_SA(1, 0), a3, voffA);
;             PG8_WAIT_V(8); PG8_WAIT_L(0); PG8_BAR; PG8_MMA2(1); PG8_BAR; PG8_SCHED;
.Ldf_skipA_4:
	ds_read_b128 v[152:155], v149
	ds_read_b128 v[156:159], v149 offset:1024
	ds_read_b128 v[160:163], v149 offset:2048
	ds_read_b128 v[164:167], v149 offset:3072
	ds_read_b128 v[168:171], v150
	ds_read_b128 v[172:175], v150 offset:1024
	ds_read_b128 v[176:179], v150 offset:2048
	ds_read_b128 v[180:183], v150 offset:3072
	s_add_u32 s34, s42, 0xfffc0080
	s_addc_u32 s35, s43, -1
	s_cmp_eq_u32 s64, 12
	s_cselect_b32 s47, s7, s35
	s_cselect_b32 s46, s8, s34
	s_cselect_b32 s45, s9, s63
	s_cselect_b32 s44, s23, s27
	v_lshl_add_u64 v[144:145], s[42:43], 0, v[138:139]
	s_add_i32 m0, s41, 0xc000
	ds_read_b128 v[184:187], v151
	ds_read_b128 v[188:191], v151 offset:1024
	ds_read_b128 v[192:195], v151 offset:2048
	ds_read_b128 v[196:199], v151 offset:3072
	ds_read_b128 v[212:215], v151 offset:4096
	ds_read_b128 v[216:219], v151 offset:5120
	ds_read_b128 v[220:223], v151 offset:6144
	ds_read_b128 v[224:227], v151 offset:7168
	global_load_lds_dwordx4 v[144:145], off
	s_add_i32 m0, s41, 0xe000
	v_lshl_add_u64 v[144:145], s[42:43], 0, v[136:137]
	global_load_lds_dwordx4 v[144:145], off
	s_waitcnt vmcnt(8)
	s_waitcnt lgkmcnt(0)
	s_barrier
	s_setprio 1
	s_waitcnt lgkmcnt(0)
	v_mfma_f32_16x16x32_bf16 v[124:127], v[152:155], v[184:187], v[124:127]
	v_mfma_f32_16x16x32_bf16 v[120:123], v[160:163], v[184:187], v[120:123]
	v_mfma_f32_16x16x32_bf16 v[108:111], v[152:155], v[192:195], v[108:111]
	v_mfma_f32_16x16x32_bf16 v[104:107], v[160:163], v[192:195], v[104:107]
	v_mfma_f32_16x16x32_bf16 v[92:95], v[152:155], v[212:215], v[92:95]
	v_mfma_f32_16x16x32_bf16 v[88:91], v[160:163], v[212:215], v[88:91]
	v_mfma_f32_16x16x32_bf16 v[76:79], v[152:155], v[220:223], v[76:79]
	v_mfma_f32_16x16x32_bf16 v[72:75], v[160:163], v[220:223], v[72:75]
	v_mfma_f32_16x16x32_bf16 v[124:127], v[156:159], v[188:191], v[124:127]
	v_mfma_f32_16x16x32_bf16 v[120:123], v[164:167], v[188:191], v[120:123]
	v_mfma_f32_16x16x32_bf16 v[108:111], v[156:159], v[196:199], v[108:111]
	v_mfma_f32_16x16x32_bf16 v[104:107], v[164:167], v[196:199], v[104:107]
	v_mfma_f32_16x16x32_bf16 v[92:95], v[156:159], v[216:219], v[92:95]
	v_mfma_f32_16x16x32_bf16 v[88:91], v[164:167], v[216:219], v[88:91]
	v_mfma_f32_16x16x32_bf16 v[76:79], v[156:159], v[224:227], v[76:79]
	v_mfma_f32_16x16x32_bf16 v[72:75], v[164:167], v[224:227], v[72:75]
	s_setprio 0
	s_setprio 1
	v_mfma_f32_16x16x32_bf16 v[116:119], v[168:171], v[184:187], v[116:119]
	v_mfma_f32_16x16x32_bf16 v[112:115], v[176:179], v[184:187], v[112:115]
	v_mfma_f32_16x16x32_bf16 v[100:103], v[168:171], v[192:195], v[100:103]
	v_mfma_f32_16x16x32_bf16 v[96:99], v[176:179], v[192:195], v[96:99]
	v_mfma_f32_16x16x32_bf16 v[84:87], v[168:171], v[212:215], v[84:87]
	v_mfma_f32_16x16x32_bf16 v[80:83], v[176:179], v[212:215], v[80:83]
	v_mfma_f32_16x16x32_bf16 v[68:71], v[168:171], v[220:223], v[68:71]
	v_mfma_f32_16x16x32_bf16 v[64:67], v[176:179], v[220:223], v[64:67]
	v_mfma_f32_16x16x32_bf16 v[116:119], v[172:175], v[188:191], v[116:119]
	v_mfma_f32_16x16x32_bf16 v[112:115], v[180:183], v[188:191], v[112:115]
	v_mfma_f32_16x16x32_bf16 v[100:103], v[172:175], v[196:199], v[100:103]
	v_mfma_f32_16x16x32_bf16 v[96:99], v[180:183], v[196:199], v[96:99]
	v_mfma_f32_16x16x32_bf16 v[84:87], v[172:175], v[216:219], v[84:87]
	v_mfma_f32_16x16x32_bf16 v[80:83], v[180:183], v[216:219], v[80:83]
	v_mfma_f32_16x16x32_bf16 v[68:71], v[172:175], v[224:227], v[68:71]
	v_mfma_f32_16x16x32_bf16 v[64:67], v[180:183], v[224:227], v[64:67]
	s_setprio 0
	s_barrier
	s_add_i32 s34, s3, s52
	v_lshl_add_u64 v[144:145], s[44:45], 0, v[130:131]
	s_mov_b32 m0, s34
	ds_read_b128 v[184:187], v151 offset:16384
	ds_read_b128 v[188:191], v151 offset:17408
	ds_read_b128 v[192:195], v151 offset:18432
	ds_read_b128 v[196:199], v151 offset:19456
	ds_read_b128 v[212:215], v151 offset:20480
	ds_read_b128 v[216:219], v151 offset:21504
	ds_read_b128 v[220:223], v151 offset:22528
	ds_read_b128 v[224:227], v151 offset:23552
	global_load_lds_dwordx4 v[144:145], off
	s_add_i32 m0, s34, 0x2000
	s_add_u32 s34, s44, 0x40000
	v_lshl_add_u64 v[228:229], s[44:45], 0, v[134:135]
	s_addc_u32 s35, s45, 0
	s_add_i32 s65, s61, s52
	global_load_lds_dwordx4 v[228:229], off
	v_lshl_add_u64 v[230:231], s[34:35], 0, v[130:131]
	s_mov_b32 m0, s65
	v_lshl_add_u64 v[232:233], s[46:47], 0, v[132:133]
	global_load_lds_dwordx4 v[230:231], off
	s_add_i32 m0, s65, 0x2000
	v_lshl_add_u64 v[230:231], s[34:35], 0, v[134:135]
	global_load_lds_dwordx4 v[230:231], off
	s_mov_b32 m0, s41
	v_lshl_add_u64 v[230:231], s[46:47], 0, v[128:129]
	global_load_lds_dwordx4 v[230:231], off
	s_nop 0
	s_waitcnt vmcnt(7)
	s_waitcnt lgkmcnt(0)
	s_barrier
; #define PG8_STAGE(bufoff, gbase, voff) do { _Pragma("unroll") for (int _i = 0; _i < 2; ++_i) \
;         __builtin_amdgcn_global_load_lds((const unsigned*)((const char*)(gbase) + (voff)[_i]), (PG8_LAS unsigned*)(lds + (bufoff) + ldsw + _i * 8192), 16, 0, 0); } while (0)
; #define PG8_LDA(dst, b, h) do { _Pragma("unroll") for (int m = 0; m < 4; ++m) _Pragma("unroll") for (int k = 0; k < 2; ++k) dst[m][k] = *(const PG8_LAS bf16x8*)(lds + PG8_SA(b, h) + aoff + m * 2048 + k * 1024); } while (0)
; #define PG8_LDB(dst, b, h) do { _Pragma("unroll") for (int n = 0; n < 2; ++n) _Pragma("unroll") for (int k = 0; k < 2; ++k) dst[n][k] = *(const PG8_LAS bf16x8*)(lds + PG8_SB(b, h) + boff + n * 2048 + k * 1024); } while (0)
; #define PG8_WAIT_V(n) asm volatile("s_waitcnt vmcnt(" #n ")" ::: "memory")
; #define PG8_WAIT_L(n) asm volatile("s_waitcnt lgkmcnt(" #n ")" ::: "memory")
; #define PG8_BAR __builtin_amdgcn_s_barrier()
; #define PG8_SCHED __builtin_amdgcn_sched_barrier(0)
; #define PG8_MMA2(ai) PG8_MMA(ai, 0, At, B0)
;     ...
;         for (int t = 0; t < nt; t += 2) {
;             const bool last = (t == nt - 2);
;             const char* a1 = cA + (size_t)(t + 1) * kstep;
;             const char* a2 = last ? nA : cA + (size_t)(t + 2) * kstep; const char* b2 = last ? nB : cB + (size_t)(t + 2) * kstep;
;             const char* a3 = a2 + kstep; const char* b3 = b2 + kstep;
;             if (last && has_next) S.a_ready(nxt);
;             if constexpr (SP2) {
;             PG8_LDB(B0, 0, 0); PG8_LDB(B1, 0, 1); PG8_SCHED; PG8_LDA(At, 0, 0); PG8_STAGE(PG8_SA(1, 1), a1 + hstep, voffA);
;             PG8_WAIT_V(8); PG8_WAIT_L(0); PG8_BAR; PG8_MMA2(0); PG8_BAR; PG8_SCHED;
;             PG8_LDA(At, 0, 1); PG8_STAGE(PG8_SB(0, 0), b2, voffB); PG8_STAGE(PG8_SB(0, 1), b2 + hstep, voffB); PG8_STAGE(PG8_SA(0, 0), a2, voffA);
;             PG8_WAIT_V(8); PG8_WAIT_L(0); PG8_BAR; PG8_MMA2(1); PG8_BAR; PG8_SCHED;
;             PG8_LDB(B0, 1, 0); PG8_LDB(B1, 1, 1); PG8_SCHED; PG8_LDA(At, 1, 0); PG8_STAGE(PG8_SA(0, 1), a2 + hstep, voffA);
;             PG8_WAIT_V(8); PG8_WAIT_L(0); PG8_BAR; PG8_MMA2(0); PG8_BAR; PG8_SCHED;
;             PG8_LDA(At, 1, 1); PG8_STAGE(PG8_SB(1, 0), b3, voffB); PG8_STAGE(PG8_SB(1, 1), b3 + hstep, voffB); PG8_STAGE(PG8_SA(1, 0), a3, voffA);
;             PG8_WAIT_V(8); PG8_WAIT_L(0); PG8_BAR; PG8_MMA2(1); PG8_BAR; PG8_SCHED;
	s_setprio 1
	s_waitcnt lgkmcnt(0)
	v_mfma_f32_16x16x32_bf16 v[60:63], v[152:155], v[184:187], v[60:63]
	v_mfma_f32_16x16x32_bf16 v[56:59], v[160:163], v[184:187], v[56:59]
	v_mfma_f32_16x16x32_bf16 v[44:47], v[152:155], v[192:195], v[44:47]
	v_mfma_f32_16x16x32_bf16 v[40:43], v[160:163], v[192:195], v[40:43]
	v_mfma_f32_16x16x32_bf16 v[28:31], v[152:155], v[212:215], v[28:31]
	v_mfma_f32_16x16x32_bf16 v[24:27], v[160:163], v[212:215], v[24:27]
	v_mfma_f32_16x16x32_bf16 v[12:15], v[152:155], v[220:223], v[12:15]
	v_mfma_f32_16x16x32_bf16 v[8:11], v[160:163], v[220:223], v[8:11]
	v_mfma_f32_16x16x32_bf16 v[60:63], v[156:159], v[188:191], v[60:63]
	v_mfma_f32_16x16x32_bf16 v[56:59], v[164:167], v[188:191], v[56:59]
	v_mfma_f32_16x16x32_bf16 v[44:47], v[156:159], v[196:199], v[44:47]
	v_mfma_f32_16x16x32_bf16 v[40:43], v[164:167], v[196:199], v[40:43]
	v_mfma_f32_16x16x32_bf16 v[28:31], v[156:159], v[216:219], v[28:31]
	v_mfma_f32_16x16x32_bf16 v[24:27], v[164:167], v[216:219], v[24:27]
	v_mfma_f32_16x16x32_bf16 v[12:15], v[156:159], v[224:227], v[12:15]
	v_mfma_f32_16x16x32_bf16 v[8:11], v[164:167], v[224:227], v[8:11]
	s_setprio 0
	s_setprio 1
	v_mfma_f32_16x16x32_bf16 v[52:55], v[168:171], v[184:187], v[52:55]
	v_mfma_f32_16x16x32_bf16 v[48:51], v[176:179], v[184:187], v[48:51]
	v_mfma_f32_16x16x32_bf16 v[36:39], v[168:171], v[192:195], v[36:39]
	v_mfma_f32_16x16x32_bf16 v[32:35], v[176:179], v[192:195], v[32:35]
	v_mfma_f32_16x16x32_bf16 v[20:23], v[168:171], v[212:215], v[20:23]
	v_mfma_f32_16x16x32_bf16 v[16:19], v[176:179], v[212:215], v[16:19]
	v_mfma_f32_16x16x32_bf16 v[4:7], v[168:171], v[220:223], v[4:7]
	v_mfma_f32_16x16x32_bf16 v[0:3], v[176:179], v[220:223], v[0:3]
	v_mfma_f32_16x16x32_bf16 v[52:55], v[172:175], v[188:191], v[52:55]
	v_mfma_f32_16x16x32_bf16 v[48:51], v[180:183], v[188:191], v[48:51]
	v_mfma_f32_16x16x32_bf16 v[36:39], v[172:175], v[196:199], v[36:39]
	v_mfma_f32_16x16x32_bf16 v[32:35], v[180:183], v[196:199], v[32:35]
	v_mfma_f32_16x16x32_bf16 v[20:23], v[172:175], v[216:219], v[20:23]
	v_mfma_f32_16x16x32_bf16 v[16:19], v[180:183], v[216:219], v[16:19]
	v_mfma_f32_16x16x32_bf16 v[4:7], v[172:175], v[224:227], v[4:7]
	v_mfma_f32_16x16x32_bf16 v[0:3], v[180:183], v[224:227], v[0:3]
	s_setprio 0
	s_barrier
	s_add_i32 s65, 0, 0x18000
	s_add_i32 s66, 0, 0x1c000
	v_add_u32_e32 v164, s65, v147
	v_add_u32_e32 v180, s66, v147
	ds_read_b128 v[152:155], v164
	ds_read_b128 v[156:159], v164 offset:1024
	ds_read_b128 v[160:163], v164 offset:2048
	ds_read_b128 v[164:167], v164 offset:3072
	ds_read_b128 v[168:171], v180
	ds_read_b128 v[172:175], v180 offset:1024
	ds_read_b128 v[176:179], v180 offset:2048
	ds_read_b128 v[180:183], v180 offset:3072
	s_add_u32 s34, s46, 0x40000
	s_addc_u32 s35, s47, 0
	s_mov_b32 m0, s53
	s_nop 0
	global_load_lds_dwordx4 v[232:233], off
	s_mov_b32 m0, s54
	v_lshl_add_u64 v[234:235], s[34:35], 0, v[128:129]
	ds_read_b128 v[184:187], v151 offset:32768
	ds_read_b128 v[188:191], v151 offset:33792
	ds_read_b128 v[192:195], v151 offset:34816
	ds_read_b128 v[196:199], v151 offset:35840
	ds_read_b128 v[212:215], v151 offset:36864
	ds_read_b128 v[216:219], v151 offset:37888
	ds_read_b128 v[220:223], v151 offset:38912
	ds_read_b128 v[224:227], v151 offset:39936
	global_load_lds_dwordx4 v[234:235], off
	s_mov_b32 m0, s55
	v_lshl_add_u64 v[234:235], s[34:35], 0, v[132:133]
	global_load_lds_dwordx4 v[234:235], off
	s_waitcnt vmcnt(8)
	s_waitcnt lgkmcnt(0)
	s_barrier
	s_setprio 1
	s_waitcnt lgkmcnt(0)
	v_mfma_f32_16x16x32_bf16 v[124:127], v[152:155], v[184:187], v[124:127]
	v_mfma_f32_16x16x32_bf16 v[120:123], v[160:163], v[184:187], v[120:123]
	v_mfma_f32_16x16x32_bf16 v[108:111], v[152:155], v[192:195], v[108:111]
	v_mfma_f32_16x16x32_bf16 v[104:107], v[160:163], v[192:195], v[104:107]
	v_mfma_f32_16x16x32_bf16 v[92:95], v[152:155], v[212:215], v[92:95]
	v_mfma_f32_16x16x32_bf16 v[88:91], v[160:163], v[212:215], v[88:91]
	v_mfma_f32_16x16x32_bf16 v[76:79], v[152:155], v[220:223], v[76:79]
	v_mfma_f32_16x16x32_bf16 v[72:75], v[160:163], v[220:223], v[72:75]
	v_mfma_f32_16x16x32_bf16 v[124:127], v[156:159], v[188:191], v[124:127]
	v_mfma_f32_16x16x32_bf16 v[120:123], v[164:167], v[188:191], v[120:123]
	v_mfma_f32_16x16x32_bf16 v[108:111], v[156:159], v[196:199], v[108:111]
	v_mfma_f32_16x16x32_bf16 v[104:107], v[164:167], v[196:199], v[104:107]
	v_mfma_f32_16x16x32_bf16 v[92:95], v[156:159], v[216:219], v[92:95]
	v_mfma_f32_16x16x32_bf16 v[88:91], v[164:167], v[216:219], v[88:91]
	v_mfma_f32_16x16x32_bf16 v[76:79], v[156:159], v[224:227], v[76:79]
	v_mfma_f32_16x16x32_bf16 v[72:75], v[164:167], v[224:227], v[72:75]
	s_setprio 0
	s_setprio 1
	v_mfma_f32_16x16x32_bf16 v[116:119], v[168:171], v[184:187], v[116:119]
	v_mfma_f32_16x16x32_bf16 v[112:115], v[176:179], v[184:187], v[112:115]
	v_mfma_f32_16x16x32_bf16 v[100:103], v[168:171], v[192:195], v[100:103]
	v_mfma_f32_16x16x32_bf16 v[96:99], v[176:179], v[192:195], v[96:99]
	v_mfma_f32_16x16x32_bf16 v[84:87], v[168:171], v[212:215], v[84:87]
	v_mfma_f32_16x16x32_bf16 v[80:83], v[176:179], v[212:215], v[80:83]
	v_mfma_f32_16x16x32_bf16 v[68:71], v[168:171], v[220:223], v[68:71]
	v_mfma_f32_16x16x32_bf16 v[64:67], v[176:179], v[220:223], v[64:67]
	v_mfma_f32_16x16x32_bf16 v[116:119], v[172:175], v[188:191], v[116:119]
	v_mfma_f32_16x16x32_bf16 v[112:115], v[180:183], v[188:191], v[112:115]
	v_mfma_f32_16x16x32_bf16 v[100:103], v[172:175], v[196:199], v[100:103]
	v_mfma_f32_16x16x32_bf16 v[96:99], v[180:183], v[196:199], v[96:99]
	v_mfma_f32_16x16x32_bf16 v[84:87], v[172:175], v[216:219], v[84:87]
	v_mfma_f32_16x16x32_bf16 v[80:83], v[180:183], v[216:219], v[80:83]
	v_mfma_f32_16x16x32_bf16 v[68:71], v[172:175], v[224:227], v[68:71]
	v_mfma_f32_16x16x32_bf16 v[64:67], v[180:183], v[224:227], v[64:67]
	s_setprio 0
	s_barrier
	s_add_i32 s34, s65, s52
	v_lshl_add_u64 v[144:145], v[144:145], 0, s[18:19]
	s_mov_b32 m0, s34
	ds_read_b128 v[184:187], v151 offset:49152
	ds_read_b128 v[188:191], v151 offset:50176
	ds_read_b128 v[192:195], v151 offset:51200
	ds_read_b128 v[196:199], v151 offset:52224
	ds_read_b128 v[212:215], v151 offset:53248
	ds_read_b128 v[216:219], v151 offset:54272
	ds_read_b128 v[220:223], v151 offset:55296
	ds_read_b128 v[224:227], v151 offset:56320
	global_load_lds_dwordx4 v[144:145], off
	s_add_i32 m0, s34, 0x2000
	s_add_u32 s34, s44, 0x40080
	v_lshl_add_u64 v[144:145], v[228:229], 0, s[18:19]
	s_addc_u32 s35, s45, 0
	s_add_i32 s44, s66, s52
	global_load_lds_dwordx4 v[144:145], off
	s_mov_b32 m0, s44
	v_lshl_add_u64 v[144:145], s[34:35], 0, v[130:131]
	global_load_lds_dwordx4 v[144:145], off
	s_add_i32 m0, s44, 0x2000
	v_lshl_add_u64 v[144:145], s[34:35], 0, v[134:135]
	global_load_lds_dwordx4 v[144:145], off
	s_mov_b32 m0, s57
	v_lshl_add_u64 v[144:145], v[230:231], 0, s[18:19]
	global_load_lds_dwordx4 v[144:145], off
	v_lshl_add_u64 v[144:145], v[232:233], 0, s[18:19]
	s_nop 0
	s_cmp_lg_u32 s64, 12
	s_cbranch_scc1 .Ldf_skipD_4
	s_mov_b32 m0, s58
	s_nop 0
	global_load_lds_dwordx4 v[144:145], off

; #define PG8_STAGE(bufoff, gbase, voff) do { _Pragma("unroll") for (int _i = 0; _i < 2; ++_i) \
;         __builtin_amdgcn_global_load_lds((const unsigned*)((const char*)(gbase) + (voff)[_i]), (PG8_LAS unsigned*)(lds + (bufoff) + ldsw + _i * 8192), 16, 0, 0); } while (0)
; #define PG8_LDA(dst, b, h) do { _Pragma("unroll") for (int m = 0; m < 4; ++m) _Pragma("unroll") for (int k = 0; k < 2; ++k) dst[m][k] = *(const PG8_LAS bf16x8*)(lds + PG8_SA(b, h) + aoff + m * 2048 + k * 1024); } while (0)
; #define PG8_LDB(dst, b, h) do { _Pragma("unroll") for (int n = 0; n < 2; ++n) _Pragma("unroll") for (int k = 0; k < 2; ++k) dst[n][k] = *(const PG8_LAS bf16x8*)(lds + PG8_SB(b, h) + boff + n * 2048 + k * 1024); } while (0)
; #define PG8_WAIT_V(n) asm volatile("s_waitcnt vmcnt(" #n ")" ::: "memory")
; #define PG8_WAIT_L(n) asm volatile("s_waitcnt lgkmcnt(" #n ")" ::: "memory")
; #define PG8_BAR __builtin_amdgcn_s_barrier()
; #define PG8_SCHED __builtin_amdgcn_sched_barrier(0)
; #define PG8_MMA2(ai) PG8_MMA(ai, 0, At, B0)
;     ...
;         for (int t = 0; t < nt; t += 2) {
;             const bool last = (t == nt - 2);
;             const char* a1 = cA + (size_t)(t + 1) * kstep;
;             const char* a2 = last ? nA : cA + (size_t)(t + 2) * kstep; const char* b2 = last ? nB : cB + (size_t)(t + 2) * kstep;
;             const char* a3 = a2 + kstep; const char* b3 = b2 + kstep;
;             if (last && has_next) S.a_ready(nxt);
;             if constexpr (SP2) {
;             PG8_LDB(B0, 0, 0); PG8_LDB(B1, 0, 1); PG8_SCHED; PG8_LDA(At, 0, 0); PG8_STAGE(PG8_SA(1, 1), a1 + hstep, voffA);
;             PG8_WAIT_V(8); PG8_WAIT_L(0); PG8_BAR; PG8_MMA2(0); PG8_BAR; PG8_SCHED;
;             PG8_LDA(At, 0, 1); PG8_STAGE(PG8_SB(0, 0), b2, voffB); PG8_STAGE(PG8_SB(0, 1), b2 + hstep, voffB); PG8_STAGE(PG8_SA(0, 0), a2, voffA);
;             PG8_WAIT_V(8); PG8_WAIT_L(0); PG8_BAR; PG8_MMA2(1); PG8_BAR; PG8_SCHED;
;             PG8_LDB(B0, 1, 0); PG8_LDB(B1, 1, 1); PG8_SCHED; PG8_LDA(At, 1, 0); PG8_STAGE(PG8_SA(0, 1), a2 + hstep, voffA);
;             PG8_WAIT_V(8); PG8_WAIT_L(0); PG8_BAR; PG8_MMA2(0); PG8_BAR; PG8_SCHED;
;             PG8_LDA(At, 1, 1); PG8_STAGE(PG8_SB(1, 0), b3, voffB); PG8_STAGE(PG8_SB(1, 1), b3 + hstep, voffB); PG8_STAGE(PG8_SA(1, 0), a3, voffA);
;             PG8_WAIT_V(8); PG8_WAIT_L(0); PG8_BAR; PG8_MMA2(1); PG8_BAR; PG8_SCHED;
.Ldf_skipA_5:
	ds_read_b128 v[140:143], v161
	ds_read_b128 v[144:147], v161 offset:1024
	ds_read_b128 v[148:151], v161 offset:2048
	ds_read_b128 v[152:155], v161 offset:3072
	ds_read_b128 v[164:167], v162
	ds_read_b128 v[168:171], v162 offset:1024
	ds_read_b128 v[172:175], v162 offset:2048
	ds_read_b128 v[176:179], v162 offset:3072
	s_add_u32 s38, s36, 0x100
	s_addc_u32 s39, s37, 0
	s_cmp_eq_u32 s67, 40
	s_cselect_b32 s43, s15, s39
	s_cselect_b32 s42, s14, s38
	s_cselect_b32 s41, s27, s9
	s_cselect_b32 s40, s26, s8
	v_lshl_add_u64 v[156:157], s[36:37], 0, v[134:135]
	s_add_i32 m0, s49, 0xc000
	ds_read_b128 v[180:183], v163
	ds_read_b128 v[184:187], v163 offset:1024
	ds_read_b128 v[188:191], v163 offset:2048
	ds_read_b128 v[192:195], v163 offset:3072
	ds_read_b128 v[196:199], v163 offset:4096
	ds_read_b128 v[212:215], v163 offset:5120
	ds_read_b128 v[216:219], v163 offset:6144
	ds_read_b128 v[220:223], v163 offset:7168
	global_load_lds_dwordx4 v[156:157], off
	s_add_i32 m0, s49, 0xe000
	v_lshl_add_u64 v[156:157], s[36:37], 0, v[132:133]
	global_load_lds_dwordx4 v[156:157], off
	s_waitcnt vmcnt(8)
	s_waitcnt lgkmcnt(0)
	s_barrier
	s_setprio 1
	s_waitcnt lgkmcnt(0)
	v_mfma_f32_16x16x32_bf16 v[124:127], v[140:143], v[180:183], v[124:127]
	v_mfma_f32_16x16x32_bf16 v[120:123], v[148:151], v[180:183], v[120:123]
	v_mfma_f32_16x16x32_bf16 v[108:111], v[140:143], v[188:191], v[108:111]
	v_mfma_f32_16x16x32_bf16 v[104:107], v[148:151], v[188:191], v[104:107]
	v_mfma_f32_16x16x32_bf16 v[92:95], v[140:143], v[196:199], v[92:95]
	v_mfma_f32_16x16x32_bf16 v[88:91], v[148:151], v[196:199], v[88:91]
	v_mfma_f32_16x16x32_bf16 v[76:79], v[140:143], v[216:219], v[76:79]
	v_mfma_f32_16x16x32_bf16 v[72:75], v[148:151], v[216:219], v[72:75]
	v_mfma_f32_16x16x32_bf16 v[124:127], v[144:147], v[184:187], v[124:127]
	v_mfma_f32_16x16x32_bf16 v[120:123], v[152:155], v[184:187], v[120:123]
	v_mfma_f32_16x16x32_bf16 v[108:111], v[144:147], v[192:195], v[108:111]
	v_mfma_f32_16x16x32_bf16 v[104:107], v[152:155], v[192:195], v[104:107]
	v_mfma_f32_16x16x32_bf16 v[92:95], v[144:147], v[212:215], v[92:95]
	v_mfma_f32_16x16x32_bf16 v[88:91], v[152:155], v[212:215], v[88:91]
	v_mfma_f32_16x16x32_bf16 v[76:79], v[144:147], v[220:223], v[76:79]
	v_mfma_f32_16x16x32_bf16 v[72:75], v[152:155], v[220:223], v[72:75]
	s_setprio 0
	s_setprio 1
	v_mfma_f32_16x16x32_bf16 v[116:119], v[164:167], v[180:183], v[116:119]
	v_mfma_f32_16x16x32_bf16 v[112:115], v[172:175], v[180:183], v[112:115]
	v_mfma_f32_16x16x32_bf16 v[100:103], v[164:167], v[188:191], v[100:103]
	v_mfma_f32_16x16x32_bf16 v[96:99], v[172:175], v[188:191], v[96:99]
	v_mfma_f32_16x16x32_bf16 v[84:87], v[164:167], v[196:199], v[84:87]
	v_mfma_f32_16x16x32_bf16 v[80:83], v[172:175], v[196:199], v[80:83]
	v_mfma_f32_16x16x32_bf16 v[68:71], v[164:167], v[216:219], v[68:71]
	v_mfma_f32_16x16x32_bf16 v[64:67], v[172:175], v[216:219], v[64:67]
	v_mfma_f32_16x16x32_bf16 v[116:119], v[168:171], v[184:187], v[116:119]
	v_mfma_f32_16x16x32_bf16 v[112:115], v[176:179], v[184:187], v[112:115]
	v_mfma_f32_16x16x32_bf16 v[100:103], v[168:171], v[192:195], v[100:103]
	v_mfma_f32_16x16x32_bf16 v[96:99], v[176:179], v[192:195], v[96:99]
	v_mfma_f32_16x16x32_bf16 v[84:87], v[168:171], v[212:215], v[84:87]
	v_mfma_f32_16x16x32_bf16 v[80:83], v[176:179], v[212:215], v[80:83]
	v_mfma_f32_16x16x32_bf16 v[68:71], v[168:171], v[220:223], v[68:71]
	v_mfma_f32_16x16x32_bf16 v[64:67], v[176:179], v[220:223], v[64:67]
	s_setprio 0
	s_barrier
	s_add_i32 s34, s3, s48
	v_lshl_add_u64 v[156:157], s[40:41], 0, v[128:129]
	s_mov_b32 m0, s34
	ds_read_b128 v[180:183], v163 offset:16384
	ds_read_b128 v[184:187], v163 offset:17408
	ds_read_b128 v[188:191], v163 offset:18432
	ds_read_b128 v[192:195], v163 offset:19456
	ds_read_b128 v[196:199], v163 offset:20480
	ds_read_b128 v[212:215], v163 offset:21504
	ds_read_b128 v[216:219], v163 offset:22528
	ds_read_b128 v[220:223], v163 offset:23552
	global_load_lds_dwordx4 v[156:157], off
	s_add_i32 m0, s34, 0x2000
	s_add_u32 s34, s40, 0xb0000
	v_lshl_add_u64 v[224:225], s[40:41], 0, v[130:131]
	s_addc_u32 s35, s41, 0
	s_add_i32 s36, s63, s48
	global_load_lds_dwordx4 v[224:225], off
	v_lshl_add_u64 v[226:227], s[34:35], 0, v[128:129]
	s_mov_b32 m0, s36
	v_lshl_add_u64 v[228:229], s[42:43], 0, v[130:131]
	global_load_lds_dwordx4 v[226:227], off
	s_add_i32 m0, s36, 0x2000
	v_lshl_add_u64 v[226:227], s[34:35], 0, v[130:131]
	global_load_lds_dwordx4 v[226:227], off
	s_mov_b32 m0, s49
	v_lshl_add_u64 v[226:227], s[42:43], 0, v[128:129]
	global_load_lds_dwordx4 v[226:227], off
	s_nop 0
	s_waitcnt vmcnt(7)
	s_waitcnt lgkmcnt(0)
	s_barrier
; #define PG8_STAGE(bufoff, gbase, voff) do { _Pragma("unroll") for (int _i = 0; _i < 2; ++_i) \
;         __builtin_amdgcn_global_load_lds((const unsigned*)((const char*)(gbase) + (voff)[_i]), (PG8_LAS unsigned*)(lds + (bufoff) + ldsw + _i * 8192), 16, 0, 0); } while (0)
; #define PG8_LDA(dst, b, h) do { _Pragma("unroll") for (int m = 0; m < 4; ++m) _Pragma("unroll") for (int k = 0; k < 2; ++k) dst[m][k] = *(const PG8_LAS bf16x8*)(lds + PG8_SA(b, h) + aoff + m * 2048 + k * 1024); } while (0)
; #define PG8_LDB(dst, b, h) do { _Pragma("unroll") for (int n = 0; n < 2; ++n) _Pragma("unroll") for (int k = 0; k < 2; ++k) dst[n][k] = *(const PG8_LAS bf16x8*)(lds + PG8_SB(b, h) + boff + n * 2048 + k * 1024); } while (0)
; #define PG8_WAIT_V(n) asm volatile("s_waitcnt vmcnt(" #n ")" ::: "memory")
; #define PG8_WAIT_L(n) asm volatile("s_waitcnt lgkmcnt(" #n ")" ::: "memory")
; #define PG8_BAR __builtin_amdgcn_s_barrier()
; #define PG8_SCHED __builtin_amdgcn_sched_barrier(0)
; #define PG8_MMA2(ai) PG8_MMA(ai, 0, At, B0)
;     ...
;         for (int t = 0; t < nt; t += 2) {
;             const bool last = (t == nt - 2);
;             const char* a1 = cA + (size_t)(t + 1) * kstep;
;             const char* a2 = last ? nA : cA + (size_t)(t + 2) * kstep; const char* b2 = last ? nB : cB + (size_t)(t + 2) * kstep;
;             const char* a3 = a2 + kstep; const char* b3 = b2 + kstep;
;             if (last && has_next) S.a_ready(nxt);
;             if constexpr (SP2) {
;             PG8_LDB(B0, 0, 0); PG8_LDB(B1, 0, 1); PG8_SCHED; PG8_LDA(At, 0, 0); PG8_STAGE(PG8_SA(1, 1), a1 + hstep, voffA);
;             PG8_WAIT_V(8); PG8_WAIT_L(0); PG8_BAR; PG8_MMA2(0); PG8_BAR; PG8_SCHED;
;             PG8_LDA(At, 0, 1); PG8_STAGE(PG8_SB(0, 0), b2, voffB); PG8_STAGE(PG8_SB(0, 1), b2 + hstep, voffB); PG8_STAGE(PG8_SA(0, 0), a2, voffA);
;             PG8_WAIT_V(8); PG8_WAIT_L(0); PG8_BAR; PG8_MMA2(1); PG8_BAR; PG8_SCHED;
;             PG8_LDB(B0, 1, 0); PG8_LDB(B1, 1, 1); PG8_SCHED; PG8_LDA(At, 1, 0); PG8_STAGE(PG8_SA(0, 1), a2 + hstep, voffA);
;             PG8_WAIT_V(8); PG8_WAIT_L(0); PG8_BAR; PG8_MMA2(0); PG8_BAR; PG8_SCHED;
;             PG8_LDA(At, 1, 1); PG8_STAGE(PG8_SB(1, 0), b3, voffB); PG8_STAGE(PG8_SB(1, 1), b3 + hstep, voffB); PG8_STAGE(PG8_SA(1, 0), a3, voffA);
;             PG8_WAIT_V(8); PG8_WAIT_L(0); PG8_BAR; PG8_MMA2(1); PG8_BAR; PG8_SCHED;
	s_setprio 1
	s_waitcnt lgkmcnt(0)
	v_mfma_f32_16x16x32_bf16 v[60:63], v[140:143], v[180:183], v[60:63]
	v_mfma_f32_16x16x32_bf16 v[56:59], v[148:151], v[180:183], v[56:59]
	v_mfma_f32_16x16x32_bf16 v[44:47], v[140:143], v[188:191], v[44:47]
	v_mfma_f32_16x16x32_bf16 v[40:43], v[148:151], v[188:191], v[40:43]
	v_mfma_f32_16x16x32_bf16 v[28:31], v[140:143], v[196:199], v[28:31]
	v_mfma_f32_16x16x32_bf16 v[24:27], v[148:151], v[196:199], v[24:27]
	v_mfma_f32_16x16x32_bf16 v[12:15], v[140:143], v[216:219], v[12:15]
	v_mfma_f32_16x16x32_bf16 v[8:11], v[148:151], v[216:219], v[8:11]
	v_mfma_f32_16x16x32_bf16 v[60:63], v[144:147], v[184:187], v[60:63]
	v_mfma_f32_16x16x32_bf16 v[56:59], v[152:155], v[184:187], v[56:59]
	v_mfma_f32_16x16x32_bf16 v[44:47], v[144:147], v[192:195], v[44:47]
	v_mfma_f32_16x16x32_bf16 v[40:43], v[152:155], v[192:195], v[40:43]
	v_mfma_f32_16x16x32_bf16 v[28:31], v[144:147], v[212:215], v[28:31]
	v_mfma_f32_16x16x32_bf16 v[24:27], v[152:155], v[212:215], v[24:27]
	v_mfma_f32_16x16x32_bf16 v[12:15], v[144:147], v[220:223], v[12:15]
	v_mfma_f32_16x16x32_bf16 v[8:11], v[152:155], v[220:223], v[8:11]
	s_setprio 0
	s_setprio 1
	v_mfma_f32_16x16x32_bf16 v[52:55], v[164:167], v[180:183], v[52:55]
	v_mfma_f32_16x16x32_bf16 v[48:51], v[172:175], v[180:183], v[48:51]
	v_mfma_f32_16x16x32_bf16 v[36:39], v[164:167], v[188:191], v[36:39]
	v_mfma_f32_16x16x32_bf16 v[32:35], v[172:175], v[188:191], v[32:35]
	v_mfma_f32_16x16x32_bf16 v[20:23], v[164:167], v[196:199], v[20:23]
	v_mfma_f32_16x16x32_bf16 v[16:19], v[172:175], v[196:199], v[16:19]
	v_mfma_f32_16x16x32_bf16 v[4:7], v[164:167], v[216:219], v[4:7]
	v_mfma_f32_16x16x32_bf16 v[0:3], v[172:175], v[216:219], v[0:3]
	v_mfma_f32_16x16x32_bf16 v[52:55], v[168:171], v[184:187], v[52:55]
	v_mfma_f32_16x16x32_bf16 v[48:51], v[176:179], v[184:187], v[48:51]
	v_mfma_f32_16x16x32_bf16 v[36:39], v[168:171], v[192:195], v[36:39]
	v_mfma_f32_16x16x32_bf16 v[32:35], v[176:179], v[192:195], v[32:35]
	v_mfma_f32_16x16x32_bf16 v[20:23], v[168:171], v[212:215], v[20:23]
	v_mfma_f32_16x16x32_bf16 v[16:19], v[176:179], v[212:215], v[16:19]
	v_mfma_f32_16x16x32_bf16 v[4:7], v[168:171], v[220:223], v[4:7]
	v_mfma_f32_16x16x32_bf16 v[0:3], v[176:179], v[220:223], v[0:3]
	s_setprio 0
	s_barrier
	s_add_i32 s36, 0, 0x18000
	s_add_i32 s37, 0, 0x1c000
	v_add_u32_e32 v152, s36, v159
	v_add_u32_e32 v176, s37, v159
	ds_read_b128 v[140:143], v152
	ds_read_b128 v[144:147], v152 offset:1024
	ds_read_b128 v[148:151], v152 offset:2048
	ds_read_b128 v[152:155], v152 offset:3072
	ds_read_b128 v[164:167], v176
	ds_read_b128 v[168:171], v176 offset:1024
	ds_read_b128 v[172:175], v176 offset:2048
	ds_read_b128 v[176:179], v176 offset:3072
	s_add_u32 s34, s42, 0xb0000
	s_addc_u32 s35, s43, 0
	s_mov_b32 m0, s50
	s_nop 0
	global_load_lds_dwordx4 v[228:229], off
	s_mov_b32 m0, s51
	v_lshl_add_u64 v[230:231], s[34:35], 0, v[128:129]
	ds_read_b128 v[180:183], v163 offset:32768
	ds_read_b128 v[184:187], v163 offset:33792
	ds_read_b128 v[188:191], v163 offset:34816
	ds_read_b128 v[192:195], v163 offset:35840
	ds_read_b128 v[196:199], v163 offset:36864
	ds_read_b128 v[212:215], v163 offset:37888
	ds_read_b128 v[216:219], v163 offset:38912
	ds_read_b128 v[220:223], v163 offset:39936
	global_load_lds_dwordx4 v[230:231], off
	s_mov_b32 m0, s52
	v_lshl_add_u64 v[230:231], s[34:35], 0, v[130:131]
	global_load_lds_dwordx4 v[230:231], off
	s_waitcnt vmcnt(8)
	s_waitcnt lgkmcnt(0)
	s_barrier
	s_setprio 1
	s_waitcnt lgkmcnt(0)
	v_mfma_f32_16x16x32_bf16 v[124:127], v[140:143], v[180:183], v[124:127]
	v_mfma_f32_16x16x32_bf16 v[120:123], v[148:151], v[180:183], v[120:123]
	v_mfma_f32_16x16x32_bf16 v[108:111], v[140:143], v[188:191], v[108:111]
	v_mfma_f32_16x16x32_bf16 v[104:107], v[148:151], v[188:191], v[104:107]
	v_mfma_f32_16x16x32_bf16 v[92:95], v[140:143], v[196:199], v[92:95]
	v_mfma_f32_16x16x32_bf16 v[88:91], v[148:151], v[196:199], v[88:91]
	v_mfma_f32_16x16x32_bf16 v[76:79], v[140:143], v[216:219], v[76:79]
	v_mfma_f32_16x16x32_bf16 v[72:75], v[148:151], v[216:219], v[72:75]
	v_mfma_f32_16x16x32_bf16 v[124:127], v[144:147], v[184:187], v[124:127]
	v_mfma_f32_16x16x32_bf16 v[120:123], v[152:155], v[184:187], v[120:123]
	v_mfma_f32_16x16x32_bf16 v[108:111], v[144:147], v[192:195], v[108:111]
	v_mfma_f32_16x16x32_bf16 v[104:107], v[152:155], v[192:195], v[104:107]
	v_mfma_f32_16x16x32_bf16 v[92:95], v[144:147], v[212:215], v[92:95]
	v_mfma_f32_16x16x32_bf16 v[88:91], v[152:155], v[212:215], v[88:91]
	v_mfma_f32_16x16x32_bf16 v[76:79], v[144:147], v[220:223], v[76:79]
	v_mfma_f32_16x16x32_bf16 v[72:75], v[152:155], v[220:223], v[72:75]
	s_setprio 0
	s_setprio 1
	v_mfma_f32_16x16x32_bf16 v[116:119], v[164:167], v[180:183], v[116:119]
	v_mfma_f32_16x16x32_bf16 v[112:115], v[172:175], v[180:183], v[112:115]
	v_mfma_f32_16x16x32_bf16 v[100:103], v[164:167], v[188:191], v[100:103]
	v_mfma_f32_16x16x32_bf16 v[96:99], v[172:175], v[188:191], v[96:99]
	v_mfma_f32_16x16x32_bf16 v[84:87], v[164:167], v[196:199], v[84:87]
	v_mfma_f32_16x16x32_bf16 v[80:83], v[172:175], v[196:199], v[80:83]
	v_mfma_f32_16x16x32_bf16 v[68:71], v[164:167], v[216:219], v[68:71]
	v_mfma_f32_16x16x32_bf16 v[64:67], v[172:175], v[216:219], v[64:67]
	v_mfma_f32_16x16x32_bf16 v[116:119], v[168:171], v[184:187], v[116:119]
	v_mfma_f32_16x16x32_bf16 v[112:115], v[176:179], v[184:187], v[112:115]
	v_mfma_f32_16x16x32_bf16 v[100:103], v[168:171], v[192:195], v[100:103]
	v_mfma_f32_16x16x32_bf16 v[96:99], v[176:179], v[192:195], v[96:99]
	v_mfma_f32_16x16x32_bf16 v[84:87], v[168:171], v[212:215], v[84:87]
	v_mfma_f32_16x16x32_bf16 v[80:83], v[176:179], v[212:215], v[80:83]
	v_mfma_f32_16x16x32_bf16 v[68:71], v[168:171], v[220:223], v[68:71]
	v_mfma_f32_16x16x32_bf16 v[64:67], v[176:179], v[220:223], v[64:67]
	s_setprio 0
	s_barrier
	s_add_i32 s34, s36, s48
	v_lshl_add_u64 v[156:157], v[156:157], 0, s[20:21]
	s_mov_b32 m0, s34
	ds_read_b128 v[180:183], v163 offset:49152
	ds_read_b128 v[184:187], v163 offset:50176
	ds_read_b128 v[188:191], v163 offset:51200
	ds_read_b128 v[192:195], v163 offset:52224
	ds_read_b128 v[196:199], v163 offset:53248
	ds_read_b128 v[212:215], v163 offset:54272
	ds_read_b128 v[216:219], v163 offset:55296
	ds_read_b128 v[220:223], v163 offset:56320
	global_load_lds_dwordx4 v[156:157], off
	s_add_i32 m0, s34, 0x2000
	s_add_u32 s34, s40, 0xb0080
	v_lshl_add_u64 v[156:157], v[224:225], 0, s[20:21]
	s_addc_u32 s35, s41, 0
	s_add_i32 s36, s37, s48
	global_load_lds_dwordx4 v[156:157], off
	s_mov_b32 m0, s36
	v_lshl_add_u64 v[156:157], s[34:35], 0, v[128:129]
	global_load_lds_dwordx4 v[156:157], off
	s_add_i32 m0, s36, 0x2000
	v_lshl_add_u64 v[156:157], s[34:35], 0, v[130:131]
	global_load_lds_dwordx4 v[156:157], off
	s_mov_b32 m0, s58
	v_lshl_add_u64 v[156:157], v[226:227], 0, s[20:21]
	global_load_lds_dwordx4 v[156:157], off
	v_lshl_add_u64 v[156:157], v[228:229], 0, s[20:21]
	s_nop 0
	s_cmp_lg_u32 s67, 40
	s_cbranch_scc1 .Ldf_skipD_5
	s_mov_b32 m0, s59
	s_nop 0
	global_load_lds_dwordx4 v[156:157], off

; #define PG8_STAGE(bufoff, gbase, voff) do { _Pragma("unroll") for (int _i = 0; _i < 2; ++_i) \
;         __builtin_amdgcn_global_load_lds((const unsigned*)((const char*)(gbase) + (voff)[_i]), (PG8_LAS unsigned*)(lds + (bufoff) + ldsw + _i * 8192), 16, 0, 0); } while (0)
; #define PG8_LDA(dst, b, h) do { _Pragma("unroll") for (int m = 0; m < 4; ++m) _Pragma("unroll") for (int k = 0; k < 2; ++k) dst[m][k] = *(const PG8_LAS bf16x8*)(lds + PG8_SA(b, h) + aoff + m * 2048 + k * 1024); } while (0)
; #define PG8_LDB(dst, b, h) do { _Pragma("unroll") for (int n = 0; n < 2; ++n) _Pragma("unroll") for (int k = 0; k < 2; ++k) dst[n][k] = *(const PG8_LAS bf16x8*)(lds + PG8_SB(b, h) + boff + n * 2048 + k * 1024); } while (0)
; #define PG8_WAIT_V(n) asm volatile("s_waitcnt vmcnt(" #n ")" ::: "memory")
; #define PG8_WAIT_L(n) asm volatile("s_waitcnt lgkmcnt(" #n ")" ::: "memory")
; #define PG8_BAR __builtin_amdgcn_s_barrier()
; #define PG8_SCHED __builtin_amdgcn_sched_barrier(0)
; #define PG8_MMA2(ai) PG8_MMA(ai, 0, At, B0)
; #define PG8_MMA2(ai) PG8_MMA(ai, 1, At, B1)
; #define PG8_MMA2(ai) do { PG8_MMA(ai, 0, At, B0); PG8_MMA(ai, 1, At, B1); } while (0)
;     ...
;             PG8_LDB(B0, 0, 0); PG8_LDB(B1, 0, 1); PG8_SCHED; PG8_LDA(At, 0, 0); PG8_STAGE(PG8_SA(1, 1), a1 + hstep, voffA);
;             PG8_WAIT_V(8); PG8_WAIT_L(0); PG8_BAR; PG8_MMA2(0); PG8_BAR; PG8_SCHED;
;             PG8_LDA(At, 0, 1); PG8_STAGE(PG8_SB(0, 0), b2, voffB); PG8_STAGE(PG8_SB(0, 1), b2 + hstep, voffB); PG8_STAGE(PG8_SA(0, 0), a2, voffA);
;             PG8_WAIT_V(8); PG8_WAIT_L(0); PG8_BAR; PG8_MMA2(1); PG8_BAR; PG8_SCHED;
.Ldf_skipA_6:
	ds_read_b128 v[152:155], v149
	ds_read_b128 v[156:159], v149 offset:1024
	ds_read_b128 v[160:163], v149 offset:2048
	ds_read_b128 v[164:167], v149 offset:3072
	ds_read_b128 v[168:171], v150
	ds_read_b128 v[172:175], v150 offset:1024
	ds_read_b128 v[176:179], v150 offset:2048
	ds_read_b128 v[180:183], v150 offset:3072
	s_add_u32 s34, s40, 0xfffc0080
	s_addc_u32 s35, s41, -1
	s_cmp_eq_u32 s62, 12
	s_cselect_b32 s45, s7, s35
	s_cselect_b32 s44, s8, s34
	s_cselect_b32 s43, s9, s61
	s_cselect_b32 s42, s21, s23
	v_lshl_add_u64 v[144:145], s[40:41], 0, v[138:139]
	s_add_i32 m0, s39, 0xc000
	ds_read_b128 v[184:187], v151
	ds_read_b128 v[188:191], v151 offset:1024
	ds_read_b128 v[192:195], v151 offset:2048
	ds_read_b128 v[196:199], v151 offset:3072
	ds_read_b128 v[212:215], v151 offset:4096
	ds_read_b128 v[216:219], v151 offset:5120
	ds_read_b128 v[220:223], v151 offset:6144
	ds_read_b128 v[224:227], v151 offset:7168
	global_load_lds_dwordx4 v[144:145], off
	s_add_i32 m0, s39, 0xe000
	v_lshl_add_u64 v[144:145], s[40:41], 0, v[136:137]
	global_load_lds_dwordx4 v[144:145], off
	s_waitcnt vmcnt(8)
	s_waitcnt lgkmcnt(0)
	s_barrier
	s_setprio 1
	s_waitcnt lgkmcnt(0)
	v_mfma_f32_16x16x32_bf16 v[124:127], v[152:155], v[184:187], v[124:127]
	v_mfma_f32_16x16x32_bf16 v[120:123], v[160:163], v[184:187], v[120:123]
	v_mfma_f32_16x16x32_bf16 v[108:111], v[152:155], v[192:195], v[108:111]
	v_mfma_f32_16x16x32_bf16 v[104:107], v[160:163], v[192:195], v[104:107]
	v_mfma_f32_16x16x32_bf16 v[92:95], v[152:155], v[212:215], v[92:95]
	v_mfma_f32_16x16x32_bf16 v[88:91], v[160:163], v[212:215], v[88:91]
	v_mfma_f32_16x16x32_bf16 v[76:79], v[152:155], v[220:223], v[76:79]
	v_mfma_f32_16x16x32_bf16 v[72:75], v[160:163], v[220:223], v[72:75]
	v_mfma_f32_16x16x32_bf16 v[124:127], v[156:159], v[188:191], v[124:127]
	v_mfma_f32_16x16x32_bf16 v[120:123], v[164:167], v[188:191], v[120:123]
	v_mfma_f32_16x16x32_bf16 v[108:111], v[156:159], v[196:199], v[108:111]
	v_mfma_f32_16x16x32_bf16 v[104:107], v[164:167], v[196:199], v[104:107]
	v_mfma_f32_16x16x32_bf16 v[92:95], v[156:159], v[216:219], v[92:95]
	v_mfma_f32_16x16x32_bf16 v[88:91], v[164:167], v[216:219], v[88:91]
	v_mfma_f32_16x16x32_bf16 v[76:79], v[156:159], v[224:227], v[76:79]
	v_mfma_f32_16x16x32_bf16 v[72:75], v[164:167], v[224:227], v[72:75]
	s_setprio 0
	s_setprio 1
	v_mfma_f32_16x16x32_bf16 v[116:119], v[168:171], v[184:187], v[116:119]
	v_mfma_f32_16x16x32_bf16 v[112:115], v[176:179], v[184:187], v[112:115]
	v_mfma_f32_16x16x32_bf16 v[100:103], v[168:171], v[192:195], v[100:103]
	v_mfma_f32_16x16x32_bf16 v[96:99], v[176:179], v[192:195], v[96:99]
	v_mfma_f32_16x16x32_bf16 v[84:87], v[168:171], v[212:215], v[84:87]
	v_mfma_f32_16x16x32_bf16 v[80:83], v[176:179], v[212:215], v[80:83]
	v_mfma_f32_16x16x32_bf16 v[68:71], v[168:171], v[220:223], v[68:71]
	v_mfma_f32_16x16x32_bf16 v[64:67], v[176:179], v[220:223], v[64:67]
	v_mfma_f32_16x16x32_bf16 v[116:119], v[172:175], v[188:191], v[116:119]
	v_mfma_f32_16x16x32_bf16 v[112:115], v[180:183], v[188:191], v[112:115]
	v_mfma_f32_16x16x32_bf16 v[100:103], v[172:175], v[196:199], v[100:103]
	v_mfma_f32_16x16x32_bf16 v[96:99], v[180:183], v[196:199], v[96:99]
	v_mfma_f32_16x16x32_bf16 v[84:87], v[172:175], v[216:219], v[84:87]
	v_mfma_f32_16x16x32_bf16 v[80:83], v[180:183], v[216:219], v[80:83]
	v_mfma_f32_16x16x32_bf16 v[68:71], v[172:175], v[224:227], v[68:71]
	v_mfma_f32_16x16x32_bf16 v[64:67], v[180:183], v[224:227], v[64:67]
	s_setprio 0
	s_barrier
	s_add_i32 s34, s3, s50
	v_lshl_add_u64 v[144:145], s[42:43], 0, v[130:131]
	s_mov_b32 m0, s34
	ds_read_b128 v[184:187], v151 offset:16384
	ds_read_b128 v[188:191], v151 offset:17408
	ds_read_b128 v[192:195], v151 offset:18432
	ds_read_b128 v[196:199], v151 offset:19456
	ds_read_b128 v[212:215], v151 offset:20480
	ds_read_b128 v[216:219], v151 offset:21504
	ds_read_b128 v[220:223], v151 offset:22528
	ds_read_b128 v[224:227], v151 offset:23552
	global_load_lds_dwordx4 v[144:145], off
	s_add_i32 m0, s34, 0x2000
	s_add_u32 s34, s42, 0x40000
	v_lshl_add_u64 v[228:229], s[42:43], 0, v[134:135]
	s_addc_u32 s35, s43, 0
	s_add_i32 s63, s59, s50
	global_load_lds_dwordx4 v[228:229], off
	v_lshl_add_u64 v[230:231], s[34:35], 0, v[130:131]
	s_mov_b32 m0, s63
	v_lshl_add_u64 v[232:233], s[44:45], 0, v[132:133]
	global_load_lds_dwordx4 v[230:231], off
	s_add_i32 m0, s63, 0x2000
	v_lshl_add_u64 v[230:231], s[34:35], 0, v[134:135]
	global_load_lds_dwordx4 v[230:231], off
	s_mov_b32 m0, s39
	v_lshl_add_u64 v[230:231], s[44:45], 0, v[128:129]
	global_load_lds_dwordx4 v[230:231], off
	s_nop 0
	s_waitcnt vmcnt(7)
	s_waitcnt lgkmcnt(0)
	s_barrier
; #define PG8_STAGE(bufoff, gbase, voff) do { _Pragma("unroll") for (int _i = 0; _i < 2; ++_i) \
;         __builtin_amdgcn_global_load_lds((const unsigned*)((const char*)(gbase) + (voff)[_i]), (PG8_LAS unsigned*)(lds + (bufoff) + ldsw + _i * 8192), 16, 0, 0); } while (0)
; #define PG8_LDA(dst, b, h) do { _Pragma("unroll") for (int m = 0; m < 4; ++m) _Pragma("unroll") for (int k = 0; k < 2; ++k) dst[m][k] = *(const PG8_LAS bf16x8*)(lds + PG8_SA(b, h) + aoff + m * 2048 + k * 1024); } while (0)
; #define PG8_LDB(dst, b, h) do { _Pragma("unroll") for (int n = 0; n < 2; ++n) _Pragma("unroll") for (int k = 0; k < 2; ++k) dst[n][k] = *(const PG8_LAS bf16x8*)(lds + PG8_SB(b, h) + boff + n * 2048 + k * 1024); } while (0)
; #define PG8_WAIT_V(n) asm volatile("s_waitcnt vmcnt(" #n ")" ::: "memory")
; #define PG8_WAIT_L(n) asm volatile("s_waitcnt lgkmcnt(" #n ")" ::: "memory")
; #define PG8_BAR __builtin_amdgcn_s_barrier()
; #define PG8_SCHED __builtin_amdgcn_sched_barrier(0)
; #define PG8_MMA2(ai) PG8_MMA(ai, 0, At, B0)
; #define PG8_MMA2(ai) PG8_MMA(ai, 1, At, B1)
; #define PG8_MMA2(ai) do { PG8_MMA(ai, 0, At, B0); PG8_MMA(ai, 1, At, B1); } while (0)
;     ...
;             PG8_WAIT_V(8); PG8_WAIT_L(0); PG8_BAR; PG8_MMA2(1); PG8_BAR; PG8_SCHED;
;             PG8_LDB(B0, 1, 0); PG8_LDB(B1, 1, 1); PG8_SCHED; PG8_LDA(At, 1, 0); PG8_STAGE(PG8_SA(0, 1), a2 + hstep, voffA);
;             PG8_WAIT_V(8); PG8_WAIT_L(0); PG8_BAR; PG8_MMA2(0); PG8_BAR; PG8_SCHED;
;             PG8_LDA(At, 1, 1); PG8_STAGE(PG8_SB(1, 0), b3, voffB); PG8_STAGE(PG8_SB(1, 1), b3 + hstep, voffB); PG8_STAGE(PG8_SA(1, 0), a3, voffA);
	s_setprio 1
	s_waitcnt lgkmcnt(0)
	v_mfma_f32_16x16x32_bf16 v[60:63], v[152:155], v[184:187], v[60:63]
	v_mfma_f32_16x16x32_bf16 v[56:59], v[160:163], v[184:187], v[56:59]
	v_mfma_f32_16x16x32_bf16 v[44:47], v[152:155], v[192:195], v[44:47]
	v_mfma_f32_16x16x32_bf16 v[40:43], v[160:163], v[192:195], v[40:43]
	v_mfma_f32_16x16x32_bf16 v[28:31], v[152:155], v[212:215], v[28:31]
	v_mfma_f32_16x16x32_bf16 v[24:27], v[160:163], v[212:215], v[24:27]
	v_mfma_f32_16x16x32_bf16 v[12:15], v[152:155], v[220:223], v[12:15]
	v_mfma_f32_16x16x32_bf16 v[8:11], v[160:163], v[220:223], v[8:11]
	v_mfma_f32_16x16x32_bf16 v[60:63], v[156:159], v[188:191], v[60:63]
	v_mfma_f32_16x16x32_bf16 v[56:59], v[164:167], v[188:191], v[56:59]
	v_mfma_f32_16x16x32_bf16 v[44:47], v[156:159], v[196:199], v[44:47]
	v_mfma_f32_16x16x32_bf16 v[40:43], v[164:167], v[196:199], v[40:43]
	v_mfma_f32_16x16x32_bf16 v[28:31], v[156:159], v[216:219], v[28:31]
	v_mfma_f32_16x16x32_bf16 v[24:27], v[164:167], v[216:219], v[24:27]
	v_mfma_f32_16x16x32_bf16 v[12:15], v[156:159], v[224:227], v[12:15]
	v_mfma_f32_16x16x32_bf16 v[8:11], v[164:167], v[224:227], v[8:11]
	s_setprio 0
	s_setprio 1
	v_mfma_f32_16x16x32_bf16 v[52:55], v[168:171], v[184:187], v[52:55]
	v_mfma_f32_16x16x32_bf16 v[48:51], v[176:179], v[184:187], v[48:51]
	v_mfma_f32_16x16x32_bf16 v[36:39], v[168:171], v[192:195], v[36:39]
	v_mfma_f32_16x16x32_bf16 v[32:35], v[176:179], v[192:195], v[32:35]
	v_mfma_f32_16x16x32_bf16 v[20:23], v[168:171], v[212:215], v[20:23]
	v_mfma_f32_16x16x32_bf16 v[16:19], v[176:179], v[212:215], v[16:19]
	v_mfma_f32_16x16x32_bf16 v[4:7], v[168:171], v[220:223], v[4:7]
	v_mfma_f32_16x16x32_bf16 v[0:3], v[176:179], v[220:223], v[0:3]
	v_mfma_f32_16x16x32_bf16 v[52:55], v[172:175], v[188:191], v[52:55]
	v_mfma_f32_16x16x32_bf16 v[48:51], v[180:183], v[188:191], v[48:51]
	v_mfma_f32_16x16x32_bf16 v[36:39], v[172:175], v[196:199], v[36:39]
	v_mfma_f32_16x16x32_bf16 v[32:35], v[180:183], v[196:199], v[32:35]
	v_mfma_f32_16x16x32_bf16 v[20:23], v[172:175], v[216:219], v[20:23]
	v_mfma_f32_16x16x32_bf16 v[16:19], v[180:183], v[216:219], v[16:19]
	v_mfma_f32_16x16x32_bf16 v[4:7], v[172:175], v[224:227], v[4:7]
	v_mfma_f32_16x16x32_bf16 v[0:3], v[180:183], v[224:227], v[0:3]
	s_setprio 0
	s_barrier
	s_add_i32 s63, 0, 0x18000
	s_add_i32 s64, 0, 0x1c000
	v_add_u32_e32 v164, s63, v147
	v_add_u32_e32 v180, s64, v147
	ds_read_b128 v[152:155], v164
	ds_read_b128 v[156:159], v164 offset:1024
	ds_read_b128 v[160:163], v164 offset:2048
	ds_read_b128 v[164:167], v164 offset:3072
	ds_read_b128 v[168:171], v180
	ds_read_b128 v[172:175], v180 offset:1024
	ds_read_b128 v[176:179], v180 offset:2048
	ds_read_b128 v[180:183], v180 offset:3072
	s_add_u32 s34, s44, 0x40000
	s_addc_u32 s35, s45, 0
	s_mov_b32 m0, s51
	s_nop 0
	global_load_lds_dwordx4 v[232:233], off
	s_mov_b32 m0, s52
	v_lshl_add_u64 v[234:235], s[34:35], 0, v[128:129]
	ds_read_b128 v[184:187], v151 offset:32768
	ds_read_b128 v[188:191], v151 offset:33792
	ds_read_b128 v[192:195], v151 offset:34816
	ds_read_b128 v[196:199], v151 offset:35840
	ds_read_b128 v[212:215], v151 offset:36864
	ds_read_b128 v[216:219], v151 offset:37888
	ds_read_b128 v[220:223], v151 offset:38912
	ds_read_b128 v[224:227], v151 offset:39936
	global_load_lds_dwordx4 v[234:235], off
	s_mov_b32 m0, s53
	v_lshl_add_u64 v[234:235], s[34:35], 0, v[132:133]
	global_load_lds_dwordx4 v[234:235], off
	s_waitcnt vmcnt(8)
	s_waitcnt lgkmcnt(0)
	s_barrier
	s_setprio 1
	s_waitcnt lgkmcnt(0)
	v_mfma_f32_16x16x32_bf16 v[124:127], v[152:155], v[184:187], v[124:127]
	v_mfma_f32_16x16x32_bf16 v[120:123], v[160:163], v[184:187], v[120:123]
	v_mfma_f32_16x16x32_bf16 v[108:111], v[152:155], v[192:195], v[108:111]
	v_mfma_f32_16x16x32_bf16 v[104:107], v[160:163], v[192:195], v[104:107]
	v_mfma_f32_16x16x32_bf16 v[92:95], v[152:155], v[212:215], v[92:95]
	v_mfma_f32_16x16x32_bf16 v[88:91], v[160:163], v[212:215], v[88:91]
	v_mfma_f32_16x16x32_bf16 v[76:79], v[152:155], v[220:223], v[76:79]
	v_mfma_f32_16x16x32_bf16 v[72:75], v[160:163], v[220:223], v[72:75]
	v_mfma_f32_16x16x32_bf16 v[124:127], v[156:159], v[188:191], v[124:127]
	v_mfma_f32_16x16x32_bf16 v[120:123], v[164:167], v[188:191], v[120:123]
	v_mfma_f32_16x16x32_bf16 v[108:111], v[156:159], v[196:199], v[108:111]
	v_mfma_f32_16x16x32_bf16 v[104:107], v[164:167], v[196:199], v[104:107]
	v_mfma_f32_16x16x32_bf16 v[92:95], v[156:159], v[216:219], v[92:95]
	v_mfma_f32_16x16x32_bf16 v[88:91], v[164:167], v[216:219], v[88:91]
	v_mfma_f32_16x16x32_bf16 v[76:79], v[156:159], v[224:227], v[76:79]
	v_mfma_f32_16x16x32_bf16 v[72:75], v[164:167], v[224:227], v[72:75]
	s_setprio 0
	s_setprio 1
	v_mfma_f32_16x16x32_bf16 v[116:119], v[168:171], v[184:187], v[116:119]
	v_mfma_f32_16x16x32_bf16 v[112:115], v[176:179], v[184:187], v[112:115]
	v_mfma_f32_16x16x32_bf16 v[100:103], v[168:171], v[192:195], v[100:103]
	v_mfma_f32_16x16x32_bf16 v[96:99], v[176:179], v[192:195], v[96:99]
	v_mfma_f32_16x16x32_bf16 v[84:87], v[168:171], v[212:215], v[84:87]
	v_mfma_f32_16x16x32_bf16 v[80:83], v[176:179], v[212:215], v[80:83]
	v_mfma_f32_16x16x32_bf16 v[68:71], v[168:171], v[220:223], v[68:71]
	v_mfma_f32_16x16x32_bf16 v[64:67], v[176:179], v[220:223], v[64:67]
	v_mfma_f32_16x16x32_bf16 v[116:119], v[172:175], v[188:191], v[116:119]
	v_mfma_f32_16x16x32_bf16 v[112:115], v[180:183], v[188:191], v[112:115]
	v_mfma_f32_16x16x32_bf16 v[100:103], v[172:175], v[196:199], v[100:103]
	v_mfma_f32_16x16x32_bf16 v[96:99], v[180:183], v[196:199], v[96:99]
	v_mfma_f32_16x16x32_bf16 v[84:87], v[172:175], v[216:219], v[84:87]
	v_mfma_f32_16x16x32_bf16 v[80:83], v[180:183], v[216:219], v[80:83]
	v_mfma_f32_16x16x32_bf16 v[68:71], v[172:175], v[224:227], v[68:71]
	v_mfma_f32_16x16x32_bf16 v[64:67], v[180:183], v[224:227], v[64:67]
	s_setprio 0
	s_barrier
	s_add_i32 s34, s63, s50
	v_lshl_add_u64 v[144:145], v[144:145], 0, s[16:17]
	s_mov_b32 m0, s34
	ds_read_b128 v[184:187], v151 offset:49152
	ds_read_b128 v[188:191], v151 offset:50176
	ds_read_b128 v[192:195], v151 offset:51200
	ds_read_b128 v[196:199], v151 offset:52224
	ds_read_b128 v[212:215], v151 offset:53248
	ds_read_b128 v[216:219], v151 offset:54272
	ds_read_b128 v[220:223], v151 offset:55296
	ds_read_b128 v[224:227], v151 offset:56320
	global_load_lds_dwordx4 v[144:145], off
	s_add_i32 m0, s34, 0x2000
	s_add_u32 s34, s42, 0x40080
	v_lshl_add_u64 v[144:145], v[228:229], 0, s[16:17]
	s_addc_u32 s35, s43, 0
	s_add_i32 s42, s64, s50
	global_load_lds_dwordx4 v[144:145], off
	s_mov_b32 m0, s42
	v_lshl_add_u64 v[144:145], s[34:35], 0, v[130:131]
	global_load_lds_dwordx4 v[144:145], off
	s_add_i32 m0, s42, 0x2000
	v_lshl_add_u64 v[144:145], s[34:35], 0, v[134:135]
	global_load_lds_dwordx4 v[144:145], off
	s_mov_b32 m0, s55
	v_lshl_add_u64 v[144:145], v[230:231], 0, s[16:17]
	global_load_lds_dwordx4 v[144:145], off
	v_lshl_add_u64 v[144:145], v[232:233], 0, s[16:17]
	s_nop 0
	s_cmp_lg_u32 s62, 12
	s_cbranch_scc1 .Ldf_skipD_6
	s_mov_b32 m0, s56
	s_nop 0
	global_load_lds_dwordx4 v[144:145], off

; #define PG8_STAGE(bufoff, gbase, voff) do { _Pragma("unroll") for (int _i = 0; _i < 2; ++_i) \
;         __builtin_amdgcn_global_load_lds((const unsigned*)((const char*)(gbase) + (voff)[_i]), (PG8_LAS unsigned*)(lds + (bufoff) + ldsw + _i * 8192), 16, 0, 0); } while (0)
; #define PG8_LDA(dst, b, h) do { _Pragma("unroll") for (int m = 0; m < 4; ++m) _Pragma("unroll") for (int k = 0; k < 2; ++k) dst[m][k] = *(const PG8_LAS bf16x8*)(lds + PG8_SA(b, h) + aoff + m * 2048 + k * 1024); } while (0)
; #define PG8_LDB(dst, b, h) do { _Pragma("unroll") for (int n = 0; n < 2; ++n) _Pragma("unroll") for (int k = 0; k < 2; ++k) dst[n][k] = *(const PG8_LAS bf16x8*)(lds + PG8_SB(b, h) + boff + n * 2048 + k * 1024); } while (0)
; #define PG8_WAIT_V(n) asm volatile("s_waitcnt vmcnt(" #n ")" ::: "memory")
; #define PG8_WAIT_L(n) asm volatile("s_waitcnt lgkmcnt(" #n ")" ::: "memory")
; #define PG8_BAR __builtin_amdgcn_s_barrier()
; #define PG8_SCHED __builtin_amdgcn_sched_barrier(0)
; #define PG8_MMA2(ai) PG8_MMA(ai, 0, At, B0)
; #define PG8_MMA2(ai) PG8_MMA(ai, 1, At, B1)
; #define PG8_MMA2(ai) do { PG8_MMA(ai, 0, At, B0); PG8_MMA(ai, 1, At, B1); } while (0)
;     ...
;             PG8_LDB(B0, 0, 0); PG8_LDB(B1, 0, 1); PG8_SCHED; PG8_LDA(At, 0, 0); PG8_STAGE(PG8_SA(1, 1), a1 + hstep, voffA);
;             PG8_WAIT_V(8); PG8_WAIT_L(0); PG8_BAR; PG8_MMA2(0); PG8_BAR; PG8_SCHED;
;             PG8_LDA(At, 0, 1); PG8_STAGE(PG8_SB(0, 0), b2, voffB); PG8_STAGE(PG8_SB(0, 1), b2 + hstep, voffB); PG8_STAGE(PG8_SA(0, 0), a2, voffA);
;             PG8_WAIT_V(8); PG8_WAIT_L(0); PG8_BAR; PG8_MMA2(1); PG8_BAR; PG8_SCHED;
.Ldf_skipA_7:
	ds_read_b128 v[140:143], v161
	ds_read_b128 v[144:147], v161 offset:1024
	ds_read_b128 v[148:151], v161 offset:2048
	ds_read_b128 v[152:155], v161 offset:3072
	ds_read_b128 v[164:167], v162
	ds_read_b128 v[168:171], v162 offset:1024
	ds_read_b128 v[172:175], v162 offset:2048
	ds_read_b128 v[176:179], v162 offset:3072
	s_add_u32 s36, s26, 0x100
	s_addc_u32 s37, s27, 0
	s_cmp_eq_u32 s65, 40
	s_cselect_b32 s41, s13, s37
	s_cselect_b32 s40, s12, s36
	s_cselect_b32 s39, s23, s9
	s_cselect_b32 s38, s22, s8
	v_lshl_add_u64 v[156:157], s[26:27], 0, v[134:135]
	s_add_i32 m0, s47, 0xc000
	ds_read_b128 v[180:183], v163
	ds_read_b128 v[184:187], v163 offset:1024
	ds_read_b128 v[188:191], v163 offset:2048
	ds_read_b128 v[192:195], v163 offset:3072
	ds_read_b128 v[196:199], v163 offset:4096
	ds_read_b128 v[212:215], v163 offset:5120
	ds_read_b128 v[216:219], v163 offset:6144
	ds_read_b128 v[220:223], v163 offset:7168
	global_load_lds_dwordx4 v[156:157], off
	s_add_i32 m0, s47, 0xe000
	v_lshl_add_u64 v[156:157], s[26:27], 0, v[132:133]
	global_load_lds_dwordx4 v[156:157], off
	s_waitcnt vmcnt(8)
	s_waitcnt lgkmcnt(0)
	s_barrier
	s_setprio 1
	s_waitcnt lgkmcnt(0)
	v_mfma_f32_16x16x32_bf16 v[124:127], v[140:143], v[180:183], v[124:127]
	v_mfma_f32_16x16x32_bf16 v[120:123], v[148:151], v[180:183], v[120:123]
	v_mfma_f32_16x16x32_bf16 v[108:111], v[140:143], v[188:191], v[108:111]
	v_mfma_f32_16x16x32_bf16 v[104:107], v[148:151], v[188:191], v[104:107]
	v_mfma_f32_16x16x32_bf16 v[92:95], v[140:143], v[196:199], v[92:95]
	v_mfma_f32_16x16x32_bf16 v[88:91], v[148:151], v[196:199], v[88:91]
	v_mfma_f32_16x16x32_bf16 v[76:79], v[140:143], v[216:219], v[76:79]
	v_mfma_f32_16x16x32_bf16 v[72:75], v[148:151], v[216:219], v[72:75]
	v_mfma_f32_16x16x32_bf16 v[124:127], v[144:147], v[184:187], v[124:127]
	v_mfma_f32_16x16x32_bf16 v[120:123], v[152:155], v[184:187], v[120:123]
	v_mfma_f32_16x16x32_bf16 v[108:111], v[144:147], v[192:195], v[108:111]
	v_mfma_f32_16x16x32_bf16 v[104:107], v[152:155], v[192:195], v[104:107]
	v_mfma_f32_16x16x32_bf16 v[92:95], v[144:147], v[212:215], v[92:95]
	v_mfma_f32_16x16x32_bf16 v[88:91], v[152:155], v[212:215], v[88:91]
	v_mfma_f32_16x16x32_bf16 v[76:79], v[144:147], v[220:223], v[76:79]
	v_mfma_f32_16x16x32_bf16 v[72:75], v[152:155], v[220:223], v[72:75]
	s_setprio 0
	s_setprio 1
	v_mfma_f32_16x16x32_bf16 v[116:119], v[164:167], v[180:183], v[116:119]
	v_mfma_f32_16x16x32_bf16 v[112:115], v[172:175], v[180:183], v[112:115]
	v_mfma_f32_16x16x32_bf16 v[100:103], v[164:167], v[188:191], v[100:103]
	v_mfma_f32_16x16x32_bf16 v[96:99], v[172:175], v[188:191], v[96:99]
	v_mfma_f32_16x16x32_bf16 v[84:87], v[164:167], v[196:199], v[84:87]
	v_mfma_f32_16x16x32_bf16 v[80:83], v[172:175], v[196:199], v[80:83]
	v_mfma_f32_16x16x32_bf16 v[68:71], v[164:167], v[216:219], v[68:71]
	v_mfma_f32_16x16x32_bf16 v[64:67], v[172:175], v[216:219], v[64:67]
	v_mfma_f32_16x16x32_bf16 v[116:119], v[168:171], v[184:187], v[116:119]
	v_mfma_f32_16x16x32_bf16 v[112:115], v[176:179], v[184:187], v[112:115]
	v_mfma_f32_16x16x32_bf16 v[100:103], v[168:171], v[192:195], v[100:103]
	v_mfma_f32_16x16x32_bf16 v[96:99], v[176:179], v[192:195], v[96:99]
	v_mfma_f32_16x16x32_bf16 v[84:87], v[168:171], v[212:215], v[84:87]
	v_mfma_f32_16x16x32_bf16 v[80:83], v[176:179], v[212:215], v[80:83]
	v_mfma_f32_16x16x32_bf16 v[68:71], v[168:171], v[220:223], v[68:71]
	v_mfma_f32_16x16x32_bf16 v[64:67], v[176:179], v[220:223], v[64:67]
	s_setprio 0
	s_barrier
	s_add_i32 s26, s3, s46
	v_lshl_add_u64 v[156:157], s[38:39], 0, v[128:129]
	s_mov_b32 m0, s26
	ds_read_b128 v[180:183], v163 offset:16384
	ds_read_b128 v[184:187], v163 offset:17408
	ds_read_b128 v[188:191], v163 offset:18432
	ds_read_b128 v[192:195], v163 offset:19456
	ds_read_b128 v[196:199], v163 offset:20480
	ds_read_b128 v[212:215], v163 offset:21504
	ds_read_b128 v[216:219], v163 offset:22528
	ds_read_b128 v[220:223], v163 offset:23552
	global_load_lds_dwordx4 v[156:157], off
	s_add_i32 m0, s26, 0x2000
	s_add_u32 s26, s38, 0xb0000
	v_lshl_add_u64 v[224:225], s[38:39], 0, v[130:131]
	s_addc_u32 s27, s39, 0
	s_add_i32 s34, s61, s46
	global_load_lds_dwordx4 v[224:225], off
	v_lshl_add_u64 v[226:227], s[26:27], 0, v[128:129]
	s_mov_b32 m0, s34
	v_lshl_add_u64 v[228:229], s[40:41], 0, v[130:131]
	global_load_lds_dwordx4 v[226:227], off
	s_add_i32 m0, s34, 0x2000
	v_lshl_add_u64 v[226:227], s[26:27], 0, v[130:131]
	global_load_lds_dwordx4 v[226:227], off
	s_mov_b32 m0, s47
	v_lshl_add_u64 v[226:227], s[40:41], 0, v[128:129]
	global_load_lds_dwordx4 v[226:227], off
	s_nop 0
	s_waitcnt vmcnt(7)
	s_waitcnt lgkmcnt(0)
	s_barrier
; #define PG8_STAGE(bufoff, gbase, voff) do { _Pragma("unroll") for (int _i = 0; _i < 2; ++_i) \
;         __builtin_amdgcn_global_load_lds((const unsigned*)((const char*)(gbase) + (voff)[_i]), (PG8_LAS unsigned*)(lds + (bufoff) + ldsw + _i * 8192), 16, 0, 0); } while (0)
; #define PG8_LDA(dst, b, h) do { _Pragma("unroll") for (int m = 0; m < 4; ++m) _Pragma("unroll") for (int k = 0; k < 2; ++k) dst[m][k] = *(const PG8_LAS bf16x8*)(lds + PG8_SA(b, h) + aoff + m * 2048 + k * 1024); } while (0)
; #define PG8_LDB(dst, b, h) do { _Pragma("unroll") for (int n = 0; n < 2; ++n) _Pragma("unroll") for (int k = 0; k < 2; ++k) dst[n][k] = *(const PG8_LAS bf16x8*)(lds + PG8_SB(b, h) + boff + n * 2048 + k * 1024); } while (0)
; #define PG8_WAIT_V(n) asm volatile("s_waitcnt vmcnt(" #n ")" ::: "memory")
; #define PG8_WAIT_L(n) asm volatile("s_waitcnt lgkmcnt(" #n ")" ::: "memory")
; #define PG8_BAR __builtin_amdgcn_s_barrier()
; #define PG8_SCHED __builtin_amdgcn_sched_barrier(0)
; #define PG8_MMA2(ai) PG8_MMA(ai, 0, At, B0)
; #define PG8_MMA2(ai) PG8_MMA(ai, 1, At, B1)
; #define PG8_MMA2(ai) do { PG8_MMA(ai, 0, At, B0); PG8_MMA(ai, 1, At, B1); } while (0)
;     ...
;             PG8_WAIT_V(8); PG8_WAIT_L(0); PG8_BAR; PG8_MMA2(1); PG8_BAR; PG8_SCHED;
;             PG8_LDB(B0, 1, 0); PG8_LDB(B1, 1, 1); PG8_SCHED; PG8_LDA(At, 1, 0); PG8_STAGE(PG8_SA(0, 1), a2 + hstep, voffA);
;             PG8_WAIT_V(8); PG8_WAIT_L(0); PG8_BAR; PG8_MMA2(0); PG8_BAR; PG8_SCHED;
;             PG8_LDA(At, 1, 1); PG8_STAGE(PG8_SB(1, 0), b3, voffB); PG8_STAGE(PG8_SB(1, 1), b3 + hstep, voffB); PG8_STAGE(PG8_SA(1, 0), a3, voffA);
	s_setprio 1
	s_waitcnt lgkmcnt(0)
	v_mfma_f32_16x16x32_bf16 v[60:63], v[140:143], v[180:183], v[60:63]
	v_mfma_f32_16x16x32_bf16 v[56:59], v[148:151], v[180:183], v[56:59]
	v_mfma_f32_16x16x32_bf16 v[44:47], v[140:143], v[188:191], v[44:47]
	v_mfma_f32_16x16x32_bf16 v[40:43], v[148:151], v[188:191], v[40:43]
	v_mfma_f32_16x16x32_bf16 v[28:31], v[140:143], v[196:199], v[28:31]
	v_mfma_f32_16x16x32_bf16 v[24:27], v[148:151], v[196:199], v[24:27]
	v_mfma_f32_16x16x32_bf16 v[12:15], v[140:143], v[216:219], v[12:15]
	v_mfma_f32_16x16x32_bf16 v[8:11], v[148:151], v[216:219], v[8:11]
	v_mfma_f32_16x16x32_bf16 v[60:63], v[144:147], v[184:187], v[60:63]
	v_mfma_f32_16x16x32_bf16 v[56:59], v[152:155], v[184:187], v[56:59]
	v_mfma_f32_16x16x32_bf16 v[44:47], v[144:147], v[192:195], v[44:47]
	v_mfma_f32_16x16x32_bf16 v[40:43], v[152:155], v[192:195], v[40:43]
	v_mfma_f32_16x16x32_bf16 v[28:31], v[144:147], v[212:215], v[28:31]
	v_mfma_f32_16x16x32_bf16 v[24:27], v[152:155], v[212:215], v[24:27]
	v_mfma_f32_16x16x32_bf16 v[12:15], v[144:147], v[220:223], v[12:15]
	v_mfma_f32_16x16x32_bf16 v[8:11], v[152:155], v[220:223], v[8:11]
	s_setprio 0
	s_setprio 1
	v_mfma_f32_16x16x32_bf16 v[52:55], v[164:167], v[180:183], v[52:55]
	v_mfma_f32_16x16x32_bf16 v[48:51], v[172:175], v[180:183], v[48:51]
	v_mfma_f32_16x16x32_bf16 v[36:39], v[164:167], v[188:191], v[36:39]
	v_mfma_f32_16x16x32_bf16 v[32:35], v[172:175], v[188:191], v[32:35]
	v_mfma_f32_16x16x32_bf16 v[20:23], v[164:167], v[196:199], v[20:23]
	v_mfma_f32_16x16x32_bf16 v[16:19], v[172:175], v[196:199], v[16:19]
	v_mfma_f32_16x16x32_bf16 v[4:7], v[164:167], v[216:219], v[4:7]
	v_mfma_f32_16x16x32_bf16 v[0:3], v[172:175], v[216:219], v[0:3]
	v_mfma_f32_16x16x32_bf16 v[52:55], v[168:171], v[184:187], v[52:55]
	v_mfma_f32_16x16x32_bf16 v[48:51], v[176:179], v[184:187], v[48:51]
	v_mfma_f32_16x16x32_bf16 v[36:39], v[168:171], v[192:195], v[36:39]
	v_mfma_f32_16x16x32_bf16 v[32:35], v[176:179], v[192:195], v[32:35]
	v_mfma_f32_16x16x32_bf16 v[20:23], v[168:171], v[212:215], v[20:23]
	v_mfma_f32_16x16x32_bf16 v[16:19], v[176:179], v[212:215], v[16:19]
	v_mfma_f32_16x16x32_bf16 v[4:7], v[168:171], v[220:223], v[4:7]
	v_mfma_f32_16x16x32_bf16 v[0:3], v[176:179], v[220:223], v[0:3]
	s_setprio 0
	s_barrier
	s_add_i32 s34, 0, 0x18000
	s_add_i32 s35, 0, 0x1c000
	v_add_u32_e32 v152, s34, v159
	v_add_u32_e32 v176, s35, v159
	ds_read_b128 v[140:143], v152
	ds_read_b128 v[144:147], v152 offset:1024
	ds_read_b128 v[148:151], v152 offset:2048
	ds_read_b128 v[152:155], v152 offset:3072
	ds_read_b128 v[164:167], v176
	ds_read_b128 v[168:171], v176 offset:1024
	ds_read_b128 v[172:175], v176 offset:2048
	ds_read_b128 v[176:179], v176 offset:3072
	s_add_u32 s26, s40, 0xb0000
	s_addc_u32 s27, s41, 0
	s_mov_b32 m0, s48
	s_nop 0
	global_load_lds_dwordx4 v[228:229], off
	s_mov_b32 m0, s49
	v_lshl_add_u64 v[230:231], s[26:27], 0, v[128:129]
	ds_read_b128 v[180:183], v163 offset:32768
	ds_read_b128 v[184:187], v163 offset:33792
	ds_read_b128 v[188:191], v163 offset:34816
	ds_read_b128 v[192:195], v163 offset:35840
	ds_read_b128 v[196:199], v163 offset:36864
	ds_read_b128 v[212:215], v163 offset:37888
	ds_read_b128 v[216:219], v163 offset:38912
	ds_read_b128 v[220:223], v163 offset:39936
	global_load_lds_dwordx4 v[230:231], off
	s_mov_b32 m0, s50
	v_lshl_add_u64 v[230:231], s[26:27], 0, v[130:131]
	global_load_lds_dwordx4 v[230:231], off
	s_waitcnt vmcnt(8)
	s_waitcnt lgkmcnt(0)
	s_barrier
	s_setprio 1
	s_waitcnt lgkmcnt(0)
	v_mfma_f32_16x16x32_bf16 v[124:127], v[140:143], v[180:183], v[124:127]
	v_mfma_f32_16x16x32_bf16 v[120:123], v[148:151], v[180:183], v[120:123]
	v_mfma_f32_16x16x32_bf16 v[108:111], v[140:143], v[188:191], v[108:111]
	v_mfma_f32_16x16x32_bf16 v[104:107], v[148:151], v[188:191], v[104:107]
	v_mfma_f32_16x16x32_bf16 v[92:95], v[140:143], v[196:199], v[92:95]
	v_mfma_f32_16x16x32_bf16 v[88:91], v[148:151], v[196:199], v[88:91]
	v_mfma_f32_16x16x32_bf16 v[76:79], v[140:143], v[216:219], v[76:79]
	v_mfma_f32_16x16x32_bf16 v[72:75], v[148:151], v[216:219], v[72:75]
	v_mfma_f32_16x16x32_bf16 v[124:127], v[144:147], v[184:187], v[124:127]
	v_mfma_f32_16x16x32_bf16 v[120:123], v[152:155], v[184:187], v[120:123]
	v_mfma_f32_16x16x32_bf16 v[108:111], v[144:147], v[192:195], v[108:111]
	v_mfma_f32_16x16x32_bf16 v[104:107], v[152:155], v[192:195], v[104:107]
	v_mfma_f32_16x16x32_bf16 v[92:95], v[144:147], v[212:215], v[92:95]
	v_mfma_f32_16x16x32_bf16 v[88:91], v[152:155], v[212:215], v[88:91]
	v_mfma_f32_16x16x32_bf16 v[76:79], v[144:147], v[220:223], v[76:79]
	v_mfma_f32_16x16x32_bf16 v[72:75], v[152:155], v[220:223], v[72:75]
	s_setprio 0
	s_setprio 1
	v_mfma_f32_16x16x32_bf16 v[116:119], v[164:167], v[180:183], v[116:119]
	v_mfma_f32_16x16x32_bf16 v[112:115], v[172:175], v[180:183], v[112:115]
	v_mfma_f32_16x16x32_bf16 v[100:103], v[164:167], v[188:191], v[100:103]
	v_mfma_f32_16x16x32_bf16 v[96:99], v[172:175], v[188:191], v[96:99]
	v_mfma_f32_16x16x32_bf16 v[84:87], v[164:167], v[196:199], v[84:87]
	v_mfma_f32_16x16x32_bf16 v[80:83], v[172:175], v[196:199], v[80:83]
	v_mfma_f32_16x16x32_bf16 v[68:71], v[164:167], v[216:219], v[68:71]
	v_mfma_f32_16x16x32_bf16 v[64:67], v[172:175], v[216:219], v[64:67]
	v_mfma_f32_16x16x32_bf16 v[116:119], v[168:171], v[184:187], v[116:119]
	v_mfma_f32_16x16x32_bf16 v[112:115], v[176:179], v[184:187], v[112:115]
	v_mfma_f32_16x16x32_bf16 v[100:103], v[168:171], v[192:195], v[100:103]
	v_mfma_f32_16x16x32_bf16 v[96:99], v[176:179], v[192:195], v[96:99]
	v_mfma_f32_16x16x32_bf16 v[84:87], v[168:171], v[212:215], v[84:87]
	v_mfma_f32_16x16x32_bf16 v[80:83], v[176:179], v[212:215], v[80:83]
	v_mfma_f32_16x16x32_bf16 v[68:71], v[168:171], v[220:223], v[68:71]
	v_mfma_f32_16x16x32_bf16 v[64:67], v[176:179], v[220:223], v[64:67]
	s_setprio 0
	s_barrier
	s_add_i32 s26, s34, s46
	v_lshl_add_u64 v[156:157], v[156:157], 0, s[18:19]
	s_mov_b32 m0, s26
	ds_read_b128 v[180:183], v163 offset:49152
	ds_read_b128 v[184:187], v163 offset:50176
	ds_read_b128 v[188:191], v163 offset:51200
	ds_read_b128 v[192:195], v163 offset:52224
	ds_read_b128 v[196:199], v163 offset:53248
	ds_read_b128 v[212:215], v163 offset:54272
	ds_read_b128 v[216:219], v163 offset:55296
	ds_read_b128 v[220:223], v163 offset:56320
	global_load_lds_dwordx4 v[156:157], off
	s_add_i32 m0, s26, 0x2000
	s_add_u32 s26, s38, 0xb0080
	v_lshl_add_u64 v[156:157], v[224:225], 0, s[18:19]
	s_addc_u32 s27, s39, 0
	s_add_i32 s34, s35, s46
	global_load_lds_dwordx4 v[156:157], off
	s_mov_b32 m0, s34
	v_lshl_add_u64 v[156:157], s[26:27], 0, v[128:129]
	global_load_lds_dwordx4 v[156:157], off
	s_add_i32 m0, s34, 0x2000
	v_lshl_add_u64 v[156:157], s[26:27], 0, v[130:131]
	global_load_lds_dwordx4 v[156:157], off
	s_mov_b32 m0, s56
	v_lshl_add_u64 v[156:157], v[226:227], 0, s[18:19]
	global_load_lds_dwordx4 v[156:157], off
	v_lshl_add_u64 v[156:157], v[228:229], 0, s[18:19]
	s_nop 0
	s_cmp_lg_u32 s65, 40
	s_cbranch_scc1 .Ldf_skipD_7
	s_mov_b32 m0, s57
	s_nop 0
	global_load_lds_dwordx4 v[156:157], off

; #define PG8_STAGE(bufoff, gbase, voff) do { _Pragma("unroll") for (int _i = 0; _i < 2; ++_i) \
;         __builtin_amdgcn_global_load_lds((const unsigned*)((const char*)(gbase) + (voff)[_i]), (PG8_LAS unsigned*)(lds + (bufoff) + ldsw + _i * 8192), 16, 0, 0); } while (0)
; #define PG8_LDA(dst, b, h) do { _Pragma("unroll") for (int m = 0; m < 4; ++m) _Pragma("unroll") for (int k = 0; k < 2; ++k) dst[m][k] = *(const PG8_LAS bf16x8*)(lds + PG8_SA(b, h) + aoff + m * 2048 + k * 1024); } while (0)
; #define PG8_LDB(dst, b, h) do { _Pragma("unroll") for (int n = 0; n < 2; ++n) _Pragma("unroll") for (int k = 0; k < 2; ++k) dst[n][k] = *(const PG8_LAS bf16x8*)(lds + PG8_SB(b, h) + boff + n * 2048 + k * 1024); } while (0)
; #define PG8_WAIT_V(n) asm volatile("s_waitcnt vmcnt(" #n ")" ::: "memory")
; #define PG8_WAIT_L(n) asm volatile("s_waitcnt lgkmcnt(" #n ")" ::: "memory")
; #define PG8_BAR __builtin_amdgcn_s_barrier()
; #define PG8_SCHED __builtin_amdgcn_sched_barrier(0)
; #define PG8_MMA2(ai) PG8_MMA(ai, 0, At, B0)
; #define PG8_MMA2(ai) PG8_MMA(ai, 1, At, B1)
; #define PG8_MMA2(ai) do { PG8_MMA(ai, 0, At, B0); PG8_MMA(ai, 1, At, B1); } while (0)
;     ...
;             PG8_LDB(B0, 0, 0); PG8_LDB(B1, 0, 1); PG8_SCHED; PG8_LDA(At, 0, 0); PG8_STAGE(PG8_SA(1, 1), a1 + hstep, voffA);
;             PG8_WAIT_V(8); PG8_WAIT_L(0); PG8_BAR; PG8_MMA2(0); PG8_BAR; PG8_SCHED;
;             PG8_LDA(At, 0, 1); PG8_STAGE(PG8_SB(0, 0), b2, voffB); PG8_STAGE(PG8_SB(0, 1), b2 + hstep, voffB); PG8_STAGE(PG8_SA(0, 0), a2, voffA);
;             PG8_WAIT_V(8); PG8_WAIT_L(0); PG8_BAR; PG8_MMA2(1); PG8_BAR; PG8_SCHED;
.Ldf_skipA_8:
	s_waitcnt lgkmcnt(0)
	ds_read_b128 v[128:131], v182
	ds_read_b128 v[132:135], v182 offset:1024
	ds_read_b128 v[136:139], v182 offset:2048
	ds_read_b128 v[140:143], v182 offset:3072
	ds_read_b128 v[168:171], v183
	ds_read_b128 v[188:191], v183 offset:1024
	ds_read_b128 v[192:195], v183 offset:2048
	ds_read_b128 v[196:199], v183 offset:3072
	s_add_u32 s34, s14, 0xfffc0080
	s_addc_u32 s35, s15, -1
	s_cmp_eq_u32 s67, 12
	s_cselect_b32 s71, s8, s35
	s_cselect_b32 s70, s9, s34
	s_cselect_b32 s69, s17, s61
	s_cselect_b32 s68, s20, s59
	v_lshl_add_u64 v[172:173], s[14:15], 0, v[162:163]
	s_add_i32 m0, s76, 0xc000
	ds_read_b128 v[212:215], v184
	ds_read_b128 v[216:219], v184 offset:1024
	ds_read_b128 v[220:223], v184 offset:2048
	ds_read_b128 v[224:227], v184 offset:3072
	ds_read_b128 v[228:231], v184 offset:4096
	ds_read_b128 v[232:235], v184 offset:5120
	ds_read_b128 v[236:239], v184 offset:6144
	ds_read_b128 v[240:243], v184 offset:7168
	global_load_lds_dwordx4 v[172:173], off
	s_add_i32 m0, s76, 0xe000
	v_lshl_add_u64 v[172:173], s[14:15], 0, v[160:161]
	global_load_lds_dwordx4 v[172:173], off
	s_waitcnt vmcnt(8)
	s_waitcnt lgkmcnt(0)
	s_barrier
	s_setprio 1
	s_waitcnt lgkmcnt(0)
	v_mfma_f32_16x16x32_bf16 v[124:127], v[128:131], v[212:215], v[124:127]
	v_mfma_f32_16x16x32_bf16 v[120:123], v[136:139], v[212:215], v[120:123]
	v_mfma_f32_16x16x32_bf16 v[108:111], v[128:131], v[220:223], v[108:111]
	v_mfma_f32_16x16x32_bf16 v[104:107], v[136:139], v[220:223], v[104:107]
	v_mfma_f32_16x16x32_bf16 v[92:95], v[128:131], v[228:231], v[92:95]
	v_mfma_f32_16x16x32_bf16 v[88:91], v[136:139], v[228:231], v[88:91]
	v_mfma_f32_16x16x32_bf16 v[76:79], v[128:131], v[236:239], v[76:79]
	v_mfma_f32_16x16x32_bf16 v[72:75], v[136:139], v[236:239], v[72:75]
	v_mfma_f32_16x16x32_bf16 v[124:127], v[132:135], v[216:219], v[124:127]
	v_mfma_f32_16x16x32_bf16 v[120:123], v[140:143], v[216:219], v[120:123]
	v_mfma_f32_16x16x32_bf16 v[108:111], v[132:135], v[224:227], v[108:111]
	v_mfma_f32_16x16x32_bf16 v[104:107], v[140:143], v[224:227], v[104:107]
	v_mfma_f32_16x16x32_bf16 v[92:95], v[132:135], v[232:235], v[92:95]
	v_mfma_f32_16x16x32_bf16 v[88:91], v[140:143], v[232:235], v[88:91]
	v_mfma_f32_16x16x32_bf16 v[76:79], v[132:135], v[240:243], v[76:79]
	v_mfma_f32_16x16x32_bf16 v[72:75], v[140:143], v[240:243], v[72:75]
	s_setprio 0
	s_setprio 1
	v_mfma_f32_16x16x32_bf16 v[116:119], v[168:171], v[212:215], v[116:119]
	v_mfma_f32_16x16x32_bf16 v[112:115], v[192:195], v[212:215], v[112:115]
	v_mfma_f32_16x16x32_bf16 v[100:103], v[168:171], v[220:223], v[100:103]
	v_mfma_f32_16x16x32_bf16 v[96:99], v[192:195], v[220:223], v[96:99]
	v_mfma_f32_16x16x32_bf16 v[84:87], v[168:171], v[228:231], v[84:87]
	v_mfma_f32_16x16x32_bf16 v[80:83], v[192:195], v[228:231], v[80:83]
	v_mfma_f32_16x16x32_bf16 v[68:71], v[168:171], v[236:239], v[68:71]
	v_mfma_f32_16x16x32_bf16 v[64:67], v[192:195], v[236:239], v[64:67]
	v_mfma_f32_16x16x32_bf16 v[116:119], v[188:191], v[216:219], v[116:119]
	v_mfma_f32_16x16x32_bf16 v[112:115], v[196:199], v[216:219], v[112:115]
	v_mfma_f32_16x16x32_bf16 v[100:103], v[188:191], v[224:227], v[100:103]
	v_mfma_f32_16x16x32_bf16 v[96:99], v[196:199], v[224:227], v[96:99]
	v_mfma_f32_16x16x32_bf16 v[84:87], v[188:191], v[232:235], v[84:87]
	v_mfma_f32_16x16x32_bf16 v[80:83], v[196:199], v[232:235], v[80:83]
	v_mfma_f32_16x16x32_bf16 v[68:71], v[188:191], v[240:243], v[68:71]
	v_mfma_f32_16x16x32_bf16 v[64:67], v[196:199], v[240:243], v[64:67]
	s_setprio 0
	s_barrier
	s_add_i32 s34, s3, s75
	v_lshl_add_u64 v[172:173], s[68:69], 0, v[146:147]
	s_mov_b32 m0, s34
	ds_read_b128 v[212:215], v184 offset:16384
	ds_read_b128 v[216:219], v184 offset:17408
	ds_read_b128 v[220:223], v184 offset:18432
	ds_read_b128 v[224:227], v184 offset:19456
	ds_read_b128 v[228:231], v184 offset:20480
	ds_read_b128 v[232:235], v184 offset:21504
	ds_read_b128 v[236:239], v184 offset:22528
	ds_read_b128 v[240:243], v184 offset:23552
	global_load_lds_dwordx4 v[172:173], off
	s_add_i32 m0, s34, 0x2000
	s_add_u32 s34, s68, 0x40000
	v_lshl_add_u64 v[244:245], s[68:69], 0, v[150:151]
	s_addc_u32 s35, s69, 0
	s_add_i32 s82, s90, s75
	global_load_lds_dwordx4 v[244:245], off
	v_lshl_add_u64 v[246:247], s[34:35], 0, v[146:147]
	s_mov_b32 m0, s82
	v_lshl_add_u64 v[248:249], s[70:71], 0, v[148:149]
	global_load_lds_dwordx4 v[246:247], off
	s_add_i32 m0, s82, 0x2000
	v_lshl_add_u64 v[246:247], s[34:35], 0, v[150:151]
	global_load_lds_dwordx4 v[246:247], off
	s_mov_b32 m0, s76
	v_lshl_add_u64 v[246:247], s[70:71], 0, v[144:145]
	global_load_lds_dwordx4 v[246:247], off
	s_nop 0
	s_waitcnt vmcnt(7)
	s_waitcnt lgkmcnt(0)
	s_barrier
; #define PG8_STAGE(bufoff, gbase, voff) do { _Pragma("unroll") for (int _i = 0; _i < 2; ++_i) \
;         __builtin_amdgcn_global_load_lds((const unsigned*)((const char*)(gbase) + (voff)[_i]), (PG8_LAS unsigned*)(lds + (bufoff) + ldsw + _i * 8192), 16, 0, 0); } while (0)
; #define PG8_LDA(dst, b, h) do { _Pragma("unroll") for (int m = 0; m < 4; ++m) _Pragma("unroll") for (int k = 0; k < 2; ++k) dst[m][k] = *(const PG8_LAS bf16x8*)(lds + PG8_SA(b, h) + aoff + m * 2048 + k * 1024); } while (0)
; #define PG8_LDB(dst, b, h) do { _Pragma("unroll") for (int n = 0; n < 2; ++n) _Pragma("unroll") for (int k = 0; k < 2; ++k) dst[n][k] = *(const PG8_LAS bf16x8*)(lds + PG8_SB(b, h) + boff + n * 2048 + k * 1024); } while (0)
; #define PG8_WAIT_V(n) asm volatile("s_waitcnt vmcnt(" #n ")" ::: "memory")
; #define PG8_WAIT_L(n) asm volatile("s_waitcnt lgkmcnt(" #n ")" ::: "memory")
; #define PG8_BAR __builtin_amdgcn_s_barrier()
; #define PG8_SCHED __builtin_amdgcn_sched_barrier(0)
; #define PG8_MMA2(ai) PG8_MMA(ai, 0, At, B0)
; #define PG8_MMA2(ai) PG8_MMA(ai, 1, At, B1)
; #define PG8_MMA2(ai) do { PG8_MMA(ai, 0, At, B0); PG8_MMA(ai, 1, At, B1); } while (0)
;     ...
;             PG8_WAIT_V(8); PG8_WAIT_L(0); PG8_BAR; PG8_MMA2(1); PG8_BAR; PG8_SCHED;
;             PG8_LDB(B0, 1, 0); PG8_LDB(B1, 1, 1); PG8_SCHED; PG8_LDA(At, 1, 0); PG8_STAGE(PG8_SA(0, 1), a2 + hstep, voffA);
;             PG8_WAIT_V(8); PG8_WAIT_L(0); PG8_BAR; PG8_MMA2(0); PG8_BAR; PG8_SCHED;
;             PG8_LDA(At, 1, 1); PG8_STAGE(PG8_SB(1, 0), b3, voffB); PG8_STAGE(PG8_SB(1, 1), b3 + hstep, voffB); PG8_STAGE(PG8_SA(1, 0), a3, voffA);
	s_setprio 1
	s_waitcnt lgkmcnt(0)
	v_mfma_f32_16x16x32_bf16 v[60:63], v[128:131], v[212:215], v[60:63]
	v_mfma_f32_16x16x32_bf16 v[56:59], v[136:139], v[212:215], v[56:59]
	v_mfma_f32_16x16x32_bf16 v[44:47], v[128:131], v[220:223], v[44:47]
	v_mfma_f32_16x16x32_bf16 v[40:43], v[136:139], v[220:223], v[40:43]
	v_mfma_f32_16x16x32_bf16 v[28:31], v[128:131], v[228:231], v[28:31]
	v_mfma_f32_16x16x32_bf16 v[24:27], v[136:139], v[228:231], v[24:27]
	v_mfma_f32_16x16x32_bf16 v[12:15], v[128:131], v[236:239], v[12:15]
	v_mfma_f32_16x16x32_bf16 v[8:11], v[136:139], v[236:239], v[8:11]
	v_mfma_f32_16x16x32_bf16 v[60:63], v[132:135], v[216:219], v[60:63]
	v_mfma_f32_16x16x32_bf16 v[56:59], v[140:143], v[216:219], v[56:59]
	v_mfma_f32_16x16x32_bf16 v[44:47], v[132:135], v[224:227], v[44:47]
	v_mfma_f32_16x16x32_bf16 v[40:43], v[140:143], v[224:227], v[40:43]
	v_mfma_f32_16x16x32_bf16 v[28:31], v[132:135], v[232:235], v[28:31]
	v_mfma_f32_16x16x32_bf16 v[24:27], v[140:143], v[232:235], v[24:27]
	v_mfma_f32_16x16x32_bf16 v[12:15], v[132:135], v[240:243], v[12:15]
	v_mfma_f32_16x16x32_bf16 v[8:11], v[140:143], v[240:243], v[8:11]
	s_setprio 0
	s_setprio 1
	v_mfma_f32_16x16x32_bf16 v[52:55], v[168:171], v[212:215], v[52:55]
	v_mfma_f32_16x16x32_bf16 v[48:51], v[192:195], v[212:215], v[48:51]
	v_mfma_f32_16x16x32_bf16 v[36:39], v[168:171], v[220:223], v[36:39]
	v_mfma_f32_16x16x32_bf16 v[32:35], v[192:195], v[220:223], v[32:35]
	v_mfma_f32_16x16x32_bf16 v[20:23], v[168:171], v[228:231], v[20:23]
	v_mfma_f32_16x16x32_bf16 v[16:19], v[192:195], v[228:231], v[16:19]
	v_mfma_f32_16x16x32_bf16 v[4:7], v[168:171], v[236:239], v[4:7]
	v_mfma_f32_16x16x32_bf16 v[0:3], v[192:195], v[236:239], v[0:3]
	v_mfma_f32_16x16x32_bf16 v[52:55], v[188:191], v[216:219], v[52:55]
	v_mfma_f32_16x16x32_bf16 v[48:51], v[196:199], v[216:219], v[48:51]
	v_mfma_f32_16x16x32_bf16 v[36:39], v[188:191], v[224:227], v[36:39]
	v_mfma_f32_16x16x32_bf16 v[32:35], v[196:199], v[224:227], v[32:35]
	v_mfma_f32_16x16x32_bf16 v[20:23], v[188:191], v[232:235], v[20:23]
	v_mfma_f32_16x16x32_bf16 v[16:19], v[196:199], v[232:235], v[16:19]
	v_mfma_f32_16x16x32_bf16 v[4:7], v[188:191], v[240:243], v[4:7]
	v_mfma_f32_16x16x32_bf16 v[0:3], v[196:199], v[240:243], v[0:3]
	s_setprio 0
	s_barrier
	s_add_i32 s82, 0, 0x18000
	s_add_i32 s83, 0, 0x1c000
	v_add_u32_e32 v140, s82, v174
	v_add_u32_e32 v187, s83, v174
	ds_read_b128 v[128:131], v140
	ds_read_b128 v[132:135], v140 offset:1024
	ds_read_b128 v[136:139], v140 offset:2048
	ds_read_b128 v[140:143], v140 offset:3072
	ds_read_b128 v[168:171], v187
	ds_read_b128 v[188:191], v187 offset:1024
	ds_read_b128 v[192:195], v187 offset:2048
	ds_read_b128 v[196:199], v187 offset:3072
	s_add_u32 s34, s70, 0x40000
	s_addc_u32 s35, s71, 0
	s_mov_b32 m0, s77
	s_nop 0
	global_load_lds_dwordx4 v[248:249], off
	s_mov_b32 m0, s78
	v_lshl_add_u64 v[250:251], s[34:35], 0, v[144:145]
	ds_read_b128 v[212:215], v184 offset:32768
	ds_read_b128 v[216:219], v184 offset:33792
	ds_read_b128 v[220:223], v184 offset:34816
	ds_read_b128 v[224:227], v184 offset:35840
	ds_read_b128 v[228:231], v184 offset:36864
	ds_read_b128 v[232:235], v184 offset:37888
	ds_read_b128 v[236:239], v184 offset:38912
	ds_read_b128 v[240:243], v184 offset:39936
	global_load_lds_dwordx4 v[250:251], off
	s_mov_b32 m0, s79
	v_lshl_add_u64 v[250:251], s[34:35], 0, v[148:149]
	global_load_lds_dwordx4 v[250:251], off
	s_waitcnt vmcnt(8)
	s_waitcnt lgkmcnt(0)
	s_barrier
	s_setprio 1
	s_waitcnt lgkmcnt(0)
	v_mfma_f32_16x16x32_bf16 v[124:127], v[128:131], v[212:215], v[124:127]
	v_mfma_f32_16x16x32_bf16 v[120:123], v[136:139], v[212:215], v[120:123]
	v_mfma_f32_16x16x32_bf16 v[108:111], v[128:131], v[220:223], v[108:111]
	v_mfma_f32_16x16x32_bf16 v[104:107], v[136:139], v[220:223], v[104:107]
	v_mfma_f32_16x16x32_bf16 v[92:95], v[128:131], v[228:231], v[92:95]
	v_mfma_f32_16x16x32_bf16 v[88:91], v[136:139], v[228:231], v[88:91]
	v_mfma_f32_16x16x32_bf16 v[76:79], v[128:131], v[236:239], v[76:79]
	v_mfma_f32_16x16x32_bf16 v[72:75], v[136:139], v[236:239], v[72:75]
	v_mfma_f32_16x16x32_bf16 v[124:127], v[132:135], v[216:219], v[124:127]
	v_mfma_f32_16x16x32_bf16 v[120:123], v[140:143], v[216:219], v[120:123]
	v_mfma_f32_16x16x32_bf16 v[108:111], v[132:135], v[224:227], v[108:111]
	v_mfma_f32_16x16x32_bf16 v[104:107], v[140:143], v[224:227], v[104:107]
	v_mfma_f32_16x16x32_bf16 v[92:95], v[132:135], v[232:235], v[92:95]
	v_mfma_f32_16x16x32_bf16 v[88:91], v[140:143], v[232:235], v[88:91]
	v_mfma_f32_16x16x32_bf16 v[76:79], v[132:135], v[240:243], v[76:79]
	v_mfma_f32_16x16x32_bf16 v[72:75], v[140:143], v[240:243], v[72:75]
	s_setprio 0
	s_setprio 1
	v_mfma_f32_16x16x32_bf16 v[116:119], v[168:171], v[212:215], v[116:119]
	v_mfma_f32_16x16x32_bf16 v[112:115], v[192:195], v[212:215], v[112:115]
	v_mfma_f32_16x16x32_bf16 v[100:103], v[168:171], v[220:223], v[100:103]
	v_mfma_f32_16x16x32_bf16 v[96:99], v[192:195], v[220:223], v[96:99]
	v_mfma_f32_16x16x32_bf16 v[84:87], v[168:171], v[228:231], v[84:87]
	v_mfma_f32_16x16x32_bf16 v[80:83], v[192:195], v[228:231], v[80:83]
	v_mfma_f32_16x16x32_bf16 v[68:71], v[168:171], v[236:239], v[68:71]
	v_mfma_f32_16x16x32_bf16 v[64:67], v[192:195], v[236:239], v[64:67]
	v_mfma_f32_16x16x32_bf16 v[116:119], v[188:191], v[216:219], v[116:119]
	v_mfma_f32_16x16x32_bf16 v[112:115], v[196:199], v[216:219], v[112:115]
	v_mfma_f32_16x16x32_bf16 v[100:103], v[188:191], v[224:227], v[100:103]
	v_mfma_f32_16x16x32_bf16 v[96:99], v[196:199], v[224:227], v[96:99]
	v_mfma_f32_16x16x32_bf16 v[84:87], v[188:191], v[232:235], v[84:87]
	v_mfma_f32_16x16x32_bf16 v[80:83], v[196:199], v[232:235], v[80:83]
	v_mfma_f32_16x16x32_bf16 v[68:71], v[188:191], v[240:243], v[68:71]
	v_mfma_f32_16x16x32_bf16 v[64:67], v[196:199], v[240:243], v[64:67]
	s_setprio 0
	s_barrier
	s_add_i32 s34, s82, s75
	v_lshl_add_u64 v[172:173], v[172:173], 0, s[40:41]
	s_mov_b32 m0, s34
	ds_read_b128 v[212:215], v184 offset:49152
	ds_read_b128 v[216:219], v184 offset:50176
	ds_read_b128 v[220:223], v184 offset:51200
	ds_read_b128 v[224:227], v184 offset:52224
	ds_read_b128 v[228:231], v184 offset:53248
	ds_read_b128 v[232:235], v184 offset:54272
	ds_read_b128 v[236:239], v184 offset:55296
	ds_read_b128 v[240:243], v184 offset:56320
	global_load_lds_dwordx4 v[172:173], off
	s_add_i32 m0, s34, 0x2000
	s_add_u32 s34, s68, 0x40080
	v_lshl_add_u64 v[172:173], v[244:245], 0, s[40:41]
	s_addc_u32 s35, s69, 0
	s_add_i32 s68, s83, s75
	global_load_lds_dwordx4 v[172:173], off
	s_mov_b32 m0, s68
	v_lshl_add_u64 v[172:173], s[34:35], 0, v[146:147]
	global_load_lds_dwordx4 v[172:173], off
	s_add_i32 m0, s68, 0x2000
	v_lshl_add_u64 v[172:173], s[34:35], 0, v[150:151]
	global_load_lds_dwordx4 v[172:173], off
	s_mov_b32 m0, s85
	v_lshl_add_u64 v[172:173], v[246:247], 0, s[40:41]
	global_load_lds_dwordx4 v[172:173], off
	v_lshl_add_u64 v[172:173], v[248:249], 0, s[40:41]
	s_nop 0
	s_cmp_lg_u32 s67, 12
	s_cbranch_scc1 .Ldf_skipD_8
	s_mov_b32 m0, s86
	s_nop 0
	global_load_lds_dwordx4 v[172:173], off

; #define PG8_STAGE(bufoff, gbase, voff) do { _Pragma("unroll") for (int _i = 0; _i < 2; ++_i) \
;         __builtin_amdgcn_global_load_lds((const unsigned*)((const char*)(gbase) + (voff)[_i]), (PG8_LAS unsigned*)(lds + (bufoff) + ldsw + _i * 8192), 16, 0, 0); } while (0)
; #define PG8_LDA(dst, b, h) do { _Pragma("unroll") for (int m = 0; m < 4; ++m) _Pragma("unroll") for (int k = 0; k < 2; ++k) dst[m][k] = *(const PG8_LAS bf16x8*)(lds + PG8_SA(b, h) + aoff + m * 2048 + k * 1024); } while (0)
; #define PG8_LDB(dst, b, h) do { _Pragma("unroll") for (int n = 0; n < 2; ++n) _Pragma("unroll") for (int k = 0; k < 2; ++k) dst[n][k] = *(const PG8_LAS bf16x8*)(lds + PG8_SB(b, h) + boff + n * 2048 + k * 1024); } while (0)
; #define PG8_WAIT_V(n) asm volatile("s_waitcnt vmcnt(" #n ")" ::: "memory")
; #define PG8_WAIT_L(n) asm volatile("s_waitcnt lgkmcnt(" #n ")" ::: "memory")
; #define PG8_BAR __builtin_amdgcn_s_barrier()
; #define PG8_SCHED __builtin_amdgcn_sched_barrier(0)
; #define PG8_MMA2(ai) PG8_MMA(ai, 0, At, B0)
; #define PG8_MMA2(ai) PG8_MMA(ai, 1, At, B1)
; #define PG8_MMA2(ai) do { PG8_MMA(ai, 0, At, B0); PG8_MMA(ai, 1, At, B1); } while (0)
;     ...
;             PG8_LDB(B0, 0, 0); PG8_LDB(B1, 0, 1); PG8_SCHED; PG8_LDA(At, 0, 0); PG8_STAGE(PG8_SA(1, 1), a1 + hstep, voffA);
;             PG8_WAIT_V(8); PG8_WAIT_L(0); PG8_BAR; PG8_MMA2(0); PG8_BAR; PG8_SCHED;
;             PG8_LDA(At, 0, 1); PG8_STAGE(PG8_SB(0, 0), b2, voffB); PG8_STAGE(PG8_SB(0, 1), b2 + hstep, voffB); PG8_STAGE(PG8_SA(0, 0), a2, voffA);
;             PG8_WAIT_V(8); PG8_WAIT_L(0); PG8_BAR; PG8_MMA2(1); PG8_BAR; PG8_SCHED;
.Ldf_skipA_9:
	ds_read_b128 v[128:131], v161
	ds_read_b128 v[132:135], v161 offset:1024
	ds_read_b128 v[136:139], v161 offset:2048
	ds_read_b128 v[140:143], v161 offset:3072
	ds_read_b128 v[164:167], v162
	ds_read_b128 v[168:171], v162 offset:1024
	ds_read_b128 v[172:175], v162 offset:2048
	ds_read_b128 v[176:179], v162 offset:3072
	s_add_u32 s38, s36, 0x100
	s_addc_u32 s39, s37, 0
	s_cmp_eq_u32 s69, 12
	s_cselect_b32 s43, s19, s39
	s_cselect_b32 s42, s65, s38
	s_cselect_b32 s41, s17, s68
	s_cselect_b32 s40, s66, s67
	v_lshl_add_u64 v[156:157], s[36:37], 0, v[150:151]
	s_add_i32 m0, s27, 0xc000
	ds_read_b128 v[180:183], v163
	ds_read_b128 v[184:187], v163 offset:1024
	ds_read_b128 v[188:191], v163 offset:2048
	ds_read_b128 v[192:195], v163 offset:3072
	ds_read_b128 v[196:199], v163 offset:4096
	ds_read_b128 v[208:211], v163 offset:5120
	ds_read_b128 v[212:215], v163 offset:6144
	ds_read_b128 v[216:219], v163 offset:7168
	global_load_lds_dwordx4 v[156:157], off
	s_add_i32 m0, s27, 0xe000
	v_lshl_add_u64 v[156:157], s[36:37], 0, v[148:149]
	global_load_lds_dwordx4 v[156:157], off
	s_waitcnt vmcnt(8)
	s_waitcnt lgkmcnt(0)
	s_barrier
	s_setprio 1
	s_waitcnt lgkmcnt(0)
	v_mfma_f32_16x16x32_bf16 v[124:127], v[128:131], v[180:183], v[124:127]
	v_mfma_f32_16x16x32_bf16 v[120:123], v[136:139], v[180:183], v[120:123]
	v_mfma_f32_16x16x32_bf16 v[108:111], v[128:131], v[188:191], v[108:111]
	v_mfma_f32_16x16x32_bf16 v[104:107], v[136:139], v[188:191], v[104:107]
	v_mfma_f32_16x16x32_bf16 v[92:95], v[128:131], v[196:199], v[92:95]
	v_mfma_f32_16x16x32_bf16 v[88:91], v[136:139], v[196:199], v[88:91]
	v_mfma_f32_16x16x32_bf16 v[76:79], v[128:131], v[212:215], v[76:79]
	v_mfma_f32_16x16x32_bf16 v[72:75], v[136:139], v[212:215], v[72:75]
	v_mfma_f32_16x16x32_bf16 v[124:127], v[132:135], v[184:187], v[124:127]
	v_mfma_f32_16x16x32_bf16 v[120:123], v[140:143], v[184:187], v[120:123]
	v_mfma_f32_16x16x32_bf16 v[108:111], v[132:135], v[192:195], v[108:111]
	v_mfma_f32_16x16x32_bf16 v[104:107], v[140:143], v[192:195], v[104:107]
	v_mfma_f32_16x16x32_bf16 v[92:95], v[132:135], v[208:211], v[92:95]
	v_mfma_f32_16x16x32_bf16 v[88:91], v[140:143], v[208:211], v[88:91]
	v_mfma_f32_16x16x32_bf16 v[76:79], v[132:135], v[216:219], v[76:79]
	v_mfma_f32_16x16x32_bf16 v[72:75], v[140:143], v[216:219], v[72:75]
	s_setprio 0
	s_setprio 1
	v_mfma_f32_16x16x32_bf16 v[116:119], v[164:167], v[180:183], v[116:119]
	v_mfma_f32_16x16x32_bf16 v[112:115], v[172:175], v[180:183], v[112:115]
	v_mfma_f32_16x16x32_bf16 v[100:103], v[164:167], v[188:191], v[100:103]
	v_mfma_f32_16x16x32_bf16 v[96:99], v[172:175], v[188:191], v[96:99]
	v_mfma_f32_16x16x32_bf16 v[84:87], v[164:167], v[196:199], v[84:87]
	v_mfma_f32_16x16x32_bf16 v[80:83], v[172:175], v[196:199], v[80:83]
	v_mfma_f32_16x16x32_bf16 v[68:71], v[164:167], v[212:215], v[68:71]
	v_mfma_f32_16x16x32_bf16 v[64:67], v[172:175], v[212:215], v[64:67]
	v_mfma_f32_16x16x32_bf16 v[116:119], v[168:171], v[184:187], v[116:119]
	v_mfma_f32_16x16x32_bf16 v[112:115], v[176:179], v[184:187], v[112:115]
	v_mfma_f32_16x16x32_bf16 v[100:103], v[168:171], v[192:195], v[100:103]
	v_mfma_f32_16x16x32_bf16 v[96:99], v[176:179], v[192:195], v[96:99]
	v_mfma_f32_16x16x32_bf16 v[84:87], v[168:171], v[208:211], v[84:87]
	v_mfma_f32_16x16x32_bf16 v[80:83], v[176:179], v[208:211], v[80:83]
	v_mfma_f32_16x16x32_bf16 v[68:71], v[168:171], v[216:219], v[68:71]
	v_mfma_f32_16x16x32_bf16 v[64:67], v[176:179], v[216:219], v[64:67]
	s_setprio 0
	s_barrier
	s_add_i32 s34, s3, s48
	v_lshl_add_u64 v[156:157], s[40:41], 0, v[144:145]
	s_mov_b32 m0, s34
	ds_read_b128 v[180:183], v163 offset:16384
	ds_read_b128 v[184:187], v163 offset:17408
	ds_read_b128 v[188:191], v163 offset:18432
	ds_read_b128 v[192:195], v163 offset:19456
	ds_read_b128 v[196:199], v163 offset:20480
	ds_read_b128 v[208:211], v163 offset:21504
	ds_read_b128 v[212:215], v163 offset:22528
	ds_read_b128 v[216:219], v163 offset:23552
	global_load_lds_dwordx4 v[156:157], off
	s_add_i32 m0, s34, 0x2000
	s_add_u32 s34, s40, 0x40000
	v_lshl_add_u64 v[200:201], s[40:41], 0, v[146:147]
	s_addc_u32 s35, s41, 0
	s_add_i32 s36, s62, s48
	global_load_lds_dwordx4 v[200:201], off
	v_lshl_add_u64 v[220:221], s[34:35], 0, v[144:145]
	s_mov_b32 m0, s36
	v_lshl_add_u64 v[222:223], s[42:43], 0, v[146:147]
	global_load_lds_dwordx4 v[220:221], off
	s_add_i32 m0, s36, 0x2000
	v_lshl_add_u64 v[220:221], s[34:35], 0, v[146:147]
	global_load_lds_dwordx4 v[220:221], off
	s_mov_b32 m0, s27
	v_lshl_add_u64 v[220:221], s[42:43], 0, v[144:145]
	global_load_lds_dwordx4 v[220:221], off
	s_nop 0
	s_waitcnt vmcnt(7)
	s_waitcnt lgkmcnt(0)
	s_barrier
; #define PG8_STAGE(bufoff, gbase, voff) do { _Pragma("unroll") for (int _i = 0; _i < 2; ++_i) \
;         __builtin_amdgcn_global_load_lds((const unsigned*)((const char*)(gbase) + (voff)[_i]), (PG8_LAS unsigned*)(lds + (bufoff) + ldsw + _i * 8192), 16, 0, 0); } while (0)
; #define PG8_LDA(dst, b, h) do { _Pragma("unroll") for (int m = 0; m < 4; ++m) _Pragma("unroll") for (int k = 0; k < 2; ++k) dst[m][k] = *(const PG8_LAS bf16x8*)(lds + PG8_SA(b, h) + aoff + m * 2048 + k * 1024); } while (0)
; #define PG8_LDB(dst, b, h) do { _Pragma("unroll") for (int n = 0; n < 2; ++n) _Pragma("unroll") for (int k = 0; k < 2; ++k) dst[n][k] = *(const PG8_LAS bf16x8*)(lds + PG8_SB(b, h) + boff + n * 2048 + k * 1024); } while (0)
; #define PG8_WAIT_V(n) asm volatile("s_waitcnt vmcnt(" #n ")" ::: "memory")
; #define PG8_WAIT_L(n) asm volatile("s_waitcnt lgkmcnt(" #n ")" ::: "memory")
; #define PG8_BAR __builtin_amdgcn_s_barrier()
; #define PG8_SCHED __builtin_amdgcn_sched_barrier(0)
; #define PG8_MMA2(ai) PG8_MMA(ai, 0, At, B0)
; #define PG8_MMA2(ai) PG8_MMA(ai, 1, At, B1)
; #define PG8_MMA2(ai) do { PG8_MMA(ai, 0, At, B0); PG8_MMA(ai, 1, At, B1); } while (0)
;     ...
;             PG8_WAIT_V(8); PG8_WAIT_L(0); PG8_BAR; PG8_MMA2(1); PG8_BAR; PG8_SCHED;
;             PG8_LDB(B0, 1, 0); PG8_LDB(B1, 1, 1); PG8_SCHED; PG8_LDA(At, 1, 0); PG8_STAGE(PG8_SA(0, 1), a2 + hstep, voffA);
;             PG8_WAIT_V(8); PG8_WAIT_L(0); PG8_BAR; PG8_MMA2(0); PG8_BAR; PG8_SCHED;
;             PG8_LDA(At, 1, 1); PG8_STAGE(PG8_SB(1, 0), b3, voffB); PG8_STAGE(PG8_SB(1, 1), b3 + hstep, voffB); PG8_STAGE(PG8_SA(1, 0), a3, voffA);
	s_setprio 1
	s_waitcnt lgkmcnt(0)
	v_mfma_f32_16x16x32_bf16 v[60:63], v[128:131], v[180:183], v[60:63]
	v_mfma_f32_16x16x32_bf16 v[56:59], v[136:139], v[180:183], v[56:59]
	v_mfma_f32_16x16x32_bf16 v[44:47], v[128:131], v[188:191], v[44:47]
	v_mfma_f32_16x16x32_bf16 v[40:43], v[136:139], v[188:191], v[40:43]
	v_mfma_f32_16x16x32_bf16 v[28:31], v[128:131], v[196:199], v[28:31]
	v_mfma_f32_16x16x32_bf16 v[24:27], v[136:139], v[196:199], v[24:27]
	v_mfma_f32_16x16x32_bf16 v[12:15], v[128:131], v[212:215], v[12:15]
	v_mfma_f32_16x16x32_bf16 v[8:11], v[136:139], v[212:215], v[8:11]
	v_mfma_f32_16x16x32_bf16 v[60:63], v[132:135], v[184:187], v[60:63]
	v_mfma_f32_16x16x32_bf16 v[56:59], v[140:143], v[184:187], v[56:59]
	v_mfma_f32_16x16x32_bf16 v[44:47], v[132:135], v[192:195], v[44:47]
	v_mfma_f32_16x16x32_bf16 v[40:43], v[140:143], v[192:195], v[40:43]
	v_mfma_f32_16x16x32_bf16 v[28:31], v[132:135], v[208:211], v[28:31]
	v_mfma_f32_16x16x32_bf16 v[24:27], v[140:143], v[208:211], v[24:27]
	v_mfma_f32_16x16x32_bf16 v[12:15], v[132:135], v[216:219], v[12:15]
	v_mfma_f32_16x16x32_bf16 v[8:11], v[140:143], v[216:219], v[8:11]
	s_setprio 0
	s_setprio 1
	v_mfma_f32_16x16x32_bf16 v[52:55], v[164:167], v[180:183], v[52:55]
	v_mfma_f32_16x16x32_bf16 v[48:51], v[172:175], v[180:183], v[48:51]
	v_mfma_f32_16x16x32_bf16 v[36:39], v[164:167], v[188:191], v[36:39]
	v_mfma_f32_16x16x32_bf16 v[32:35], v[172:175], v[188:191], v[32:35]
	v_mfma_f32_16x16x32_bf16 v[20:23], v[164:167], v[196:199], v[20:23]
	v_mfma_f32_16x16x32_bf16 v[16:19], v[172:175], v[196:199], v[16:19]
	v_mfma_f32_16x16x32_bf16 v[4:7], v[164:167], v[212:215], v[4:7]
	v_mfma_f32_16x16x32_bf16 v[0:3], v[172:175], v[212:215], v[0:3]
	v_mfma_f32_16x16x32_bf16 v[52:55], v[168:171], v[184:187], v[52:55]
	v_mfma_f32_16x16x32_bf16 v[48:51], v[176:179], v[184:187], v[48:51]
	v_mfma_f32_16x16x32_bf16 v[36:39], v[168:171], v[192:195], v[36:39]
	v_mfma_f32_16x16x32_bf16 v[32:35], v[176:179], v[192:195], v[32:35]
	v_mfma_f32_16x16x32_bf16 v[20:23], v[168:171], v[208:211], v[20:23]
	v_mfma_f32_16x16x32_bf16 v[16:19], v[176:179], v[208:211], v[16:19]
	v_mfma_f32_16x16x32_bf16 v[4:7], v[168:171], v[216:219], v[4:7]
	v_mfma_f32_16x16x32_bf16 v[0:3], v[176:179], v[216:219], v[0:3]
	s_setprio 0
	s_barrier
	s_add_i32 s36, 0, 0x18000
	s_add_i32 s37, 0, 0x1c000
	v_add_u32_e32 v140, s36, v159
	v_add_u32_e32 v176, s37, v159
	ds_read_b128 v[128:131], v140
	ds_read_b128 v[132:135], v140 offset:1024
	ds_read_b128 v[136:139], v140 offset:2048
	ds_read_b128 v[140:143], v140 offset:3072
	ds_read_b128 v[164:167], v176
	ds_read_b128 v[168:171], v176 offset:1024
	ds_read_b128 v[172:175], v176 offset:2048
	ds_read_b128 v[176:179], v176 offset:3072
	s_add_u32 s34, s42, 0x40000
	s_addc_u32 s35, s43, 0
	s_mov_b32 m0, s49
	s_nop 0
	global_load_lds_dwordx4 v[222:223], off
	s_mov_b32 m0, s50
	v_lshl_add_u64 v[224:225], s[34:35], 0, v[144:145]
	ds_read_b128 v[180:183], v163 offset:32768
	ds_read_b128 v[184:187], v163 offset:33792
	ds_read_b128 v[188:191], v163 offset:34816
	ds_read_b128 v[192:195], v163 offset:35840
	ds_read_b128 v[196:199], v163 offset:36864
	ds_read_b128 v[208:211], v163 offset:37888
	ds_read_b128 v[212:215], v163 offset:38912
	ds_read_b128 v[216:219], v163 offset:39936
	global_load_lds_dwordx4 v[224:225], off
	s_mov_b32 m0, s51
	v_lshl_add_u64 v[224:225], s[34:35], 0, v[146:147]
	global_load_lds_dwordx4 v[224:225], off
	s_waitcnt vmcnt(8)
	s_waitcnt lgkmcnt(0)
	s_barrier
	s_setprio 1
	s_waitcnt lgkmcnt(0)
	v_mfma_f32_16x16x32_bf16 v[124:127], v[128:131], v[180:183], v[124:127]
	v_mfma_f32_16x16x32_bf16 v[120:123], v[136:139], v[180:183], v[120:123]
	v_mfma_f32_16x16x32_bf16 v[108:111], v[128:131], v[188:191], v[108:111]
	v_mfma_f32_16x16x32_bf16 v[104:107], v[136:139], v[188:191], v[104:107]
	v_mfma_f32_16x16x32_bf16 v[92:95], v[128:131], v[196:199], v[92:95]
	v_mfma_f32_16x16x32_bf16 v[88:91], v[136:139], v[196:199], v[88:91]
	v_mfma_f32_16x16x32_bf16 v[76:79], v[128:131], v[212:215], v[76:79]
	v_mfma_f32_16x16x32_bf16 v[72:75], v[136:139], v[212:215], v[72:75]
	v_mfma_f32_16x16x32_bf16 v[124:127], v[132:135], v[184:187], v[124:127]
	v_mfma_f32_16x16x32_bf16 v[120:123], v[140:143], v[184:187], v[120:123]
	v_mfma_f32_16x16x32_bf16 v[108:111], v[132:135], v[192:195], v[108:111]
	v_mfma_f32_16x16x32_bf16 v[104:107], v[140:143], v[192:195], v[104:107]
	v_mfma_f32_16x16x32_bf16 v[92:95], v[132:135], v[208:211], v[92:95]
	v_mfma_f32_16x16x32_bf16 v[88:91], v[140:143], v[208:211], v[88:91]
	v_mfma_f32_16x16x32_bf16 v[76:79], v[132:135], v[216:219], v[76:79]
	v_mfma_f32_16x16x32_bf16 v[72:75], v[140:143], v[216:219], v[72:75]
	s_setprio 0
	s_setprio 1
	v_mfma_f32_16x16x32_bf16 v[116:119], v[164:167], v[180:183], v[116:119]
	v_mfma_f32_16x16x32_bf16 v[112:115], v[172:175], v[180:183], v[112:115]
	v_mfma_f32_16x16x32_bf16 v[100:103], v[164:167], v[188:191], v[100:103]
	v_mfma_f32_16x16x32_bf16 v[96:99], v[172:175], v[188:191], v[96:99]
	v_mfma_f32_16x16x32_bf16 v[84:87], v[164:167], v[196:199], v[84:87]
	v_mfma_f32_16x16x32_bf16 v[80:83], v[172:175], v[196:199], v[80:83]
	v_mfma_f32_16x16x32_bf16 v[68:71], v[164:167], v[212:215], v[68:71]
	v_mfma_f32_16x16x32_bf16 v[64:67], v[172:175], v[212:215], v[64:67]
	v_mfma_f32_16x16x32_bf16 v[116:119], v[168:171], v[184:187], v[116:119]
	v_mfma_f32_16x16x32_bf16 v[112:115], v[176:179], v[184:187], v[112:115]
	v_mfma_f32_16x16x32_bf16 v[100:103], v[168:171], v[192:195], v[100:103]
	v_mfma_f32_16x16x32_bf16 v[96:99], v[176:179], v[192:195], v[96:99]
	v_mfma_f32_16x16x32_bf16 v[84:87], v[168:171], v[208:211], v[84:87]
	v_mfma_f32_16x16x32_bf16 v[80:83], v[176:179], v[208:211], v[80:83]
	v_mfma_f32_16x16x32_bf16 v[68:71], v[168:171], v[216:219], v[68:71]
	v_mfma_f32_16x16x32_bf16 v[64:67], v[176:179], v[216:219], v[64:67]
	s_setprio 0
	s_barrier
	s_add_i32 s34, s36, s48
	v_lshl_add_u64 v[156:157], v[156:157], 0, s[12:13]
	s_mov_b32 m0, s34
	ds_read_b128 v[180:183], v163 offset:49152
	ds_read_b128 v[184:187], v163 offset:50176
	ds_read_b128 v[188:191], v163 offset:51200
	ds_read_b128 v[192:195], v163 offset:52224
	ds_read_b128 v[196:199], v163 offset:53248
	ds_read_b128 v[208:211], v163 offset:54272
	ds_read_b128 v[212:215], v163 offset:55296
	ds_read_b128 v[216:219], v163 offset:56320
	global_load_lds_dwordx4 v[156:157], off
	s_add_i32 m0, s34, 0x2000
	s_add_u32 s34, s40, 0x40080
	v_lshl_add_u64 v[156:157], v[200:201], 0, s[12:13]
	s_addc_u32 s35, s41, 0
	s_add_i32 s36, s37, s48
	global_load_lds_dwordx4 v[156:157], off
	s_mov_b32 m0, s36
	v_lshl_add_u64 v[156:157], s[34:35], 0, v[144:145]
	global_load_lds_dwordx4 v[156:157], off
	s_add_i32 m0, s36, 0x2000
	v_lshl_add_u64 v[156:157], s[34:35], 0, v[146:147]
	global_load_lds_dwordx4 v[156:157], off
	s_mov_b32 m0, s57
	v_lshl_add_u64 v[156:157], v[220:221], 0, s[12:13]
	global_load_lds_dwordx4 v[156:157], off
	v_lshl_add_u64 v[156:157], v[222:223], 0, s[12:13]
	s_nop 0
	s_cmp_lg_u32 s69, 12
	s_cbranch_scc1 .Ldf_skipD_9
	s_mov_b32 m0, s58
	s_nop 0
	global_load_lds_dwordx4 v[156:157], off

; #define PG8_STAGE(bufoff, gbase, voff) do { _Pragma("unroll") for (int _i = 0; _i < 2; ++_i) \
;         __builtin_amdgcn_global_load_lds((const unsigned*)((const char*)(gbase) + (voff)[_i]), (PG8_LAS unsigned*)(lds + (bufoff) + ldsw + _i * 8192), 16, 0, 0); } while (0)
; #define PG8_LDA(dst, b, h) do { _Pragma("unroll") for (int m = 0; m < 4; ++m) _Pragma("unroll") for (int k = 0; k < 2; ++k) dst[m][k] = *(const PG8_LAS bf16x8*)(lds + PG8_SA(b, h) + aoff + m * 2048 + k * 1024); } while (0)
; #define PG8_LDB(dst, b, h) do { _Pragma("unroll") for (int n = 0; n < 2; ++n) _Pragma("unroll") for (int k = 0; k < 2; ++k) dst[n][k] = *(const PG8_LAS bf16x8*)(lds + PG8_SB(b, h) + boff + n * 2048 + k * 1024); } while (0)
; #define PG8_WAIT_V(n) asm volatile("s_waitcnt vmcnt(" #n ")" ::: "memory")
; #define PG8_WAIT_L(n) asm volatile("s_waitcnt lgkmcnt(" #n ")" ::: "memory")
; #define PG8_BAR __builtin_amdgcn_s_barrier()
; #define PG8_SCHED __builtin_amdgcn_sched_barrier(0)
; #define PG8_MMA2(ai) PG8_MMA(ai, 0, At, B0)
; #define PG8_MMA2(ai) PG8_MMA(ai, 1, At, B1)
; #define PG8_MMA2(ai) do { PG8_MMA(ai, 0, At, B0); PG8_MMA(ai, 1, At, B1); } while (0)
;     ...
;             PG8_LDB(B0, 0, 0); PG8_LDB(B1, 0, 1); PG8_SCHED; PG8_LDA(At, 0, 0); PG8_STAGE(PG8_SA(1, 1), a1 + hstep, voffA);
;             PG8_WAIT_V(8); PG8_WAIT_L(0); PG8_BAR; PG8_MMA2(0); PG8_BAR; PG8_SCHED;
;             PG8_LDA(At, 0, 1); PG8_STAGE(PG8_SB(0, 0), b2, voffB); PG8_STAGE(PG8_SB(0, 1), b2 + hstep, voffB); PG8_STAGE(PG8_SA(0, 0), a2, voffA);
;             PG8_WAIT_V(8); PG8_WAIT_L(0); PG8_BAR; PG8_MMA2(1); PG8_BAR; PG8_SCHED;
.Ldf_skipA_10:
	ds_read_b128 v[152:155], v149
	ds_read_b128 v[156:159], v149 offset:1024
	ds_read_b128 v[160:163], v149 offset:2048
	ds_read_b128 v[164:167], v149 offset:3072
	ds_read_b128 v[168:171], v150
	ds_read_b128 v[172:175], v150 offset:1024
	ds_read_b128 v[176:179], v150 offset:2048
	ds_read_b128 v[180:183], v150 offset:3072
	s_add_u32 s34, s36, 0xfffc0080
	s_addc_u32 s35, s37, -1
	s_cmp_eq_u32 s63, 12
	s_cselect_b32 s41, s19, s35
	s_cselect_b32 s40, s59, s34
	s_cselect_b32 s39, s17, s62
	s_cselect_b32 s38, s60, s61
	v_lshl_add_u64 v[144:145], s[36:37], 0, v[138:139]
	s_add_i32 m0, s27, 0xc000
	ds_read_b128 v[184:187], v151
	ds_read_b128 v[188:191], v151 offset:1024
	ds_read_b128 v[192:195], v151 offset:2048
	ds_read_b128 v[196:199], v151 offset:3072
	ds_read_b128 v[208:211], v151 offset:4096
	ds_read_b128 v[212:215], v151 offset:5120
	ds_read_b128 v[216:219], v151 offset:6144
	ds_read_b128 v[220:223], v151 offset:7168
	global_load_lds_dwordx4 v[144:145], off
	s_add_i32 m0, s27, 0xe000
	v_lshl_add_u64 v[144:145], s[36:37], 0, v[136:137]
	global_load_lds_dwordx4 v[144:145], off
	s_waitcnt vmcnt(8)
	s_waitcnt lgkmcnt(0)
	s_barrier
	s_setprio 1
	s_waitcnt lgkmcnt(0)
	v_mfma_f32_16x16x32_bf16 v[124:127], v[152:155], v[184:187], v[124:127]
	v_mfma_f32_16x16x32_bf16 v[120:123], v[160:163], v[184:187], v[120:123]
	v_mfma_f32_16x16x32_bf16 v[108:111], v[152:155], v[192:195], v[108:111]
	v_mfma_f32_16x16x32_bf16 v[104:107], v[160:163], v[192:195], v[104:107]
	v_mfma_f32_16x16x32_bf16 v[92:95], v[152:155], v[208:211], v[92:95]
	v_mfma_f32_16x16x32_bf16 v[88:91], v[160:163], v[208:211], v[88:91]
	v_mfma_f32_16x16x32_bf16 v[76:79], v[152:155], v[216:219], v[76:79]
	v_mfma_f32_16x16x32_bf16 v[72:75], v[160:163], v[216:219], v[72:75]
	v_mfma_f32_16x16x32_bf16 v[124:127], v[156:159], v[188:191], v[124:127]
	v_mfma_f32_16x16x32_bf16 v[120:123], v[164:167], v[188:191], v[120:123]
	v_mfma_f32_16x16x32_bf16 v[108:111], v[156:159], v[196:199], v[108:111]
	v_mfma_f32_16x16x32_bf16 v[104:107], v[164:167], v[196:199], v[104:107]
	v_mfma_f32_16x16x32_bf16 v[92:95], v[156:159], v[212:215], v[92:95]
	v_mfma_f32_16x16x32_bf16 v[88:91], v[164:167], v[212:215], v[88:91]
	v_mfma_f32_16x16x32_bf16 v[76:79], v[156:159], v[220:223], v[76:79]
	v_mfma_f32_16x16x32_bf16 v[72:75], v[164:167], v[220:223], v[72:75]
	s_setprio 0
	s_setprio 1
	v_mfma_f32_16x16x32_bf16 v[116:119], v[168:171], v[184:187], v[116:119]
	v_mfma_f32_16x16x32_bf16 v[112:115], v[176:179], v[184:187], v[112:115]
	v_mfma_f32_16x16x32_bf16 v[100:103], v[168:171], v[192:195], v[100:103]
	v_mfma_f32_16x16x32_bf16 v[96:99], v[176:179], v[192:195], v[96:99]
	v_mfma_f32_16x16x32_bf16 v[84:87], v[168:171], v[208:211], v[84:87]
	v_mfma_f32_16x16x32_bf16 v[80:83], v[176:179], v[208:211], v[80:83]
	v_mfma_f32_16x16x32_bf16 v[68:71], v[168:171], v[216:219], v[68:71]
	v_mfma_f32_16x16x32_bf16 v[64:67], v[176:179], v[216:219], v[64:67]
	v_mfma_f32_16x16x32_bf16 v[116:119], v[172:175], v[188:191], v[116:119]
	v_mfma_f32_16x16x32_bf16 v[112:115], v[180:183], v[188:191], v[112:115]
	v_mfma_f32_16x16x32_bf16 v[100:103], v[172:175], v[196:199], v[100:103]
	v_mfma_f32_16x16x32_bf16 v[96:99], v[180:183], v[196:199], v[96:99]
	v_mfma_f32_16x16x32_bf16 v[84:87], v[172:175], v[212:215], v[84:87]
	v_mfma_f32_16x16x32_bf16 v[80:83], v[180:183], v[212:215], v[80:83]
	v_mfma_f32_16x16x32_bf16 v[68:71], v[172:175], v[220:223], v[68:71]
	v_mfma_f32_16x16x32_bf16 v[64:67], v[180:183], v[220:223], v[64:67]
	s_setprio 0
	s_barrier
	s_add_i32 s34, s3, s45
	v_lshl_add_u64 v[144:145], s[38:39], 0, v[132:133]
	s_mov_b32 m0, s34
	ds_read_b128 v[184:187], v151 offset:16384
	ds_read_b128 v[188:191], v151 offset:17408
	ds_read_b128 v[192:195], v151 offset:18432
	ds_read_b128 v[196:199], v151 offset:19456
	ds_read_b128 v[208:211], v151 offset:20480
	ds_read_b128 v[212:215], v151 offset:21504
	ds_read_b128 v[216:219], v151 offset:22528
	ds_read_b128 v[220:223], v151 offset:23552
	global_load_lds_dwordx4 v[144:145], off
	s_add_i32 m0, s34, 0x2000
	s_add_u32 s34, s38, 0x40000
	v_lshl_add_u64 v[200:201], s[38:39], 0, v[128:129]
	s_addc_u32 s35, s39, 0
	s_add_i32 s64, s56, s45
	global_load_lds_dwordx4 v[200:201], off
	v_lshl_add_u64 v[224:225], s[34:35], 0, v[132:133]
	s_mov_b32 m0, s64
	v_lshl_add_u64 v[226:227], s[40:41], 0, v[130:131]
	global_load_lds_dwordx4 v[224:225], off
	s_add_i32 m0, s64, 0x2000
	v_lshl_add_u64 v[224:225], s[34:35], 0, v[128:129]
	global_load_lds_dwordx4 v[224:225], off
	s_mov_b32 m0, s27
	v_lshl_add_u64 v[224:225], s[40:41], 0, v[134:135]
	global_load_lds_dwordx4 v[224:225], off
	s_nop 0
	s_waitcnt vmcnt(7)
	s_waitcnt lgkmcnt(0)
	s_barrier
; #define PG8_STAGE(bufoff, gbase, voff) do { _Pragma("unroll") for (int _i = 0; _i < 2; ++_i) \
;         __builtin_amdgcn_global_load_lds((const unsigned*)((const char*)(gbase) + (voff)[_i]), (PG8_LAS unsigned*)(lds + (bufoff) + ldsw + _i * 8192), 16, 0, 0); } while (0)
; #define PG8_LDA(dst, b, h) do { _Pragma("unroll") for (int m = 0; m < 4; ++m) _Pragma("unroll") for (int k = 0; k < 2; ++k) dst[m][k] = *(const PG8_LAS bf16x8*)(lds + PG8_SA(b, h) + aoff + m * 2048 + k * 1024); } while (0)
; #define PG8_LDB(dst, b, h) do { _Pragma("unroll") for (int n = 0; n < 2; ++n) _Pragma("unroll") for (int k = 0; k < 2; ++k) dst[n][k] = *(const PG8_LAS bf16x8*)(lds + PG8_SB(b, h) + boff + n * 2048 + k * 1024); } while (0)
; #define PG8_WAIT_V(n) asm volatile("s_waitcnt vmcnt(" #n ")" ::: "memory")
; #define PG8_WAIT_L(n) asm volatile("s_waitcnt lgkmcnt(" #n ")" ::: "memory")
; #define PG8_BAR __builtin_amdgcn_s_barrier()
; #define PG8_SCHED __builtin_amdgcn_sched_barrier(0)
; #define PG8_MMA2(ai) PG8_MMA(ai, 0, At, B0)
; #define PG8_MMA2(ai) PG8_MMA(ai, 1, At, B1)
; #define PG8_MMA2(ai) do { PG8_MMA(ai, 0, At, B0); PG8_MMA(ai, 1, At, B1); } while (0)
;     ...
;             PG8_WAIT_V(8); PG8_WAIT_L(0); PG8_BAR; PG8_MMA2(1); PG8_BAR; PG8_SCHED;
;             PG8_LDB(B0, 1, 0); PG8_LDB(B1, 1, 1); PG8_SCHED; PG8_LDA(At, 1, 0); PG8_STAGE(PG8_SA(0, 1), a2 + hstep, voffA);
;             PG8_WAIT_V(8); PG8_WAIT_L(0); PG8_BAR; PG8_MMA2(0); PG8_BAR; PG8_SCHED;
;             PG8_LDA(At, 1, 1); PG8_STAGE(PG8_SB(1, 0), b3, voffB); PG8_STAGE(PG8_SB(1, 1), b3 + hstep, voffB); PG8_STAGE(PG8_SA(1, 0), a3, voffA);
	s_setprio 1
	s_waitcnt lgkmcnt(0)
	v_mfma_f32_16x16x32_bf16 v[60:63], v[152:155], v[184:187], v[60:63]
	v_mfma_f32_16x16x32_bf16 v[56:59], v[160:163], v[184:187], v[56:59]
	v_mfma_f32_16x16x32_bf16 v[44:47], v[152:155], v[192:195], v[44:47]
	v_mfma_f32_16x16x32_bf16 v[40:43], v[160:163], v[192:195], v[40:43]
	v_mfma_f32_16x16x32_bf16 v[28:31], v[152:155], v[208:211], v[28:31]
	v_mfma_f32_16x16x32_bf16 v[24:27], v[160:163], v[208:211], v[24:27]
	v_mfma_f32_16x16x32_bf16 v[12:15], v[152:155], v[216:219], v[12:15]
	v_mfma_f32_16x16x32_bf16 v[8:11], v[160:163], v[216:219], v[8:11]
	v_mfma_f32_16x16x32_bf16 v[60:63], v[156:159], v[188:191], v[60:63]
	v_mfma_f32_16x16x32_bf16 v[56:59], v[164:167], v[188:191], v[56:59]
	v_mfma_f32_16x16x32_bf16 v[44:47], v[156:159], v[196:199], v[44:47]
	v_mfma_f32_16x16x32_bf16 v[40:43], v[164:167], v[196:199], v[40:43]
	v_mfma_f32_16x16x32_bf16 v[28:31], v[156:159], v[212:215], v[28:31]
	v_mfma_f32_16x16x32_bf16 v[24:27], v[164:167], v[212:215], v[24:27]
	v_mfma_f32_16x16x32_bf16 v[12:15], v[156:159], v[220:223], v[12:15]
	v_mfma_f32_16x16x32_bf16 v[8:11], v[164:167], v[220:223], v[8:11]
	s_setprio 0
	s_setprio 1
	v_mfma_f32_16x16x32_bf16 v[52:55], v[168:171], v[184:187], v[52:55]
	v_mfma_f32_16x16x32_bf16 v[48:51], v[176:179], v[184:187], v[48:51]
	v_mfma_f32_16x16x32_bf16 v[36:39], v[168:171], v[192:195], v[36:39]
	v_mfma_f32_16x16x32_bf16 v[32:35], v[176:179], v[192:195], v[32:35]
	v_mfma_f32_16x16x32_bf16 v[20:23], v[168:171], v[208:211], v[20:23]
	v_mfma_f32_16x16x32_bf16 v[16:19], v[176:179], v[208:211], v[16:19]
	v_mfma_f32_16x16x32_bf16 v[4:7], v[168:171], v[216:219], v[4:7]
	v_mfma_f32_16x16x32_bf16 v[0:3], v[176:179], v[216:219], v[0:3]
	v_mfma_f32_16x16x32_bf16 v[52:55], v[172:175], v[188:191], v[52:55]
	v_mfma_f32_16x16x32_bf16 v[48:51], v[180:183], v[188:191], v[48:51]
	v_mfma_f32_16x16x32_bf16 v[36:39], v[172:175], v[196:199], v[36:39]
	v_mfma_f32_16x16x32_bf16 v[32:35], v[180:183], v[196:199], v[32:35]
	v_mfma_f32_16x16x32_bf16 v[20:23], v[172:175], v[212:215], v[20:23]
	v_mfma_f32_16x16x32_bf16 v[16:19], v[180:183], v[212:215], v[16:19]
	v_mfma_f32_16x16x32_bf16 v[4:7], v[172:175], v[220:223], v[4:7]
	v_mfma_f32_16x16x32_bf16 v[0:3], v[180:183], v[220:223], v[0:3]
	s_setprio 0
	s_barrier
	s_add_i32 s64, 0, 0x18000
	s_add_i32 s65, 0, 0x1c000
	v_add_u32_e32 v164, s64, v147
	v_add_u32_e32 v180, s65, v147
	ds_read_b128 v[152:155], v164
	ds_read_b128 v[156:159], v164 offset:1024
	ds_read_b128 v[160:163], v164 offset:2048
	ds_read_b128 v[164:167], v164 offset:3072
	ds_read_b128 v[168:171], v180
	ds_read_b128 v[172:175], v180 offset:1024
	ds_read_b128 v[176:179], v180 offset:2048
	ds_read_b128 v[180:183], v180 offset:3072
	s_add_u32 s34, s40, 0x40000
	s_addc_u32 s35, s41, 0
	s_mov_b32 m0, s48
	s_nop 0
	global_load_lds_dwordx4 v[226:227], off
	s_mov_b32 m0, s49
	v_lshl_add_u64 v[228:229], s[34:35], 0, v[134:135]
	ds_read_b128 v[184:187], v151 offset:32768
	ds_read_b128 v[188:191], v151 offset:33792
	ds_read_b128 v[192:195], v151 offset:34816
	ds_read_b128 v[196:199], v151 offset:35840
	ds_read_b128 v[208:211], v151 offset:36864
	ds_read_b128 v[212:215], v151 offset:37888
	ds_read_b128 v[216:219], v151 offset:38912
	ds_read_b128 v[220:223], v151 offset:39936
	global_load_lds_dwordx4 v[228:229], off
	s_mov_b32 m0, s50
	v_lshl_add_u64 v[228:229], s[34:35], 0, v[130:131]
	global_load_lds_dwordx4 v[228:229], off
	s_waitcnt vmcnt(8)
	s_waitcnt lgkmcnt(0)
	s_barrier
	s_setprio 1
	s_waitcnt lgkmcnt(0)
	v_mfma_f32_16x16x32_bf16 v[124:127], v[152:155], v[184:187], v[124:127]
	v_mfma_f32_16x16x32_bf16 v[120:123], v[160:163], v[184:187], v[120:123]
	v_mfma_f32_16x16x32_bf16 v[108:111], v[152:155], v[192:195], v[108:111]
	v_mfma_f32_16x16x32_bf16 v[104:107], v[160:163], v[192:195], v[104:107]
	v_mfma_f32_16x16x32_bf16 v[92:95], v[152:155], v[208:211], v[92:95]
	v_mfma_f32_16x16x32_bf16 v[88:91], v[160:163], v[208:211], v[88:91]
	v_mfma_f32_16x16x32_bf16 v[76:79], v[152:155], v[216:219], v[76:79]
	v_mfma_f32_16x16x32_bf16 v[72:75], v[160:163], v[216:219], v[72:75]
	v_mfma_f32_16x16x32_bf16 v[124:127], v[156:159], v[188:191], v[124:127]
	v_mfma_f32_16x16x32_bf16 v[120:123], v[164:167], v[188:191], v[120:123]
	v_mfma_f32_16x16x32_bf16 v[108:111], v[156:159], v[196:199], v[108:111]
	v_mfma_f32_16x16x32_bf16 v[104:107], v[164:167], v[196:199], v[104:107]
	v_mfma_f32_16x16x32_bf16 v[92:95], v[156:159], v[212:215], v[92:95]
	v_mfma_f32_16x16x32_bf16 v[88:91], v[164:167], v[212:215], v[88:91]
	v_mfma_f32_16x16x32_bf16 v[76:79], v[156:159], v[220:223], v[76:79]
	v_mfma_f32_16x16x32_bf16 v[72:75], v[164:167], v[220:223], v[72:75]
	s_setprio 0
	s_setprio 1
	v_mfma_f32_16x16x32_bf16 v[116:119], v[168:171], v[184:187], v[116:119]
	v_mfma_f32_16x16x32_bf16 v[112:115], v[176:179], v[184:187], v[112:115]
	v_mfma_f32_16x16x32_bf16 v[100:103], v[168:171], v[192:195], v[100:103]
	v_mfma_f32_16x16x32_bf16 v[96:99], v[176:179], v[192:195], v[96:99]
	v_mfma_f32_16x16x32_bf16 v[84:87], v[168:171], v[208:211], v[84:87]
	v_mfma_f32_16x16x32_bf16 v[80:83], v[176:179], v[208:211], v[80:83]
	v_mfma_f32_16x16x32_bf16 v[68:71], v[168:171], v[216:219], v[68:71]
	v_mfma_f32_16x16x32_bf16 v[64:67], v[176:179], v[216:219], v[64:67]
	v_mfma_f32_16x16x32_bf16 v[116:119], v[172:175], v[188:191], v[116:119]
	v_mfma_f32_16x16x32_bf16 v[112:115], v[180:183], v[188:191], v[112:115]
	v_mfma_f32_16x16x32_bf16 v[100:103], v[172:175], v[196:199], v[100:103]
	v_mfma_f32_16x16x32_bf16 v[96:99], v[180:183], v[196:199], v[96:99]
	v_mfma_f32_16x16x32_bf16 v[84:87], v[172:175], v[212:215], v[84:87]
	v_mfma_f32_16x16x32_bf16 v[80:83], v[180:183], v[212:215], v[80:83]
	v_mfma_f32_16x16x32_bf16 v[68:71], v[172:175], v[220:223], v[68:71]
	v_mfma_f32_16x16x32_bf16 v[64:67], v[180:183], v[220:223], v[64:67]
	s_setprio 0
	s_barrier
	s_add_i32 s34, s64, s45
	v_lshl_add_u64 v[144:145], v[144:145], 0, s[12:13]
	s_mov_b32 m0, s34
	ds_read_b128 v[184:187], v151 offset:49152
	ds_read_b128 v[188:191], v151 offset:50176
	ds_read_b128 v[192:195], v151 offset:51200
	ds_read_b128 v[196:199], v151 offset:52224
	ds_read_b128 v[208:211], v151 offset:53248
	ds_read_b128 v[212:215], v151 offset:54272
	ds_read_b128 v[216:219], v151 offset:55296
	ds_read_b128 v[220:223], v151 offset:56320
	global_load_lds_dwordx4 v[144:145], off
	s_add_i32 m0, s34, 0x2000
	s_add_u32 s34, s38, 0x40080
	v_lshl_add_u64 v[144:145], v[200:201], 0, s[12:13]
	s_addc_u32 s35, s39, 0
	s_add_i32 s38, s65, s45
	global_load_lds_dwordx4 v[144:145], off
	s_mov_b32 m0, s38
	v_lshl_add_u64 v[144:145], s[34:35], 0, v[132:133]
	global_load_lds_dwordx4 v[144:145], off
	s_add_i32 m0, s38, 0x2000
	v_lshl_add_u64 v[144:145], s[34:35], 0, v[128:129]
	global_load_lds_dwordx4 v[144:145], off
	s_mov_b32 m0, s52
	v_lshl_add_u64 v[144:145], v[224:225], 0, s[12:13]
	global_load_lds_dwordx4 v[144:145], off
	v_lshl_add_u64 v[144:145], v[226:227], 0, s[12:13]
	s_nop 0
	s_cmp_lg_u32 s63, 12
	s_cbranch_scc1 .Ldf_skipD_10
	s_mov_b32 m0, s53
	s_nop 0
	global_load_lds_dwordx4 v[144:145], off

; #define PG8_STAGE(bufoff, gbase, voff) do { _Pragma("unroll") for (int _i = 0; _i < 2; ++_i) \
;         __builtin_amdgcn_global_load_lds((const unsigned*)((const char*)(gbase) + (voff)[_i]), (PG8_LAS unsigned*)(lds + (bufoff) + ldsw + _i * 8192), 16, 0, 0); } while (0)
; #define PG8_LDA(dst, b, h) do { _Pragma("unroll") for (int m = 0; m < 4; ++m) _Pragma("unroll") for (int k = 0; k < 2; ++k) dst[m][k] = *(const PG8_LAS bf16x8*)(lds + PG8_SA(b, h) + aoff + m * 2048 + k * 1024); } while (0)
; #define PG8_LDB(dst, b, h) do { _Pragma("unroll") for (int n = 0; n < 2; ++n) _Pragma("unroll") for (int k = 0; k < 2; ++k) dst[n][k] = *(const PG8_LAS bf16x8*)(lds + PG8_SB(b, h) + boff + n * 2048 + k * 1024); } while (0)
; #define PG8_WAIT_V(n) asm volatile("s_waitcnt vmcnt(" #n ")" ::: "memory")
; #define PG8_WAIT_L(n) asm volatile("s_waitcnt lgkmcnt(" #n ")" ::: "memory")
; #define PG8_BAR __builtin_amdgcn_s_barrier()
; #define PG8_SCHED __builtin_amdgcn_sched_barrier(0)
; #define PG8_MMA2(ai) PG8_MMA(ai, 0, At, B0)
; #define PG8_MMA2(ai) PG8_MMA(ai, 1, At, B1)
; #define PG8_MMA2(ai) do { PG8_MMA(ai, 0, At, B0); PG8_MMA(ai, 1, At, B1); } while (0)
;     ...
;             PG8_LDB(B0, 0, 0); PG8_LDB(B1, 0, 1); PG8_SCHED; PG8_LDA(At, 0, 0); PG8_STAGE(PG8_SA(1, 1), a1 + hstep, voffA);
;             PG8_WAIT_V(8); PG8_WAIT_L(0); PG8_BAR; PG8_MMA2(0); PG8_BAR; PG8_SCHED;
;             PG8_LDA(At, 0, 1); PG8_STAGE(PG8_SB(0, 0), b2, voffB); PG8_STAGE(PG8_SB(0, 1), b2 + hstep, voffB); PG8_STAGE(PG8_SA(0, 0), a2, voffA);
;             PG8_WAIT_V(8); PG8_WAIT_L(0); PG8_BAR; PG8_MMA2(1); PG8_BAR; PG8_SCHED;
.Ldf_skipA_11:
	ds_read_b128 v[140:143], v161
	ds_read_b128 v[144:147], v161 offset:1024
	ds_read_b128 v[148:151], v161 offset:2048
	ds_read_b128 v[152:155], v161 offset:3072
	ds_read_b128 v[164:167], v162
	ds_read_b128 v[168:171], v162 offset:1024
	ds_read_b128 v[172:175], v162 offset:2048
	ds_read_b128 v[176:179], v162 offset:3072
	s_add_u32 s20, s18, 0x100
	s_addc_u32 s21, s19, 0
	s_cmp_eq_u32 s61, 40
	s_cselect_b32 s27, s7, s21
	s_cselect_b32 s26, s6, s20
	s_cselect_b32 s23, s17, s60
	s_cselect_b32 s22, s16, s59
	v_lshl_add_u64 v[156:157], s[18:19], 0, v[134:135]
	s_add_i32 m0, s39, 0xc000
	ds_read_b128 v[180:183], v163
	ds_read_b128 v[184:187], v163 offset:1024
	ds_read_b128 v[188:191], v163 offset:2048
	ds_read_b128 v[192:195], v163 offset:3072
	ds_read_b128 v[196:199], v163 offset:4096
	ds_read_b128 v[208:211], v163 offset:5120
	ds_read_b128 v[212:215], v163 offset:6144
	ds_read_b128 v[216:219], v163 offset:7168
	global_load_lds_dwordx4 v[156:157], off
	s_add_i32 m0, s39, 0xe000
	v_lshl_add_u64 v[156:157], s[18:19], 0, v[132:133]
	global_load_lds_dwordx4 v[156:157], off
	s_waitcnt vmcnt(8)
	s_waitcnt lgkmcnt(0)
	s_barrier
	s_setprio 1
	s_waitcnt lgkmcnt(0)
	v_mfma_f32_16x16x32_bf16 v[124:127], v[140:143], v[180:183], v[124:127]
	v_mfma_f32_16x16x32_bf16 v[120:123], v[148:151], v[180:183], v[120:123]
	v_mfma_f32_16x16x32_bf16 v[108:111], v[140:143], v[188:191], v[108:111]
	v_mfma_f32_16x16x32_bf16 v[104:107], v[148:151], v[188:191], v[104:107]
	v_mfma_f32_16x16x32_bf16 v[92:95], v[140:143], v[196:199], v[92:95]
	v_mfma_f32_16x16x32_bf16 v[88:91], v[148:151], v[196:199], v[88:91]
	v_mfma_f32_16x16x32_bf16 v[76:79], v[140:143], v[212:215], v[76:79]
	v_mfma_f32_16x16x32_bf16 v[72:75], v[148:151], v[212:215], v[72:75]
	v_mfma_f32_16x16x32_bf16 v[124:127], v[144:147], v[184:187], v[124:127]
	v_mfma_f32_16x16x32_bf16 v[120:123], v[152:155], v[184:187], v[120:123]
	v_mfma_f32_16x16x32_bf16 v[108:111], v[144:147], v[192:195], v[108:111]
	v_mfma_f32_16x16x32_bf16 v[104:107], v[152:155], v[192:195], v[104:107]
	v_mfma_f32_16x16x32_bf16 v[92:95], v[144:147], v[208:211], v[92:95]
	v_mfma_f32_16x16x32_bf16 v[88:91], v[152:155], v[208:211], v[88:91]
	v_mfma_f32_16x16x32_bf16 v[76:79], v[144:147], v[216:219], v[76:79]
	v_mfma_f32_16x16x32_bf16 v[72:75], v[152:155], v[216:219], v[72:75]
	s_setprio 0
	s_setprio 1
	v_mfma_f32_16x16x32_bf16 v[116:119], v[164:167], v[180:183], v[116:119]
	v_mfma_f32_16x16x32_bf16 v[112:115], v[172:175], v[180:183], v[112:115]
	v_mfma_f32_16x16x32_bf16 v[100:103], v[164:167], v[188:191], v[100:103]
	v_mfma_f32_16x16x32_bf16 v[96:99], v[172:175], v[188:191], v[96:99]
	v_mfma_f32_16x16x32_bf16 v[84:87], v[164:167], v[196:199], v[84:87]
	v_mfma_f32_16x16x32_bf16 v[80:83], v[172:175], v[196:199], v[80:83]
	v_mfma_f32_16x16x32_bf16 v[68:71], v[164:167], v[212:215], v[68:71]
	v_mfma_f32_16x16x32_bf16 v[64:67], v[172:175], v[212:215], v[64:67]
	v_mfma_f32_16x16x32_bf16 v[116:119], v[168:171], v[184:187], v[116:119]
	v_mfma_f32_16x16x32_bf16 v[112:115], v[176:179], v[184:187], v[112:115]
	v_mfma_f32_16x16x32_bf16 v[100:103], v[168:171], v[192:195], v[100:103]
	v_mfma_f32_16x16x32_bf16 v[96:99], v[176:179], v[192:195], v[96:99]
	v_mfma_f32_16x16x32_bf16 v[84:87], v[168:171], v[208:211], v[84:87]
	v_mfma_f32_16x16x32_bf16 v[80:83], v[176:179], v[208:211], v[80:83]
	v_mfma_f32_16x16x32_bf16 v[68:71], v[168:171], v[216:219], v[68:71]
	v_mfma_f32_16x16x32_bf16 v[64:67], v[176:179], v[216:219], v[64:67]
	s_setprio 0
	s_barrier
	s_add_i32 s18, s3, s38
	v_lshl_add_u64 v[156:157], s[22:23], 0, v[128:129]
	s_mov_b32 m0, s18
	ds_read_b128 v[180:183], v163 offset:16384
	ds_read_b128 v[184:187], v163 offset:17408
	ds_read_b128 v[188:191], v163 offset:18432
	ds_read_b128 v[192:195], v163 offset:19456
	ds_read_b128 v[196:199], v163 offset:20480
	ds_read_b128 v[208:211], v163 offset:21504
	ds_read_b128 v[212:215], v163 offset:22528
	ds_read_b128 v[216:219], v163 offset:23552
	global_load_lds_dwordx4 v[156:157], off
	s_add_i32 m0, s18, 0x2000
	s_add_u32 s18, s22, 0xb0000
	v_lshl_add_u64 v[200:201], s[22:23], 0, v[130:131]
	s_addc_u32 s19, s23, 0
	s_add_i32 s62, s53, s38
	global_load_lds_dwordx4 v[200:201], off
	v_lshl_add_u64 v[220:221], s[18:19], 0, v[128:129]
	s_mov_b32 m0, s62
	v_lshl_add_u64 v[222:223], s[26:27], 0, v[130:131]
	global_load_lds_dwordx4 v[220:221], off
	s_add_i32 m0, s62, 0x2000
	v_lshl_add_u64 v[220:221], s[18:19], 0, v[130:131]
	global_load_lds_dwordx4 v[220:221], off
	s_mov_b32 m0, s39
	v_lshl_add_u64 v[220:221], s[26:27], 0, v[128:129]
	global_load_lds_dwordx4 v[220:221], off
	s_nop 0
	s_waitcnt vmcnt(7)
	s_waitcnt lgkmcnt(0)
	s_barrier
; #define PG8_STAGE(bufoff, gbase, voff) do { _Pragma("unroll") for (int _i = 0; _i < 2; ++_i) \
;         __builtin_amdgcn_global_load_lds((const unsigned*)((const char*)(gbase) + (voff)[_i]), (PG8_LAS unsigned*)(lds + (bufoff) + ldsw + _i * 8192), 16, 0, 0); } while (0)
; #define PG8_LDA(dst, b, h) do { _Pragma("unroll") for (int m = 0; m < 4; ++m) _Pragma("unroll") for (int k = 0; k < 2; ++k) dst[m][k] = *(const PG8_LAS bf16x8*)(lds + PG8_SA(b, h) + aoff + m * 2048 + k * 1024); } while (0)
; #define PG8_LDB(dst, b, h) do { _Pragma("unroll") for (int n = 0; n < 2; ++n) _Pragma("unroll") for (int k = 0; k < 2; ++k) dst[n][k] = *(const PG8_LAS bf16x8*)(lds + PG8_SB(b, h) + boff + n * 2048 + k * 1024); } while (0)
; #define PG8_WAIT_V(n) asm volatile("s_waitcnt vmcnt(" #n ")" ::: "memory")
; #define PG8_WAIT_L(n) asm volatile("s_waitcnt lgkmcnt(" #n ")" ::: "memory")
; #define PG8_BAR __builtin_amdgcn_s_barrier()
; #define PG8_SCHED __builtin_amdgcn_sched_barrier(0)
; #define PG8_MMA2(ai) PG8_MMA(ai, 0, At, B0)
; #define PG8_MMA2(ai) PG8_MMA(ai, 1, At, B1)
; #define PG8_MMA2(ai) do { PG8_MMA(ai, 0, At, B0); PG8_MMA(ai, 1, At, B1); } while (0)
;     ...
;             PG8_WAIT_V(8); PG8_WAIT_L(0); PG8_BAR; PG8_MMA2(1); PG8_BAR; PG8_SCHED;
;             PG8_LDB(B0, 1, 0); PG8_LDB(B1, 1, 1); PG8_SCHED; PG8_LDA(At, 1, 0); PG8_STAGE(PG8_SA(0, 1), a2 + hstep, voffA);
;             PG8_WAIT_V(8); PG8_WAIT_L(0); PG8_BAR; PG8_MMA2(0); PG8_BAR; PG8_SCHED;
;             PG8_LDA(At, 1, 1); PG8_STAGE(PG8_SB(1, 0), b3, voffB); PG8_STAGE(PG8_SB(1, 1), b3 + hstep, voffB); PG8_STAGE(PG8_SA(1, 0), a3, voffA);
	s_setprio 1
	s_waitcnt lgkmcnt(0)
	v_mfma_f32_16x16x32_bf16 v[60:63], v[140:143], v[180:183], v[60:63]
	v_mfma_f32_16x16x32_bf16 v[56:59], v[148:151], v[180:183], v[56:59]
	v_mfma_f32_16x16x32_bf16 v[44:47], v[140:143], v[188:191], v[44:47]
	v_mfma_f32_16x16x32_bf16 v[40:43], v[148:151], v[188:191], v[40:43]
	v_mfma_f32_16x16x32_bf16 v[28:31], v[140:143], v[196:199], v[28:31]
	v_mfma_f32_16x16x32_bf16 v[24:27], v[148:151], v[196:199], v[24:27]
	v_mfma_f32_16x16x32_bf16 v[12:15], v[140:143], v[212:215], v[12:15]
	v_mfma_f32_16x16x32_bf16 v[8:11], v[148:151], v[212:215], v[8:11]
	v_mfma_f32_16x16x32_bf16 v[60:63], v[144:147], v[184:187], v[60:63]
	v_mfma_f32_16x16x32_bf16 v[56:59], v[152:155], v[184:187], v[56:59]
	v_mfma_f32_16x16x32_bf16 v[44:47], v[144:147], v[192:195], v[44:47]
	v_mfma_f32_16x16x32_bf16 v[40:43], v[152:155], v[192:195], v[40:43]
	v_mfma_f32_16x16x32_bf16 v[28:31], v[144:147], v[208:211], v[28:31]
	v_mfma_f32_16x16x32_bf16 v[24:27], v[152:155], v[208:211], v[24:27]
	v_mfma_f32_16x16x32_bf16 v[12:15], v[144:147], v[216:219], v[12:15]
	v_mfma_f32_16x16x32_bf16 v[8:11], v[152:155], v[216:219], v[8:11]
	s_setprio 0
	s_setprio 1
	v_mfma_f32_16x16x32_bf16 v[52:55], v[164:167], v[180:183], v[52:55]
	v_mfma_f32_16x16x32_bf16 v[48:51], v[172:175], v[180:183], v[48:51]
	v_mfma_f32_16x16x32_bf16 v[36:39], v[164:167], v[188:191], v[36:39]
	v_mfma_f32_16x16x32_bf16 v[32:35], v[172:175], v[188:191], v[32:35]
	v_mfma_f32_16x16x32_bf16 v[20:23], v[164:167], v[196:199], v[20:23]
	v_mfma_f32_16x16x32_bf16 v[16:19], v[172:175], v[196:199], v[16:19]
	v_mfma_f32_16x16x32_bf16 v[4:7], v[164:167], v[212:215], v[4:7]
	v_mfma_f32_16x16x32_bf16 v[0:3], v[172:175], v[212:215], v[0:3]
	v_mfma_f32_16x16x32_bf16 v[52:55], v[168:171], v[184:187], v[52:55]
	v_mfma_f32_16x16x32_bf16 v[48:51], v[176:179], v[184:187], v[48:51]
	v_mfma_f32_16x16x32_bf16 v[36:39], v[168:171], v[192:195], v[36:39]
	v_mfma_f32_16x16x32_bf16 v[32:35], v[176:179], v[192:195], v[32:35]
	v_mfma_f32_16x16x32_bf16 v[20:23], v[168:171], v[208:211], v[20:23]
	v_mfma_f32_16x16x32_bf16 v[16:19], v[176:179], v[208:211], v[16:19]
	v_mfma_f32_16x16x32_bf16 v[4:7], v[168:171], v[216:219], v[4:7]
	v_mfma_f32_16x16x32_bf16 v[0:3], v[176:179], v[216:219], v[0:3]
	s_setprio 0
	s_barrier
	s_add_i32 s62, 0, 0x18000
	s_add_i32 s63, 0, 0x1c000
	v_add_u32_e32 v152, s62, v159
	v_add_u32_e32 v176, s63, v159
	ds_read_b128 v[140:143], v152
	ds_read_b128 v[144:147], v152 offset:1024
	ds_read_b128 v[148:151], v152 offset:2048
	ds_read_b128 v[152:155], v152 offset:3072
	ds_read_b128 v[164:167], v176
	ds_read_b128 v[168:171], v176 offset:1024
	ds_read_b128 v[172:175], v176 offset:2048
	ds_read_b128 v[176:179], v176 offset:3072
	s_add_u32 s18, s26, 0xb0000
	s_addc_u32 s19, s27, 0
	s_mov_b32 m0, s40
	s_nop 0
	global_load_lds_dwordx4 v[222:223], off
	s_mov_b32 m0, s41
	v_lshl_add_u64 v[224:225], s[18:19], 0, v[128:129]
	ds_read_b128 v[180:183], v163 offset:32768
	ds_read_b128 v[184:187], v163 offset:33792
	ds_read_b128 v[188:191], v163 offset:34816
	ds_read_b128 v[192:195], v163 offset:35840
	ds_read_b128 v[196:199], v163 offset:36864
	ds_read_b128 v[208:211], v163 offset:37888
	ds_read_b128 v[212:215], v163 offset:38912
	ds_read_b128 v[216:219], v163 offset:39936
	global_load_lds_dwordx4 v[224:225], off
	s_mov_b32 m0, s42
	v_lshl_add_u64 v[224:225], s[18:19], 0, v[130:131]
	global_load_lds_dwordx4 v[224:225], off
	s_waitcnt vmcnt(8)
	s_waitcnt lgkmcnt(0)
	s_barrier
	s_setprio 1
	s_waitcnt lgkmcnt(0)
	v_mfma_f32_16x16x32_bf16 v[124:127], v[140:143], v[180:183], v[124:127]
	v_mfma_f32_16x16x32_bf16 v[120:123], v[148:151], v[180:183], v[120:123]
	v_mfma_f32_16x16x32_bf16 v[108:111], v[140:143], v[188:191], v[108:111]
	v_mfma_f32_16x16x32_bf16 v[104:107], v[148:151], v[188:191], v[104:107]
	v_mfma_f32_16x16x32_bf16 v[92:95], v[140:143], v[196:199], v[92:95]
	v_mfma_f32_16x16x32_bf16 v[88:91], v[148:151], v[196:199], v[88:91]
	v_mfma_f32_16x16x32_bf16 v[76:79], v[140:143], v[212:215], v[76:79]
	v_mfma_f32_16x16x32_bf16 v[72:75], v[148:151], v[212:215], v[72:75]
	v_mfma_f32_16x16x32_bf16 v[124:127], v[144:147], v[184:187], v[124:127]
	v_mfma_f32_16x16x32_bf16 v[120:123], v[152:155], v[184:187], v[120:123]
	v_mfma_f32_16x16x32_bf16 v[108:111], v[144:147], v[192:195], v[108:111]
	v_mfma_f32_16x16x32_bf16 v[104:107], v[152:155], v[192:195], v[104:107]
	v_mfma_f32_16x16x32_bf16 v[92:95], v[144:147], v[208:211], v[92:95]
	v_mfma_f32_16x16x32_bf16 v[88:91], v[152:155], v[208:211], v[88:91]
	v_mfma_f32_16x16x32_bf16 v[76:79], v[144:147], v[216:219], v[76:79]
	v_mfma_f32_16x16x32_bf16 v[72:75], v[152:155], v[216:219], v[72:75]
	s_setprio 0
	s_setprio 1
	v_mfma_f32_16x16x32_bf16 v[116:119], v[164:167], v[180:183], v[116:119]
	v_mfma_f32_16x16x32_bf16 v[112:115], v[172:175], v[180:183], v[112:115]
	v_mfma_f32_16x16x32_bf16 v[100:103], v[164:167], v[188:191], v[100:103]
	v_mfma_f32_16x16x32_bf16 v[96:99], v[172:175], v[188:191], v[96:99]
	v_mfma_f32_16x16x32_bf16 v[84:87], v[164:167], v[196:199], v[84:87]
	v_mfma_f32_16x16x32_bf16 v[80:83], v[172:175], v[196:199], v[80:83]
	v_mfma_f32_16x16x32_bf16 v[68:71], v[164:167], v[212:215], v[68:71]
	v_mfma_f32_16x16x32_bf16 v[64:67], v[172:175], v[212:215], v[64:67]
	v_mfma_f32_16x16x32_bf16 v[116:119], v[168:171], v[184:187], v[116:119]
	v_mfma_f32_16x16x32_bf16 v[112:115], v[176:179], v[184:187], v[112:115]
	v_mfma_f32_16x16x32_bf16 v[100:103], v[168:171], v[192:195], v[100:103]
	v_mfma_f32_16x16x32_bf16 v[96:99], v[176:179], v[192:195], v[96:99]
	v_mfma_f32_16x16x32_bf16 v[84:87], v[168:171], v[208:211], v[84:87]
	v_mfma_f32_16x16x32_bf16 v[80:83], v[176:179], v[208:211], v[80:83]
	v_mfma_f32_16x16x32_bf16 v[68:71], v[168:171], v[216:219], v[68:71]
	v_mfma_f32_16x16x32_bf16 v[64:67], v[176:179], v[216:219], v[64:67]
	s_setprio 0
	s_barrier
	s_add_i32 s18, s62, s38
	v_lshl_add_u64 v[156:157], v[156:157], 0, s[12:13]
	s_mov_b32 m0, s18
	ds_read_b128 v[180:183], v163 offset:49152
	ds_read_b128 v[184:187], v163 offset:50176
	ds_read_b128 v[188:191], v163 offset:51200
	ds_read_b128 v[192:195], v163 offset:52224
	ds_read_b128 v[196:199], v163 offset:53248
	ds_read_b128 v[208:211], v163 offset:54272
	ds_read_b128 v[212:215], v163 offset:55296
	ds_read_b128 v[216:219], v163 offset:56320
	global_load_lds_dwordx4 v[156:157], off
	s_add_i32 m0, s18, 0x2000
	s_add_u32 s18, s22, 0xb0080
	v_lshl_add_u64 v[156:157], v[200:201], 0, s[12:13]
	s_addc_u32 s19, s23, 0
	s_add_i32 s22, s63, s38
	global_load_lds_dwordx4 v[156:157], off
	s_mov_b32 m0, s22
	v_lshl_add_u64 v[156:157], s[18:19], 0, v[128:129]
	global_load_lds_dwordx4 v[156:157], off
	s_add_i32 m0, s22, 0x2000
	v_lshl_add_u64 v[156:157], s[18:19], 0, v[130:131]
	global_load_lds_dwordx4 v[156:157], off
	s_mov_b32 m0, s48
	v_lshl_add_u64 v[156:157], v[220:221], 0, s[12:13]
	global_load_lds_dwordx4 v[156:157], off
	v_lshl_add_u64 v[156:157], v[222:223], 0, s[12:13]
	s_nop 0
	s_cmp_lg_u32 s61, 40
	s_cbranch_scc1 .Ldf_skipD_11
	s_mov_b32 m0, s49
	s_nop 0
	global_load_lds_dwordx4 v[156:157], off
